# K-loops: s_setprio 1 issued before the pre-MFMA barrier and s_setprio 0 after the post-MFMA barrier (one fewer instruction between barrier release and first MFMA / between last MFMA and barrier arriva
# speedup vs baseline: 1.0139x; 1.0013x over previous
; #define PG8_STAGE(bufoff, gbase, voff) do { _Pragma("unroll") for (int _i = 0; _i < 2; ++_i) \
;         __builtin_amdgcn_global_load_lds((const unsigned*)((const char*)(gbase) + (voff)[_i]), (PG8_LAS unsigned*)(lds + (bufoff) + ldsw + _i * 8192), 16, 0, 0); } while (0)
; #define PG8_LDA(dst, b, h) do { _Pragma("unroll") for (int m = 0; m < 4; ++m) _Pragma("unroll") for (int k = 0; k < 2; ++k) dst[m][k] = *(const PG8_LAS bf16x8*)(lds + PG8_SA(b, h) + aoff + m * 2048 + k * 1024); } while (0)
; #define PG8_LDB(dst, b, h) do { _Pragma("unroll") for (int n = 0; n < 2; ++n) _Pragma("unroll") for (int k = 0; k < 2; ++k) dst[n][k] = *(const PG8_LAS bf16x8*)(lds + PG8_SB(b, h) + boff + n * 2048 + k * 1024); } while (0)
; #define PG8_MMA(ai, bj, At, Bt) do { __builtin_amdgcn_s_setprio(1); _Pragma("unroll") for (int m = 0; m < 4; ++m) _Pragma("unroll") for (int n = 0; n < 2; ++n) _Pragma("unroll") for (int k = 0; k < 2; ++k) \
;         acc[ai][bj][m][n] = __builtin_amdgcn_mfma_f32_16x16x32_bf16(Bt[n][k], At[m][k], acc[ai][bj][m][n], 0, 0, 0); __builtin_amdgcn_s_setprio(0); } while (0)
; #define PG8_WAIT_V(n) asm volatile("s_waitcnt vmcnt(" #n ")" ::: "memory")
; #define PG8_WAIT_L(n) asm volatile("s_waitcnt lgkmcnt(" #n ")" ::: "memory")
; #define PG8_BAR __builtin_amdgcn_s_barrier()
; #define PG8_SCHED __builtin_amdgcn_sched_barrier(0)
; template <class Epi, class Sched, bool ALIGN_EPI = false, bool SP2 = false>
; __device__ __forceinline__ void gemm_phase(PG8_LAS unsigned char* lds, const Gemm g, const Sched& S, const Epi& E) {
;     ...
;             PG8_LDB(B0, 0, 0); PG8_LDB(B1, 0, 1); PG8_SCHED; PG8_LDA(At, 0, 0); PG8_STAGE(PG8_SA(1, 1), a1 + hstep, voffA);
;             PG8_WAIT_V(8); PG8_WAIT_L(0); PG8_BAR; PG8_MMA(0, 0, At, B0); PG8_MMA(0, 1, At, B1); PG8_BAR; PG8_SCHED;
;             PG8_LDA(At, 0, 1); PG8_STAGE(PG8_SB(0, 0), b2, voffB); PG8_STAGE(PG8_SB(0, 1), b2 + hstep, voffB); PG8_STAGE(PG8_SA(0, 0), a2, voffA);
;             PG8_WAIT_V(8); PG8_WAIT_L(0); PG8_BAR; PG8_MMA(1, 0, At, B0); PG8_MMA(1, 1, At, B1); PG8_BAR; PG8_SCHED;
.Labo_peel:
	ds_read_b128 v[68:71], v254
	ds_read_b128 v[72:75], v254 offset:1024
	ds_read_b128 v[76:79], v254 offset:2048
	ds_read_b128 v[80:83], v254 offset:3072
	ds_read_b128 v[174:177], v254 offset:16384
	ds_read_b128 v[182:185], v254 offset:17408
	ds_read_b128 v[186:189], v254 offset:18432
	ds_read_b128 v[210:213], v254 offset:19456
	s_add_u32 s2, s0, 0xfffc0080
	s_addc_u32 s3, s1, -1
	s_cmp_eq_u32 s56, 12
	s_cselect_b32 s5, s27, s3
	s_cselect_b32 s4, s52, s2
	s_cselect_b32 s3, s25, s55
	s_cselect_b32 s2, s53, s54
	s_add_i32 m0, s29, 0xc000
	ds_read_b128 v[214:217], v179
	ds_read_b128 v[218:221], v179 offset:1024
	ds_read_b128 v[222:225], v179 offset:2048
	ds_read_b128 v[226:229], v179 offset:3072
	ds_read_b128 v[230:233], v179 offset:4096
	ds_read_b128 v[234:237], v179 offset:5120
	ds_read_b128 v[238:241], v179 offset:6144
	ds_read_b128 v[242:245], v179 offset:7168
	global_load_lds_dwordx4 v170, s[0:1]
	s_add_i32 m0, s29, 0xe000
	s_nop 0
	global_load_lds_dwordx4 v172, s[0:1]
	s_waitcnt vmcnt(8)
	s_waitcnt lgkmcnt(0)
	s_setprio 1
	s_barrier
	v_mfma_f32_16x16x32_bf16 v[140:143], v[68:71], v[214:217], 0
	v_mfma_f32_16x16x32_bf16 v[136:139], v[76:79], v[214:217], 0
	v_mfma_f32_16x16x32_bf16 v[124:127], v[68:71], v[222:225], 0
	v_mfma_f32_16x16x32_bf16 v[120:123], v[76:79], v[222:225], 0
	v_mfma_f32_16x16x32_bf16 v[108:111], v[68:71], v[230:233], 0
	v_mfma_f32_16x16x32_bf16 v[104:107], v[76:79], v[230:233], 0
	v_mfma_f32_16x16x32_bf16 v[92:95], v[68:71], v[238:241], 0
	v_mfma_f32_16x16x32_bf16 v[88:91], v[76:79], v[238:241], 0
	v_mfma_f32_16x16x32_bf16 v[140:143], v[72:75], v[218:221], v[140:143]
	v_mfma_f32_16x16x32_bf16 v[136:139], v[80:83], v[218:221], v[136:139]
	v_mfma_f32_16x16x32_bf16 v[124:127], v[72:75], v[226:229], v[124:127]
	v_mfma_f32_16x16x32_bf16 v[120:123], v[80:83], v[226:229], v[120:123]
	v_mfma_f32_16x16x32_bf16 v[108:111], v[72:75], v[234:237], v[108:111]
	v_mfma_f32_16x16x32_bf16 v[104:107], v[80:83], v[234:237], v[104:107]
	v_mfma_f32_16x16x32_bf16 v[92:95], v[72:75], v[242:245], v[92:95]
	v_mfma_f32_16x16x32_bf16 v[88:91], v[80:83], v[242:245], v[88:91]
	v_mfma_f32_16x16x32_bf16 v[132:135], v[174:177], v[214:217], 0
	v_mfma_f32_16x16x32_bf16 v[128:131], v[186:189], v[214:217], 0
	v_mfma_f32_16x16x32_bf16 v[116:119], v[174:177], v[222:225], 0
	v_mfma_f32_16x16x32_bf16 v[112:115], v[186:189], v[222:225], 0
	v_mfma_f32_16x16x32_bf16 v[100:103], v[174:177], v[230:233], 0
	v_mfma_f32_16x16x32_bf16 v[96:99], v[186:189], v[230:233], 0
	v_mfma_f32_16x16x32_bf16 v[84:87], v[174:177], v[238:241], 0
	v_mfma_f32_16x16x32_bf16 v[64:67], v[186:189], v[238:241], 0
	v_mfma_f32_16x16x32_bf16 v[132:135], v[182:185], v[218:221], v[132:135]
	v_mfma_f32_16x16x32_bf16 v[128:131], v[210:213], v[218:221], v[128:131]
	v_mfma_f32_16x16x32_bf16 v[116:119], v[182:185], v[226:229], v[116:119]
	v_mfma_f32_16x16x32_bf16 v[112:115], v[210:213], v[226:229], v[112:115]
	v_mfma_f32_16x16x32_bf16 v[100:103], v[182:185], v[234:237], v[100:103]
	v_mfma_f32_16x16x32_bf16 v[96:99], v[210:213], v[234:237], v[96:99]
	v_mfma_f32_16x16x32_bf16 v[84:87], v[182:185], v[242:245], v[84:87]
	v_mfma_f32_16x16x32_bf16 v[64:67], v[210:213], v[242:245], v[64:67]
	s_barrier
	s_setprio 0
	s_mov_b32 m0, s30
	s_add_u32 s58, s2, 0x40000
	s_addc_u32 s59, s3, 0
	ds_read_b128 v[214:217], v179 offset:16384
	ds_read_b128 v[218:221], v179 offset:17408
	ds_read_b128 v[222:225], v179 offset:18432
	ds_read_b128 v[226:229], v179 offset:19456
	ds_read_b128 v[230:233], v179 offset:20480
	ds_read_b128 v[234:237], v179 offset:21504
	ds_read_b128 v[238:241], v179 offset:22528
	ds_read_b128 v[242:245], v179 offset:23552
	global_load_lds_dwordx4 v166, s[2:3]
	s_mov_b32 m0, s31
	s_nop 0
	global_load_lds_dwordx4 v162, s[2:3]
	s_mov_b32 m0, s33
	s_nop 0
	global_load_lds_dwordx4 v166, s[58:59]
	s_mov_b32 m0, s34
	s_nop 0
	global_load_lds_dwordx4 v162, s[58:59]
	s_mov_b32 m0, s29
	s_nop 0
	global_load_lds_dwordx4 v168, s[4:5]
	s_mov_b32 m0, s35
	s_nop 0
	global_load_lds_dwordx4 v164, s[4:5]
	s_waitcnt vmcnt(8)
	s_waitcnt lgkmcnt(0)
	s_setprio 1
	s_barrier
	v_mfma_f32_16x16x32_bf16 v[60:63], v[68:71], v[214:217], 0
	v_mfma_f32_16x16x32_bf16 v[56:59], v[76:79], v[214:217], 0
	v_mfma_f32_16x16x32_bf16 v[44:47], v[68:71], v[222:225], 0
	v_mfma_f32_16x16x32_bf16 v[40:43], v[76:79], v[222:225], 0
	v_mfma_f32_16x16x32_bf16 v[28:31], v[68:71], v[230:233], 0
	v_mfma_f32_16x16x32_bf16 v[24:27], v[76:79], v[230:233], 0
	v_mfma_f32_16x16x32_bf16 v[12:15], v[68:71], v[238:241], 0
	v_mfma_f32_16x16x32_bf16 v[8:11], v[76:79], v[238:241], 0
	v_mfma_f32_16x16x32_bf16 v[60:63], v[72:75], v[218:221], v[60:63]
	v_mfma_f32_16x16x32_bf16 v[56:59], v[80:83], v[218:221], v[56:59]
	v_mfma_f32_16x16x32_bf16 v[44:47], v[72:75], v[226:229], v[44:47]
	v_mfma_f32_16x16x32_bf16 v[40:43], v[80:83], v[226:229], v[40:43]
	v_mfma_f32_16x16x32_bf16 v[28:31], v[72:75], v[234:237], v[28:31]
	v_mfma_f32_16x16x32_bf16 v[24:27], v[80:83], v[234:237], v[24:27]
	v_mfma_f32_16x16x32_bf16 v[12:15], v[72:75], v[242:245], v[12:15]
	v_mfma_f32_16x16x32_bf16 v[8:11], v[80:83], v[242:245], v[8:11]
	v_mfma_f32_16x16x32_bf16 v[52:55], v[174:177], v[214:217], 0
	v_mfma_f32_16x16x32_bf16 v[48:51], v[186:189], v[214:217], 0
	v_mfma_f32_16x16x32_bf16 v[36:39], v[174:177], v[222:225], 0
	v_mfma_f32_16x16x32_bf16 v[32:35], v[186:189], v[222:225], 0
	v_mfma_f32_16x16x32_bf16 v[20:23], v[174:177], v[230:233], 0
	v_mfma_f32_16x16x32_bf16 v[16:19], v[186:189], v[230:233], 0
	v_mfma_f32_16x16x32_bf16 v[4:7], v[174:177], v[238:241], 0
	v_mfma_f32_16x16x32_bf16 v[0:3], v[186:189], v[238:241], 0
	v_mfma_f32_16x16x32_bf16 v[52:55], v[182:185], v[218:221], v[52:55]
	v_mfma_f32_16x16x32_bf16 v[48:51], v[210:213], v[218:221], v[48:51]
	v_mfma_f32_16x16x32_bf16 v[36:39], v[182:185], v[226:229], v[36:39]
	v_mfma_f32_16x16x32_bf16 v[32:35], v[210:213], v[226:229], v[32:35]
	v_mfma_f32_16x16x32_bf16 v[20:23], v[182:185], v[234:237], v[20:23]
	v_mfma_f32_16x16x32_bf16 v[16:19], v[210:213], v[234:237], v[16:19]
	v_mfma_f32_16x16x32_bf16 v[4:7], v[182:185], v[242:245], v[4:7]
	v_mfma_f32_16x16x32_bf16 v[0:3], v[210:213], v[242:245], v[0:3]
	s_barrier
; #define PG8_STAGE(bufoff, gbase, voff) do { _Pragma("unroll") for (int _i = 0; _i < 2; ++_i) \
;         __builtin_amdgcn_global_load_lds((const unsigned*)((const char*)(gbase) + (voff)[_i]), (PG8_LAS unsigned*)(lds + (bufoff) + ldsw + _i * 8192), 16, 0, 0); } while (0)
; #define PG8_LDA(dst, b, h) do { _Pragma("unroll") for (int m = 0; m < 4; ++m) _Pragma("unroll") for (int k = 0; k < 2; ++k) dst[m][k] = *(const PG8_LAS bf16x8*)(lds + PG8_SA(b, h) + aoff + m * 2048 + k * 1024); } while (0)
; #define PG8_LDB(dst, b, h) do { _Pragma("unroll") for (int n = 0; n < 2; ++n) _Pragma("unroll") for (int k = 0; k < 2; ++k) dst[n][k] = *(const PG8_LAS bf16x8*)(lds + PG8_SB(b, h) + boff + n * 2048 + k * 1024); } while (0)
; #define PG8_MMA(ai, bj, At, Bt) do { __builtin_amdgcn_s_setprio(1); _Pragma("unroll") for (int m = 0; m < 4; ++m) _Pragma("unroll") for (int n = 0; n < 2; ++n) _Pragma("unroll") for (int k = 0; k < 2; ++k) \
;         acc[ai][bj][m][n] = __builtin_amdgcn_mfma_f32_16x16x32_bf16(Bt[n][k], At[m][k], acc[ai][bj][m][n], 0, 0, 0); __builtin_amdgcn_s_setprio(0); } while (0)
; #define PG8_WAIT_V(n) asm volatile("s_waitcnt vmcnt(" #n ")" ::: "memory")
; #define PG8_WAIT_L(n) asm volatile("s_waitcnt lgkmcnt(" #n ")" ::: "memory")
; #define PG8_BAR __builtin_amdgcn_s_barrier()
; #define PG8_SCHED __builtin_amdgcn_sched_barrier(0)
; template <class Epi, class Sched, bool ALIGN_EPI = false, bool SP2 = false>
; __device__ __forceinline__ void gemm_phase(PG8_LAS unsigned char* lds, const Gemm g, const Sched& S, const Epi& E) {
;     ...
;             PG8_LDB(B0, 1, 0); PG8_LDB(B1, 1, 1); PG8_SCHED; PG8_LDA(At, 1, 0); PG8_STAGE(PG8_SA(0, 1), a2 + hstep, voffA);
;             PG8_WAIT_V(8); PG8_WAIT_L(0); PG8_BAR; PG8_MMA(0, 0, At, B0); PG8_MMA(0, 1, At, B1); PG8_BAR; PG8_SCHED;
;             PG8_LDA(At, 1, 1); PG8_STAGE(PG8_SB(1, 0), b3, voffB); PG8_STAGE(PG8_SB(1, 1), b3 + hstep, voffB); PG8_STAGE(PG8_SA(1, 0), a3, voffA);
;             PG8_WAIT_V(8); PG8_WAIT_L(0); PG8_BAR; PG8_MMA(1, 0, At, B0); PG8_MMA(1, 1, At, B1); PG8_BAR; PG8_SCHED;
	s_setprio 0
	ds_read_b128 v[68:71], v254 offset:32768
	ds_read_b128 v[72:75], v254 offset:33792
	ds_read_b128 v[76:79], v254 offset:34816
	ds_read_b128 v[80:83], v254 offset:35840
	ds_read_b128 v[174:177], v254 offset:49152
	ds_read_b128 v[182:185], v254 offset:50176
	ds_read_b128 v[186:189], v254 offset:51200
	ds_read_b128 v[210:213], v254 offset:52224
	s_add_u32 s4, s4, 0x40000
	s_addc_u32 s5, s5, 0
	s_mov_b32 m0, s40
	ds_read_b128 v[214:217], v179 offset:32768
	ds_read_b128 v[218:221], v179 offset:33792
	ds_read_b128 v[222:225], v179 offset:34816
	ds_read_b128 v[226:229], v179 offset:35840
	ds_read_b128 v[230:233], v179 offset:36864
	ds_read_b128 v[234:237], v179 offset:37888
	ds_read_b128 v[238:241], v179 offset:38912
	ds_read_b128 v[242:245], v179 offset:39936
	global_load_lds_dwordx4 v168, s[4:5]
	s_mov_b32 m0, s41
	s_nop 0
	global_load_lds_dwordx4 v164, s[4:5]
	s_waitcnt vmcnt(8)
	s_waitcnt lgkmcnt(0)
	s_setprio 1
	s_barrier
	v_mfma_f32_16x16x32_bf16 v[140:143], v[68:71], v[214:217], v[140:143]
	v_mfma_f32_16x16x32_bf16 v[136:139], v[76:79], v[214:217], v[136:139]
	v_mfma_f32_16x16x32_bf16 v[124:127], v[68:71], v[222:225], v[124:127]
	v_mfma_f32_16x16x32_bf16 v[120:123], v[76:79], v[222:225], v[120:123]
	v_mfma_f32_16x16x32_bf16 v[108:111], v[68:71], v[230:233], v[108:111]
	v_mfma_f32_16x16x32_bf16 v[104:107], v[76:79], v[230:233], v[104:107]
	v_mfma_f32_16x16x32_bf16 v[92:95], v[68:71], v[238:241], v[92:95]
	v_mfma_f32_16x16x32_bf16 v[88:91], v[76:79], v[238:241], v[88:91]
	v_mfma_f32_16x16x32_bf16 v[140:143], v[72:75], v[218:221], v[140:143]
	v_mfma_f32_16x16x32_bf16 v[136:139], v[80:83], v[218:221], v[136:139]
	v_mfma_f32_16x16x32_bf16 v[124:127], v[72:75], v[226:229], v[124:127]
	v_mfma_f32_16x16x32_bf16 v[120:123], v[80:83], v[226:229], v[120:123]
	v_mfma_f32_16x16x32_bf16 v[108:111], v[72:75], v[234:237], v[108:111]
	v_mfma_f32_16x16x32_bf16 v[104:107], v[80:83], v[234:237], v[104:107]
	v_mfma_f32_16x16x32_bf16 v[92:95], v[72:75], v[242:245], v[92:95]
	v_mfma_f32_16x16x32_bf16 v[88:91], v[80:83], v[242:245], v[88:91]
	v_mfma_f32_16x16x32_bf16 v[132:135], v[174:177], v[214:217], v[132:135]
	v_mfma_f32_16x16x32_bf16 v[128:131], v[186:189], v[214:217], v[128:131]
	v_mfma_f32_16x16x32_bf16 v[116:119], v[174:177], v[222:225], v[116:119]
	v_mfma_f32_16x16x32_bf16 v[112:115], v[186:189], v[222:225], v[112:115]
	v_mfma_f32_16x16x32_bf16 v[100:103], v[174:177], v[230:233], v[100:103]
	v_mfma_f32_16x16x32_bf16 v[96:99], v[186:189], v[230:233], v[96:99]
	v_mfma_f32_16x16x32_bf16 v[84:87], v[174:177], v[238:241], v[84:87]
	v_mfma_f32_16x16x32_bf16 v[64:67], v[186:189], v[238:241], v[64:67]
	v_mfma_f32_16x16x32_bf16 v[132:135], v[182:185], v[218:221], v[132:135]
	v_mfma_f32_16x16x32_bf16 v[128:131], v[210:213], v[218:221], v[128:131]
	v_mfma_f32_16x16x32_bf16 v[116:119], v[182:185], v[226:229], v[116:119]
	v_mfma_f32_16x16x32_bf16 v[112:115], v[210:213], v[226:229], v[112:115]
	v_mfma_f32_16x16x32_bf16 v[100:103], v[182:185], v[234:237], v[100:103]
	v_mfma_f32_16x16x32_bf16 v[96:99], v[210:213], v[234:237], v[96:99]
	v_mfma_f32_16x16x32_bf16 v[84:87], v[182:185], v[242:245], v[84:87]
	v_mfma_f32_16x16x32_bf16 v[64:67], v[210:213], v[242:245], v[64:67]
	s_barrier
	s_setprio 0
	s_mov_b32 m0, s45
	s_add_u32 s2, s2, 0x40080
	s_addc_u32 s3, s3, 0
	ds_read_b128 v[214:217], v179 offset:49152
	ds_read_b128 v[218:221], v179 offset:50176
	ds_read_b128 v[222:225], v179 offset:51200
	ds_read_b128 v[226:229], v179 offset:52224
	ds_read_b128 v[230:233], v179 offset:53248
	ds_read_b128 v[234:237], v179 offset:54272
	ds_read_b128 v[238:241], v179 offset:55296
	ds_read_b128 v[242:245], v179 offset:56320
	s_add_u32 s98, s2, 0xfffc0000
	s_addc_u32 s99, s3, -1
	global_load_lds_dwordx4 v166, s[98:99]
	s_mov_b32 m0, s46
	s_nop 0
	global_load_lds_dwordx4 v162, s[98:99]
	s_mov_b32 m0, s49
	s_nop 0
	global_load_lds_dwordx4 v166, s[2:3]
	s_mov_b32 m0, s50
	s_nop 0
	global_load_lds_dwordx4 v162, s[2:3]
	s_mov_b32 m0, s47
	s_nop 0
	s_add_u32 s100, s4, 0xfffc0080
	s_addc_u32 s101, s5, -1
	global_load_lds_dwordx4 v168, s[100:101]
	s_mov_b32 m0, s48
	s_nop 0
	global_load_lds_dwordx4 v164, s[100:101]
	s_waitcnt vmcnt(8)
	s_waitcnt lgkmcnt(0)
	s_setprio 1
	s_barrier
	v_mfma_f32_16x16x32_bf16 v[60:63], v[68:71], v[214:217], v[60:63]
	v_mfma_f32_16x16x32_bf16 v[56:59], v[76:79], v[214:217], v[56:59]
	v_mfma_f32_16x16x32_bf16 v[44:47], v[68:71], v[222:225], v[44:47]
	v_mfma_f32_16x16x32_bf16 v[40:43], v[76:79], v[222:225], v[40:43]
	v_mfma_f32_16x16x32_bf16 v[28:31], v[68:71], v[230:233], v[28:31]
	v_mfma_f32_16x16x32_bf16 v[24:27], v[76:79], v[230:233], v[24:27]
	v_mfma_f32_16x16x32_bf16 v[12:15], v[68:71], v[238:241], v[12:15]
	v_mfma_f32_16x16x32_bf16 v[8:11], v[76:79], v[238:241], v[8:11]
	v_mfma_f32_16x16x32_bf16 v[60:63], v[72:75], v[218:221], v[60:63]
	v_mfma_f32_16x16x32_bf16 v[56:59], v[80:83], v[218:221], v[56:59]
	v_mfma_f32_16x16x32_bf16 v[44:47], v[72:75], v[226:229], v[44:47]
	v_mfma_f32_16x16x32_bf16 v[40:43], v[80:83], v[226:229], v[40:43]
	v_mfma_f32_16x16x32_bf16 v[28:31], v[72:75], v[234:237], v[28:31]
	v_mfma_f32_16x16x32_bf16 v[24:27], v[80:83], v[234:237], v[24:27]
	v_mfma_f32_16x16x32_bf16 v[12:15], v[72:75], v[242:245], v[12:15]
	v_mfma_f32_16x16x32_bf16 v[8:11], v[80:83], v[242:245], v[8:11]
	v_mfma_f32_16x16x32_bf16 v[52:55], v[174:177], v[214:217], v[52:55]
	v_mfma_f32_16x16x32_bf16 v[48:51], v[186:189], v[214:217], v[48:51]
	v_mfma_f32_16x16x32_bf16 v[36:39], v[174:177], v[222:225], v[36:39]
	v_mfma_f32_16x16x32_bf16 v[32:35], v[186:189], v[222:225], v[32:35]
	v_mfma_f32_16x16x32_bf16 v[20:23], v[174:177], v[230:233], v[20:23]
	v_mfma_f32_16x16x32_bf16 v[16:19], v[186:189], v[230:233], v[16:19]
	v_mfma_f32_16x16x32_bf16 v[4:7], v[174:177], v[238:241], v[4:7]
	v_mfma_f32_16x16x32_bf16 v[0:3], v[186:189], v[238:241], v[0:3]
	v_mfma_f32_16x16x32_bf16 v[52:55], v[182:185], v[218:221], v[52:55]
	v_mfma_f32_16x16x32_bf16 v[48:51], v[210:213], v[218:221], v[48:51]
	v_mfma_f32_16x16x32_bf16 v[36:39], v[182:185], v[226:229], v[36:39]
	v_mfma_f32_16x16x32_bf16 v[32:35], v[210:213], v[226:229], v[32:35]
	v_mfma_f32_16x16x32_bf16 v[20:23], v[182:185], v[234:237], v[20:23]
	v_mfma_f32_16x16x32_bf16 v[16:19], v[210:213], v[234:237], v[16:19]
	v_mfma_f32_16x16x32_bf16 v[4:7], v[182:185], v[242:245], v[4:7]
	v_mfma_f32_16x16x32_bf16 v[0:3], v[210:213], v[242:245], v[0:3]
	s_barrier
	s_setprio 0
	s_add_i32 s56, s56, 2
	s_add_u32 s0, s0, 0x100
	s_addc_u32 s1, s1, 0
	s_add_u32 s54, s54, 0x100
	s_addc_u32 s55, s55, 0
	s_cmp_gt_u32 s56, 13
; #define PG8_STAGE(bufoff, gbase, voff) do { _Pragma("unroll") for (int _i = 0; _i < 2; ++_i) \
;         __builtin_amdgcn_global_load_lds((const unsigned*)((const char*)(gbase) + (voff)[_i]), (PG8_LAS unsigned*)(lds + (bufoff) + ldsw + _i * 8192), 16, 0, 0); } while (0)
; #define PG8_LDA(dst, b, h) do { _Pragma("unroll") for (int m = 0; m < 4; ++m) _Pragma("unroll") for (int k = 0; k < 2; ++k) dst[m][k] = *(const PG8_LAS bf16x8*)(lds + PG8_SA(b, h) + aoff + m * 2048 + k * 1024); } while (0)
; #define PG8_LDB(dst, b, h) do { _Pragma("unroll") for (int n = 0; n < 2; ++n) _Pragma("unroll") for (int k = 0; k < 2; ++k) dst[n][k] = *(const PG8_LAS bf16x8*)(lds + PG8_SB(b, h) + boff + n * 2048 + k * 1024); } while (0)
; #define PG8_MMA(ai, bj, At, Bt) do { __builtin_amdgcn_s_setprio(1); _Pragma("unroll") for (int m = 0; m < 4; ++m) _Pragma("unroll") for (int n = 0; n < 2; ++n) _Pragma("unroll") for (int k = 0; k < 2; ++k) \
;         acc[ai][bj][m][n] = __builtin_amdgcn_mfma_f32_16x16x32_bf16(Bt[n][k], At[m][k], acc[ai][bj][m][n], 0, 0, 0); __builtin_amdgcn_s_setprio(0); } while (0)
; #define PG8_WAIT_V(n) asm volatile("s_waitcnt vmcnt(" #n ")" ::: "memory")
; #define PG8_WAIT_L(n) asm volatile("s_waitcnt lgkmcnt(" #n ")" ::: "memory")
; #define PG8_BAR __builtin_amdgcn_s_barrier()
; #define PG8_SCHED __builtin_amdgcn_sched_barrier(0)
; template <class Epi, class Sched, bool ALIGN_EPI = false, bool SP2 = false>
; __device__ __forceinline__ void gemm_phase(PG8_LAS unsigned char* lds, const Gemm g, const Sched& S, const Epi& E) {
;     ...
;             PG8_LDB(B0, 0, 0); PG8_LDB(B1, 0, 1); PG8_SCHED; PG8_LDA(At, 0, 0); PG8_STAGE(PG8_SA(1, 1), a1 + hstep, voffA);
;             PG8_WAIT_V(8); PG8_WAIT_L(0); PG8_BAR; PG8_MMA(0, 0, At, B0); PG8_MMA(0, 1, At, B1); PG8_BAR; PG8_SCHED;
;             PG8_LDA(At, 0, 1); PG8_STAGE(PG8_SB(0, 0), b2, voffB); PG8_STAGE(PG8_SB(0, 1), b2 + hstep, voffB); PG8_STAGE(PG8_SA(0, 0), a2, voffA);
;             PG8_WAIT_V(8); PG8_WAIT_L(0); PG8_BAR; PG8_MMA(1, 0, At, B0); PG8_MMA(1, 1, At, B1); PG8_BAR; PG8_SCHED;
.LBB0_327:
	ds_read_b128 v[68:71], v254
	ds_read_b128 v[72:75], v254 offset:1024
	ds_read_b128 v[76:79], v254 offset:2048
	ds_read_b128 v[80:83], v254 offset:3072
	ds_read_b128 v[174:177], v254 offset:16384
	ds_read_b128 v[182:185], v254 offset:17408
	ds_read_b128 v[186:189], v254 offset:18432
	ds_read_b128 v[210:213], v254 offset:19456
	s_add_u32 s2, s0, 0xfffc0080
	s_addc_u32 s3, s1, -1
	s_cmp_eq_u32 s56, 12
	s_cselect_b32 s5, s27, s3
	s_cselect_b32 s4, s52, s2
	s_cselect_b32 s3, s25, s55
	s_cselect_b32 s2, s53, s54
	s_add_i32 m0, s29, 0xc000
	ds_read_b128 v[214:217], v179
	ds_read_b128 v[218:221], v179 offset:1024
	ds_read_b128 v[222:225], v179 offset:2048
	ds_read_b128 v[226:229], v179 offset:3072
	ds_read_b128 v[230:233], v179 offset:4096
	ds_read_b128 v[234:237], v179 offset:5120
	ds_read_b128 v[238:241], v179 offset:6144
	ds_read_b128 v[242:245], v179 offset:7168
	global_load_lds_dwordx4 v170, s[0:1]
	s_add_i32 m0, s29, 0xe000
	s_nop 0
	global_load_lds_dwordx4 v172, s[0:1]
	s_waitcnt vmcnt(8)
	s_waitcnt lgkmcnt(0)
	s_setprio 1
	s_barrier
	v_mfma_f32_16x16x32_bf16 v[140:143], v[68:71], v[214:217], v[140:143]
	v_mfma_f32_16x16x32_bf16 v[136:139], v[76:79], v[214:217], v[136:139]
	v_mfma_f32_16x16x32_bf16 v[124:127], v[68:71], v[222:225], v[124:127]
	v_mfma_f32_16x16x32_bf16 v[120:123], v[76:79], v[222:225], v[120:123]
	v_mfma_f32_16x16x32_bf16 v[108:111], v[68:71], v[230:233], v[108:111]
	v_mfma_f32_16x16x32_bf16 v[104:107], v[76:79], v[230:233], v[104:107]
	v_mfma_f32_16x16x32_bf16 v[92:95], v[68:71], v[238:241], v[92:95]
	v_mfma_f32_16x16x32_bf16 v[88:91], v[76:79], v[238:241], v[88:91]
	v_mfma_f32_16x16x32_bf16 v[140:143], v[72:75], v[218:221], v[140:143]
	v_mfma_f32_16x16x32_bf16 v[136:139], v[80:83], v[218:221], v[136:139]
	v_mfma_f32_16x16x32_bf16 v[124:127], v[72:75], v[226:229], v[124:127]
	v_mfma_f32_16x16x32_bf16 v[120:123], v[80:83], v[226:229], v[120:123]
	v_mfma_f32_16x16x32_bf16 v[108:111], v[72:75], v[234:237], v[108:111]
	v_mfma_f32_16x16x32_bf16 v[104:107], v[80:83], v[234:237], v[104:107]
	v_mfma_f32_16x16x32_bf16 v[92:95], v[72:75], v[242:245], v[92:95]
	v_mfma_f32_16x16x32_bf16 v[88:91], v[80:83], v[242:245], v[88:91]
	v_mfma_f32_16x16x32_bf16 v[132:135], v[174:177], v[214:217], v[132:135]
	v_mfma_f32_16x16x32_bf16 v[128:131], v[186:189], v[214:217], v[128:131]
	v_mfma_f32_16x16x32_bf16 v[116:119], v[174:177], v[222:225], v[116:119]
	v_mfma_f32_16x16x32_bf16 v[112:115], v[186:189], v[222:225], v[112:115]
	v_mfma_f32_16x16x32_bf16 v[100:103], v[174:177], v[230:233], v[100:103]
	v_mfma_f32_16x16x32_bf16 v[96:99], v[186:189], v[230:233], v[96:99]
	v_mfma_f32_16x16x32_bf16 v[84:87], v[174:177], v[238:241], v[84:87]
	v_mfma_f32_16x16x32_bf16 v[64:67], v[186:189], v[238:241], v[64:67]
	v_mfma_f32_16x16x32_bf16 v[132:135], v[182:185], v[218:221], v[132:135]
	v_mfma_f32_16x16x32_bf16 v[128:131], v[210:213], v[218:221], v[128:131]
	v_mfma_f32_16x16x32_bf16 v[116:119], v[182:185], v[226:229], v[116:119]
	v_mfma_f32_16x16x32_bf16 v[112:115], v[210:213], v[226:229], v[112:115]
	v_mfma_f32_16x16x32_bf16 v[100:103], v[182:185], v[234:237], v[100:103]
	v_mfma_f32_16x16x32_bf16 v[96:99], v[210:213], v[234:237], v[96:99]
	v_mfma_f32_16x16x32_bf16 v[84:87], v[182:185], v[242:245], v[84:87]
	v_mfma_f32_16x16x32_bf16 v[64:67], v[210:213], v[242:245], v[64:67]
	s_barrier
	s_setprio 0
	s_mov_b32 m0, s30
	s_add_u32 s58, s2, 0x40000
	s_addc_u32 s59, s3, 0
	ds_read_b128 v[214:217], v179 offset:16384
	ds_read_b128 v[218:221], v179 offset:17408
	ds_read_b128 v[222:225], v179 offset:18432
	ds_read_b128 v[226:229], v179 offset:19456
	ds_read_b128 v[230:233], v179 offset:20480
	ds_read_b128 v[234:237], v179 offset:21504
	ds_read_b128 v[238:241], v179 offset:22528
	ds_read_b128 v[242:245], v179 offset:23552
	global_load_lds_dwordx4 v166, s[2:3]
	s_mov_b32 m0, s31
	s_nop 0
	global_load_lds_dwordx4 v162, s[2:3]
	s_mov_b32 m0, s33
	s_nop 0
	global_load_lds_dwordx4 v166, s[58:59]
	s_mov_b32 m0, s34
	s_nop 0
	global_load_lds_dwordx4 v162, s[58:59]
	s_mov_b32 m0, s29
	s_nop 0
	global_load_lds_dwordx4 v168, s[4:5]
	s_mov_b32 m0, s35
	s_nop 0
	global_load_lds_dwordx4 v164, s[4:5]
	s_waitcnt vmcnt(8)
	s_waitcnt lgkmcnt(0)
	s_setprio 1
	s_barrier
	v_mfma_f32_16x16x32_bf16 v[60:63], v[68:71], v[214:217], v[60:63]
	v_mfma_f32_16x16x32_bf16 v[56:59], v[76:79], v[214:217], v[56:59]
	v_mfma_f32_16x16x32_bf16 v[44:47], v[68:71], v[222:225], v[44:47]
	v_mfma_f32_16x16x32_bf16 v[40:43], v[76:79], v[222:225], v[40:43]
	v_mfma_f32_16x16x32_bf16 v[28:31], v[68:71], v[230:233], v[28:31]
	v_mfma_f32_16x16x32_bf16 v[24:27], v[76:79], v[230:233], v[24:27]
	v_mfma_f32_16x16x32_bf16 v[12:15], v[68:71], v[238:241], v[12:15]
	v_mfma_f32_16x16x32_bf16 v[8:11], v[76:79], v[238:241], v[8:11]
	v_mfma_f32_16x16x32_bf16 v[60:63], v[72:75], v[218:221], v[60:63]
	v_mfma_f32_16x16x32_bf16 v[56:59], v[80:83], v[218:221], v[56:59]
	v_mfma_f32_16x16x32_bf16 v[44:47], v[72:75], v[226:229], v[44:47]
	v_mfma_f32_16x16x32_bf16 v[40:43], v[80:83], v[226:229], v[40:43]
	v_mfma_f32_16x16x32_bf16 v[28:31], v[72:75], v[234:237], v[28:31]
	v_mfma_f32_16x16x32_bf16 v[24:27], v[80:83], v[234:237], v[24:27]
	v_mfma_f32_16x16x32_bf16 v[12:15], v[72:75], v[242:245], v[12:15]
	v_mfma_f32_16x16x32_bf16 v[8:11], v[80:83], v[242:245], v[8:11]
	v_mfma_f32_16x16x32_bf16 v[52:55], v[174:177], v[214:217], v[52:55]
	v_mfma_f32_16x16x32_bf16 v[48:51], v[186:189], v[214:217], v[48:51]
	v_mfma_f32_16x16x32_bf16 v[36:39], v[174:177], v[222:225], v[36:39]
	v_mfma_f32_16x16x32_bf16 v[32:35], v[186:189], v[222:225], v[32:35]
	v_mfma_f32_16x16x32_bf16 v[20:23], v[174:177], v[230:233], v[20:23]
	v_mfma_f32_16x16x32_bf16 v[16:19], v[186:189], v[230:233], v[16:19]
	v_mfma_f32_16x16x32_bf16 v[4:7], v[174:177], v[238:241], v[4:7]
	v_mfma_f32_16x16x32_bf16 v[0:3], v[186:189], v[238:241], v[0:3]
	v_mfma_f32_16x16x32_bf16 v[52:55], v[182:185], v[218:221], v[52:55]
	v_mfma_f32_16x16x32_bf16 v[48:51], v[210:213], v[218:221], v[48:51]
	v_mfma_f32_16x16x32_bf16 v[36:39], v[182:185], v[226:229], v[36:39]
	v_mfma_f32_16x16x32_bf16 v[32:35], v[210:213], v[226:229], v[32:35]
	v_mfma_f32_16x16x32_bf16 v[20:23], v[182:185], v[234:237], v[20:23]
	v_mfma_f32_16x16x32_bf16 v[16:19], v[210:213], v[234:237], v[16:19]
	v_mfma_f32_16x16x32_bf16 v[4:7], v[182:185], v[242:245], v[4:7]
	v_mfma_f32_16x16x32_bf16 v[0:3], v[210:213], v[242:245], v[0:3]
	s_barrier
; #define PG8_STAGE(bufoff, gbase, voff) do { _Pragma("unroll") for (int _i = 0; _i < 2; ++_i) \
;         __builtin_amdgcn_global_load_lds((const unsigned*)((const char*)(gbase) + (voff)[_i]), (PG8_LAS unsigned*)(lds + (bufoff) + ldsw + _i * 8192), 16, 0, 0); } while (0)
; #define PG8_LDA(dst, b, h) do { _Pragma("unroll") for (int m = 0; m < 4; ++m) _Pragma("unroll") for (int k = 0; k < 2; ++k) dst[m][k] = *(const PG8_LAS bf16x8*)(lds + PG8_SA(b, h) + aoff + m * 2048 + k * 1024); } while (0)
; #define PG8_LDB(dst, b, h) do { _Pragma("unroll") for (int n = 0; n < 2; ++n) _Pragma("unroll") for (int k = 0; k < 2; ++k) dst[n][k] = *(const PG8_LAS bf16x8*)(lds + PG8_SB(b, h) + boff + n * 2048 + k * 1024); } while (0)
; #define PG8_MMA(ai, bj, At, Bt) do { __builtin_amdgcn_s_setprio(1); _Pragma("unroll") for (int m = 0; m < 4; ++m) _Pragma("unroll") for (int n = 0; n < 2; ++n) _Pragma("unroll") for (int k = 0; k < 2; ++k) \
;         acc[ai][bj][m][n] = __builtin_amdgcn_mfma_f32_16x16x32_bf16(Bt[n][k], At[m][k], acc[ai][bj][m][n], 0, 0, 0); __builtin_amdgcn_s_setprio(0); } while (0)
; #define PG8_WAIT_V(n) asm volatile("s_waitcnt vmcnt(" #n ")" ::: "memory")
; #define PG8_WAIT_L(n) asm volatile("s_waitcnt lgkmcnt(" #n ")" ::: "memory")
; #define PG8_BAR __builtin_amdgcn_s_barrier()
; #define PG8_SCHED __builtin_amdgcn_sched_barrier(0)
; template <class Epi, class Sched, bool ALIGN_EPI = false, bool SP2 = false>
; __device__ __forceinline__ void gemm_phase(PG8_LAS unsigned char* lds, const Gemm g, const Sched& S, const Epi& E) {
;     ...
;             PG8_LDB(B0, 1, 0); PG8_LDB(B1, 1, 1); PG8_SCHED; PG8_LDA(At, 1, 0); PG8_STAGE(PG8_SA(0, 1), a2 + hstep, voffA);
;             PG8_WAIT_V(8); PG8_WAIT_L(0); PG8_BAR; PG8_MMA(0, 0, At, B0); PG8_MMA(0, 1, At, B1); PG8_BAR; PG8_SCHED;
;             PG8_LDA(At, 1, 1); PG8_STAGE(PG8_SB(1, 0), b3, voffB); PG8_STAGE(PG8_SB(1, 1), b3 + hstep, voffB); PG8_STAGE(PG8_SA(1, 0), a3, voffA);
;             PG8_WAIT_V(8); PG8_WAIT_L(0); PG8_BAR; PG8_MMA(1, 0, At, B0); PG8_MMA(1, 1, At, B1); PG8_BAR; PG8_SCHED;
;     ...
;         if constexpr (ALIGN_EPI) { if (wr == 0) PG8_BAR; }
	s_setprio 0
	ds_read_b128 v[68:71], v254 offset:32768
	ds_read_b128 v[72:75], v254 offset:33792
	ds_read_b128 v[76:79], v254 offset:34816
	ds_read_b128 v[80:83], v254 offset:35840
	ds_read_b128 v[174:177], v254 offset:49152
	ds_read_b128 v[182:185], v254 offset:50176
	ds_read_b128 v[186:189], v254 offset:51200
	ds_read_b128 v[210:213], v254 offset:52224
	s_add_u32 s4, s4, 0x40000
	s_addc_u32 s5, s5, 0
	s_mov_b32 m0, s40
	ds_read_b128 v[214:217], v179 offset:32768
	ds_read_b128 v[218:221], v179 offset:33792
	ds_read_b128 v[222:225], v179 offset:34816
	ds_read_b128 v[226:229], v179 offset:35840
	ds_read_b128 v[230:233], v179 offset:36864
	ds_read_b128 v[234:237], v179 offset:37888
	ds_read_b128 v[238:241], v179 offset:38912
	ds_read_b128 v[242:245], v179 offset:39936
	global_load_lds_dwordx4 v168, s[4:5]
	s_mov_b32 m0, s41
	s_nop 0
	global_load_lds_dwordx4 v164, s[4:5]
	s_waitcnt vmcnt(8)
	s_waitcnt lgkmcnt(0)
	s_setprio 1
	s_barrier
	v_mfma_f32_16x16x32_bf16 v[140:143], v[68:71], v[214:217], v[140:143]
	v_mfma_f32_16x16x32_bf16 v[136:139], v[76:79], v[214:217], v[136:139]
	v_mfma_f32_16x16x32_bf16 v[124:127], v[68:71], v[222:225], v[124:127]
	v_mfma_f32_16x16x32_bf16 v[120:123], v[76:79], v[222:225], v[120:123]
	v_mfma_f32_16x16x32_bf16 v[108:111], v[68:71], v[230:233], v[108:111]
	v_mfma_f32_16x16x32_bf16 v[104:107], v[76:79], v[230:233], v[104:107]
	v_mfma_f32_16x16x32_bf16 v[92:95], v[68:71], v[238:241], v[92:95]
	v_mfma_f32_16x16x32_bf16 v[88:91], v[76:79], v[238:241], v[88:91]
	v_mfma_f32_16x16x32_bf16 v[140:143], v[72:75], v[218:221], v[140:143]
	v_mfma_f32_16x16x32_bf16 v[136:139], v[80:83], v[218:221], v[136:139]
	v_mfma_f32_16x16x32_bf16 v[124:127], v[72:75], v[226:229], v[124:127]
	v_mfma_f32_16x16x32_bf16 v[120:123], v[80:83], v[226:229], v[120:123]
	v_mfma_f32_16x16x32_bf16 v[108:111], v[72:75], v[234:237], v[108:111]
	v_mfma_f32_16x16x32_bf16 v[104:107], v[80:83], v[234:237], v[104:107]
	v_mfma_f32_16x16x32_bf16 v[92:95], v[72:75], v[242:245], v[92:95]
	v_mfma_f32_16x16x32_bf16 v[88:91], v[80:83], v[242:245], v[88:91]
	v_mfma_f32_16x16x32_bf16 v[132:135], v[174:177], v[214:217], v[132:135]
	v_mfma_f32_16x16x32_bf16 v[128:131], v[186:189], v[214:217], v[128:131]
	v_mfma_f32_16x16x32_bf16 v[116:119], v[174:177], v[222:225], v[116:119]
	v_mfma_f32_16x16x32_bf16 v[112:115], v[186:189], v[222:225], v[112:115]
	v_mfma_f32_16x16x32_bf16 v[100:103], v[174:177], v[230:233], v[100:103]
	v_mfma_f32_16x16x32_bf16 v[96:99], v[186:189], v[230:233], v[96:99]
	v_mfma_f32_16x16x32_bf16 v[84:87], v[174:177], v[238:241], v[84:87]
	v_mfma_f32_16x16x32_bf16 v[64:67], v[186:189], v[238:241], v[64:67]
	v_mfma_f32_16x16x32_bf16 v[132:135], v[182:185], v[218:221], v[132:135]
	v_mfma_f32_16x16x32_bf16 v[128:131], v[210:213], v[218:221], v[128:131]
	v_mfma_f32_16x16x32_bf16 v[116:119], v[182:185], v[226:229], v[116:119]
	v_mfma_f32_16x16x32_bf16 v[112:115], v[210:213], v[226:229], v[112:115]
	v_mfma_f32_16x16x32_bf16 v[100:103], v[182:185], v[234:237], v[100:103]
	v_mfma_f32_16x16x32_bf16 v[96:99], v[210:213], v[234:237], v[96:99]
	v_mfma_f32_16x16x32_bf16 v[84:87], v[182:185], v[242:245], v[84:87]
	v_mfma_f32_16x16x32_bf16 v[64:67], v[210:213], v[242:245], v[64:67]
	s_barrier
	s_setprio 0
	s_mov_b32 m0, s45
	s_add_u32 s2, s2, 0x40080
	s_addc_u32 s3, s3, 0
	ds_read_b128 v[214:217], v179 offset:49152
	ds_read_b128 v[218:221], v179 offset:50176
	ds_read_b128 v[222:225], v179 offset:51200
	ds_read_b128 v[226:229], v179 offset:52224
	ds_read_b128 v[230:233], v179 offset:53248
	ds_read_b128 v[234:237], v179 offset:54272
	ds_read_b128 v[238:241], v179 offset:55296
	ds_read_b128 v[242:245], v179 offset:56320
	s_add_u32 s98, s2, 0xfffc0000
	s_addc_u32 s99, s3, -1
	global_load_lds_dwordx4 v166, s[98:99]
	s_mov_b32 m0, s46
	s_nop 0
	global_load_lds_dwordx4 v162, s[98:99]
	s_mov_b32 m0, s49
	s_nop 0
	global_load_lds_dwordx4 v166, s[2:3]
	s_mov_b32 m0, s50
	s_nop 0
	global_load_lds_dwordx4 v162, s[2:3]
	s_mov_b32 m0, s47
	s_nop 0
	s_add_u32 s100, s4, 0xfffc0080
	s_addc_u32 s101, s5, -1
	global_load_lds_dwordx4 v168, s[100:101]
	s_mov_b32 m0, s48
	s_nop 0
	global_load_lds_dwordx4 v164, s[100:101]
	s_waitcnt vmcnt(8)
	s_waitcnt lgkmcnt(0)
	s_setprio 1
	s_barrier
	v_mfma_f32_16x16x32_bf16 v[60:63], v[68:71], v[214:217], v[60:63]
	v_mfma_f32_16x16x32_bf16 v[56:59], v[76:79], v[214:217], v[56:59]
	v_mfma_f32_16x16x32_bf16 v[44:47], v[68:71], v[222:225], v[44:47]
	v_mfma_f32_16x16x32_bf16 v[40:43], v[76:79], v[222:225], v[40:43]
	v_mfma_f32_16x16x32_bf16 v[28:31], v[68:71], v[230:233], v[28:31]
	v_mfma_f32_16x16x32_bf16 v[24:27], v[76:79], v[230:233], v[24:27]
	v_mfma_f32_16x16x32_bf16 v[12:15], v[68:71], v[238:241], v[12:15]
	v_mfma_f32_16x16x32_bf16 v[8:11], v[76:79], v[238:241], v[8:11]
	v_mfma_f32_16x16x32_bf16 v[60:63], v[72:75], v[218:221], v[60:63]
	v_mfma_f32_16x16x32_bf16 v[56:59], v[80:83], v[218:221], v[56:59]
	v_mfma_f32_16x16x32_bf16 v[44:47], v[72:75], v[226:229], v[44:47]
	v_mfma_f32_16x16x32_bf16 v[40:43], v[80:83], v[226:229], v[40:43]
	v_mfma_f32_16x16x32_bf16 v[28:31], v[72:75], v[234:237], v[28:31]
	v_mfma_f32_16x16x32_bf16 v[24:27], v[80:83], v[234:237], v[24:27]
	v_mfma_f32_16x16x32_bf16 v[12:15], v[72:75], v[242:245], v[12:15]
	v_mfma_f32_16x16x32_bf16 v[8:11], v[80:83], v[242:245], v[8:11]
	v_mfma_f32_16x16x32_bf16 v[52:55], v[174:177], v[214:217], v[52:55]
	v_mfma_f32_16x16x32_bf16 v[48:51], v[186:189], v[214:217], v[48:51]
	v_mfma_f32_16x16x32_bf16 v[36:39], v[174:177], v[222:225], v[36:39]
	v_mfma_f32_16x16x32_bf16 v[32:35], v[186:189], v[222:225], v[32:35]
	v_mfma_f32_16x16x32_bf16 v[20:23], v[174:177], v[230:233], v[20:23]
	v_mfma_f32_16x16x32_bf16 v[16:19], v[186:189], v[230:233], v[16:19]
	v_mfma_f32_16x16x32_bf16 v[4:7], v[174:177], v[238:241], v[4:7]
	v_mfma_f32_16x16x32_bf16 v[0:3], v[186:189], v[238:241], v[0:3]
	v_mfma_f32_16x16x32_bf16 v[52:55], v[182:185], v[218:221], v[52:55]
	v_mfma_f32_16x16x32_bf16 v[48:51], v[210:213], v[218:221], v[48:51]
	v_mfma_f32_16x16x32_bf16 v[36:39], v[182:185], v[226:229], v[36:39]
	v_mfma_f32_16x16x32_bf16 v[32:35], v[210:213], v[226:229], v[32:35]
	v_mfma_f32_16x16x32_bf16 v[20:23], v[182:185], v[234:237], v[20:23]
	v_mfma_f32_16x16x32_bf16 v[16:19], v[210:213], v[234:237], v[16:19]
	v_mfma_f32_16x16x32_bf16 v[4:7], v[182:185], v[242:245], v[4:7]
	v_mfma_f32_16x16x32_bf16 v[0:3], v[210:213], v[242:245], v[0:3]
	s_barrier
	s_setprio 0
	s_add_i32 s56, s56, 2
	s_add_u32 s0, s0, 0x100
	s_addc_u32 s1, s1, 0
	s_add_u32 s54, s54, 0x100
	s_addc_u32 s55, s55, 0
	s_cmp_gt_u32 s56, 13
	s_cbranch_scc0 .LBB0_327
	s_and_b64 vcc, exec, s[22:23]
	s_cbranch_vccz .LBB0_330
	s_barrier

; #define PG8_STAGE(bufoff, gbase, voff) do { _Pragma("unroll") for (int _i = 0; _i < 2; ++_i) \
;         __builtin_amdgcn_global_load_lds((const unsigned*)((const char*)(gbase) + (voff)[_i]), (PG8_LAS unsigned*)(lds + (bufoff) + ldsw + _i * 8192), 16, 0, 0); } while (0)
; #define PG8_LDA(dst, b, h) do { _Pragma("unroll") for (int m = 0; m < 4; ++m) _Pragma("unroll") for (int k = 0; k < 2; ++k) dst[m][k] = *(const PG8_LAS bf16x8*)(lds + PG8_SA(b, h) + aoff + m * 2048 + k * 1024); } while (0)
; #define PG8_LDB(dst, b, h) do { _Pragma("unroll") for (int n = 0; n < 2; ++n) _Pragma("unroll") for (int k = 0; k < 2; ++k) dst[n][k] = *(const PG8_LAS bf16x8*)(lds + PG8_SB(b, h) + boff + n * 2048 + k * 1024); } while (0)
; #define PG8_MMA(ai, bj, At, Bt) do { __builtin_amdgcn_s_setprio(1); _Pragma("unroll") for (int m = 0; m < 4; ++m) _Pragma("unroll") for (int n = 0; n < 2; ++n) _Pragma("unroll") for (int k = 0; k < 2; ++k) \
;         acc[ai][bj][m][n] = __builtin_amdgcn_mfma_f32_16x16x32_bf16(Bt[n][k], At[m][k], acc[ai][bj][m][n], 0, 0, 0); __builtin_amdgcn_s_setprio(0); } while (0)
; #define PG8_WAIT_V(n) asm volatile("s_waitcnt vmcnt(" #n ")" ::: "memory")
; #define PG8_WAIT_L(n) asm volatile("s_waitcnt lgkmcnt(" #n ")" ::: "memory")
; #define PG8_BAR __builtin_amdgcn_s_barrier()
; #define PG8_SCHED __builtin_amdgcn_sched_barrier(0)
; template <class Epi, class Sched, bool ALIGN_EPI = false, bool SP2 = false>
; __device__ __forceinline__ void gemm_phase(PG8_LAS unsigned char* lds, const Gemm g, const Sched& S, const Epi& E) {
;     ...
;             PG8_LDB(B0, 0, 0); PG8_LDB(B1, 0, 1); PG8_SCHED; PG8_LDA(At, 0, 0); PG8_STAGE(PG8_SA(1, 1), a1 + hstep, voffA);
;             PG8_WAIT_V(8); PG8_WAIT_L(0); PG8_BAR; PG8_MMA(0, 0, At, B0); PG8_MMA(0, 1, At, B1); PG8_BAR; PG8_SCHED;
;             PG8_LDA(At, 0, 1); PG8_STAGE(PG8_SB(0, 0), b2, voffB); PG8_STAGE(PG8_SB(0, 1), b2 + hstep, voffB); PG8_STAGE(PG8_SA(0, 0), a2, voffA);
;             PG8_WAIT_V(8); PG8_WAIT_L(0); PG8_BAR; PG8_MMA(1, 0, At, B0); PG8_MMA(1, 1, At, B1); PG8_BAR; PG8_SCHED;
.Lup_peel:
	ds_read_b128 v[140:143], v254
	ds_read_b128 v[168:171], v254 offset:1024
	ds_read_b128 v[172:175], v254 offset:2048
	ds_read_b128 v[176:179], v254 offset:3072
	ds_read_b128 v[180:183], v254 offset:16384
	ds_read_b128 v[184:187], v254 offset:17408
	ds_read_b128 v[188:191], v254 offset:18432
	ds_read_b128 v[210:213], v254 offset:19456
	s_add_u32 s16, s14, 0xfffc0080
	s_addc_u32 s17, s15, -1
	s_cmp_eq_u32 s53, 12
	s_cselect_b32 s19, s7, s17
	s_cselect_b32 s18, s49, s16
	s_cselect_b32 s17, s5, s52
	s_cselect_b32 s16, s50, s51
	s_mov_b32 m0, s43
	ds_read_b128 v[214:217], v165
	ds_read_b128 v[218:221], v165 offset:1024
	ds_read_b128 v[222:225], v165 offset:2048
	ds_read_b128 v[226:229], v165 offset:3072
	ds_read_b128 v[230:233], v165 offset:4096
	ds_read_b128 v[234:237], v165 offset:5120
	ds_read_b128 v[238:241], v165 offset:6144
	ds_read_b128 v[242:245], v165 offset:7168
	global_load_lds_dwordx4 v136, s[14:15]
	s_mov_b32 m0, s44
	s_nop 0
	global_load_lds_dwordx4 v138, s[14:15]
	s_waitcnt vmcnt(8)
	s_waitcnt lgkmcnt(0)
	s_setprio 1
	s_barrier
	v_mfma_f32_16x16x32_bf16 v[124:127], v[140:143], v[214:217], 0
	v_mfma_f32_16x16x32_bf16 v[116:119], v[172:175], v[214:217], 0
	v_mfma_f32_16x16x32_bf16 v[108:111], v[140:143], v[222:225], 0
	v_mfma_f32_16x16x32_bf16 v[100:103], v[172:175], v[222:225], 0
	v_mfma_f32_16x16x32_bf16 v[92:95], v[140:143], v[230:233], 0
	v_mfma_f32_16x16x32_bf16 v[84:87], v[172:175], v[230:233], 0
	v_mfma_f32_16x16x32_bf16 v[76:79], v[140:143], v[238:241], 0
	v_mfma_f32_16x16x32_bf16 v[68:71], v[172:175], v[238:241], 0
	v_mfma_f32_16x16x32_bf16 v[124:127], v[168:171], v[218:221], v[124:127]
	v_mfma_f32_16x16x32_bf16 v[116:119], v[176:179], v[218:221], v[116:119]
	v_mfma_f32_16x16x32_bf16 v[108:111], v[168:171], v[226:229], v[108:111]
	v_mfma_f32_16x16x32_bf16 v[100:103], v[176:179], v[226:229], v[100:103]
	v_mfma_f32_16x16x32_bf16 v[92:95], v[168:171], v[234:237], v[92:95]
	v_mfma_f32_16x16x32_bf16 v[84:87], v[176:179], v[234:237], v[84:87]
	v_mfma_f32_16x16x32_bf16 v[76:79], v[168:171], v[242:245], v[76:79]
	v_mfma_f32_16x16x32_bf16 v[68:71], v[176:179], v[242:245], v[68:71]
	v_mfma_f32_16x16x32_bf16 v[120:123], v[180:183], v[214:217], 0
	v_mfma_f32_16x16x32_bf16 v[112:115], v[188:191], v[214:217], 0
	v_mfma_f32_16x16x32_bf16 v[104:107], v[180:183], v[222:225], 0
	v_mfma_f32_16x16x32_bf16 v[96:99], v[188:191], v[222:225], 0
	v_mfma_f32_16x16x32_bf16 v[88:91], v[180:183], v[230:233], 0
	v_mfma_f32_16x16x32_bf16 v[80:83], v[188:191], v[230:233], 0
	v_mfma_f32_16x16x32_bf16 v[72:75], v[180:183], v[238:241], 0
	v_mfma_f32_16x16x32_bf16 v[64:67], v[188:191], v[238:241], 0
	v_mfma_f32_16x16x32_bf16 v[120:123], v[184:187], v[218:221], v[120:123]
	v_mfma_f32_16x16x32_bf16 v[112:115], v[210:213], v[218:221], v[112:115]
	v_mfma_f32_16x16x32_bf16 v[104:107], v[184:187], v[226:229], v[104:107]
	v_mfma_f32_16x16x32_bf16 v[96:99], v[210:213], v[226:229], v[96:99]
	v_mfma_f32_16x16x32_bf16 v[88:91], v[184:187], v[234:237], v[88:91]
	v_mfma_f32_16x16x32_bf16 v[80:83], v[210:213], v[234:237], v[80:83]
	v_mfma_f32_16x16x32_bf16 v[72:75], v[184:187], v[242:245], v[72:75]
	v_mfma_f32_16x16x32_bf16 v[64:67], v[210:213], v[242:245], v[64:67]
	s_barrier
	s_setprio 0
	s_mov_b32 m0, s27
	s_add_u32 s54, s16, 0x40000
	s_addc_u32 s55, s17, 0
	ds_read_b128 v[214:217], v165 offset:16384
	ds_read_b128 v[218:221], v165 offset:17408
	ds_read_b128 v[222:225], v165 offset:18432
	ds_read_b128 v[226:229], v165 offset:19456
	ds_read_b128 v[230:233], v165 offset:20480
	ds_read_b128 v[234:237], v165 offset:21504
	ds_read_b128 v[238:241], v165 offset:22528
	ds_read_b128 v[242:245], v165 offset:23552
	global_load_lds_dwordx4 v132, s[16:17]
	s_mov_b32 m0, s28
	s_nop 0
	global_load_lds_dwordx4 v128, s[16:17]
	s_mov_b32 m0, s29
	s_nop 0
	global_load_lds_dwordx4 v132, s[54:55]
	s_mov_b32 m0, s30
	s_nop 0
	global_load_lds_dwordx4 v128, s[54:55]
	s_mov_b32 m0, s22
	s_nop 0
	global_load_lds_dwordx4 v134, s[18:19]
	s_mov_b32 m0, s31
	s_nop 0
	global_load_lds_dwordx4 v130, s[18:19]
	s_waitcnt vmcnt(8)
	s_waitcnt lgkmcnt(0)
	s_setprio 1
	s_barrier
	v_mfma_f32_16x16x32_bf16 v[60:63], v[140:143], v[214:217], 0
	v_mfma_f32_16x16x32_bf16 v[52:55], v[172:175], v[214:217], 0
	v_mfma_f32_16x16x32_bf16 v[44:47], v[140:143], v[222:225], 0
	v_mfma_f32_16x16x32_bf16 v[36:39], v[172:175], v[222:225], 0
	v_mfma_f32_16x16x32_bf16 v[28:31], v[140:143], v[230:233], 0
	v_mfma_f32_16x16x32_bf16 v[20:23], v[172:175], v[230:233], 0
	v_mfma_f32_16x16x32_bf16 v[12:15], v[140:143], v[238:241], 0
	v_mfma_f32_16x16x32_bf16 v[4:7], v[172:175], v[238:241], 0
	v_mfma_f32_16x16x32_bf16 v[60:63], v[168:171], v[218:221], v[60:63]
	v_mfma_f32_16x16x32_bf16 v[52:55], v[176:179], v[218:221], v[52:55]
	v_mfma_f32_16x16x32_bf16 v[44:47], v[168:171], v[226:229], v[44:47]
	v_mfma_f32_16x16x32_bf16 v[36:39], v[176:179], v[226:229], v[36:39]
	v_mfma_f32_16x16x32_bf16 v[28:31], v[168:171], v[234:237], v[28:31]
	v_mfma_f32_16x16x32_bf16 v[20:23], v[176:179], v[234:237], v[20:23]
	v_mfma_f32_16x16x32_bf16 v[12:15], v[168:171], v[242:245], v[12:15]
	v_mfma_f32_16x16x32_bf16 v[4:7], v[176:179], v[242:245], v[4:7]
	v_mfma_f32_16x16x32_bf16 v[56:59], v[180:183], v[214:217], 0
	v_mfma_f32_16x16x32_bf16 v[48:51], v[188:191], v[214:217], 0
	v_mfma_f32_16x16x32_bf16 v[40:43], v[180:183], v[222:225], 0
	v_mfma_f32_16x16x32_bf16 v[32:35], v[188:191], v[222:225], 0
	v_mfma_f32_16x16x32_bf16 v[24:27], v[180:183], v[230:233], 0
	v_mfma_f32_16x16x32_bf16 v[16:19], v[188:191], v[230:233], 0
	v_mfma_f32_16x16x32_bf16 v[8:11], v[180:183], v[238:241], 0
	v_mfma_f32_16x16x32_bf16 v[0:3], v[188:191], v[238:241], 0
	v_mfma_f32_16x16x32_bf16 v[56:59], v[184:187], v[218:221], v[56:59]
	v_mfma_f32_16x16x32_bf16 v[48:51], v[210:213], v[218:221], v[48:51]
	v_mfma_f32_16x16x32_bf16 v[40:43], v[184:187], v[226:229], v[40:43]
	v_mfma_f32_16x16x32_bf16 v[32:35], v[210:213], v[226:229], v[32:35]
	v_mfma_f32_16x16x32_bf16 v[24:27], v[184:187], v[234:237], v[24:27]
	v_mfma_f32_16x16x32_bf16 v[16:19], v[210:213], v[234:237], v[16:19]
	v_mfma_f32_16x16x32_bf16 v[8:11], v[184:187], v[242:245], v[8:11]
	v_mfma_f32_16x16x32_bf16 v[0:3], v[210:213], v[242:245], v[0:3]
	s_barrier
; #define PG8_STAGE(bufoff, gbase, voff) do { _Pragma("unroll") for (int _i = 0; _i < 2; ++_i) \
;         __builtin_amdgcn_global_load_lds((const unsigned*)((const char*)(gbase) + (voff)[_i]), (PG8_LAS unsigned*)(lds + (bufoff) + ldsw + _i * 8192), 16, 0, 0); } while (0)
; #define PG8_LDA(dst, b, h) do { _Pragma("unroll") for (int m = 0; m < 4; ++m) _Pragma("unroll") for (int k = 0; k < 2; ++k) dst[m][k] = *(const PG8_LAS bf16x8*)(lds + PG8_SA(b, h) + aoff + m * 2048 + k * 1024); } while (0)
; #define PG8_LDB(dst, b, h) do { _Pragma("unroll") for (int n = 0; n < 2; ++n) _Pragma("unroll") for (int k = 0; k < 2; ++k) dst[n][k] = *(const PG8_LAS bf16x8*)(lds + PG8_SB(b, h) + boff + n * 2048 + k * 1024); } while (0)
; #define PG8_MMA(ai, bj, At, Bt) do { __builtin_amdgcn_s_setprio(1); _Pragma("unroll") for (int m = 0; m < 4; ++m) _Pragma("unroll") for (int n = 0; n < 2; ++n) _Pragma("unroll") for (int k = 0; k < 2; ++k) \
;         acc[ai][bj][m][n] = __builtin_amdgcn_mfma_f32_16x16x32_bf16(Bt[n][k], At[m][k], acc[ai][bj][m][n], 0, 0, 0); __builtin_amdgcn_s_setprio(0); } while (0)
; #define PG8_WAIT_V(n) asm volatile("s_waitcnt vmcnt(" #n ")" ::: "memory")
; #define PG8_WAIT_L(n) asm volatile("s_waitcnt lgkmcnt(" #n ")" ::: "memory")
; #define PG8_BAR __builtin_amdgcn_s_barrier()
; #define PG8_SCHED __builtin_amdgcn_sched_barrier(0)
; template <class Epi, class Sched, bool ALIGN_EPI = false, bool SP2 = false>
; __device__ __forceinline__ void gemm_phase(PG8_LAS unsigned char* lds, const Gemm g, const Sched& S, const Epi& E) {
;     ...
;             PG8_LDB(B0, 1, 0); PG8_LDB(B1, 1, 1); PG8_SCHED; PG8_LDA(At, 1, 0); PG8_STAGE(PG8_SA(0, 1), a2 + hstep, voffA);
;             PG8_WAIT_V(8); PG8_WAIT_L(0); PG8_BAR; PG8_MMA(0, 0, At, B0); PG8_MMA(0, 1, At, B1); PG8_BAR; PG8_SCHED;
;             PG8_LDA(At, 1, 1); PG8_STAGE(PG8_SB(1, 0), b3, voffB); PG8_STAGE(PG8_SB(1, 1), b3 + hstep, voffB); PG8_STAGE(PG8_SA(1, 0), a3, voffA);
;             PG8_WAIT_V(8); PG8_WAIT_L(0); PG8_BAR; PG8_MMA(1, 0, At, B0); PG8_MMA(1, 1, At, B1); PG8_BAR; PG8_SCHED;
	s_setprio 0
	ds_read_b128 v[140:143], v254 offset:32768
	ds_read_b128 v[168:171], v254 offset:33792
	ds_read_b128 v[172:175], v254 offset:34816
	ds_read_b128 v[176:179], v254 offset:35840
	ds_read_b128 v[180:183], v254 offset:49152
	ds_read_b128 v[184:187], v254 offset:50176
	ds_read_b128 v[188:191], v254 offset:51200
	ds_read_b128 v[210:213], v254 offset:52224
	s_add_u32 s18, s18, 0x40000
	s_addc_u32 s19, s19, 0
	s_mov_b32 m0, s33
	ds_read_b128 v[214:217], v165 offset:32768
	ds_read_b128 v[218:221], v165 offset:33792
	ds_read_b128 v[222:225], v165 offset:34816
	ds_read_b128 v[226:229], v165 offset:35840
	ds_read_b128 v[230:233], v165 offset:36864
	ds_read_b128 v[234:237], v165 offset:37888
	ds_read_b128 v[238:241], v165 offset:38912
	ds_read_b128 v[242:245], v165 offset:39936
	global_load_lds_dwordx4 v134, s[18:19]
	s_mov_b32 m0, s34
	s_nop 0
	global_load_lds_dwordx4 v130, s[18:19]
	s_waitcnt vmcnt(8)
	s_waitcnt lgkmcnt(0)
	s_setprio 1
	s_barrier
	v_mfma_f32_16x16x32_bf16 v[124:127], v[140:143], v[214:217], v[124:127]
	v_mfma_f32_16x16x32_bf16 v[116:119], v[172:175], v[214:217], v[116:119]
	v_mfma_f32_16x16x32_bf16 v[108:111], v[140:143], v[222:225], v[108:111]
	v_mfma_f32_16x16x32_bf16 v[100:103], v[172:175], v[222:225], v[100:103]
	v_mfma_f32_16x16x32_bf16 v[92:95], v[140:143], v[230:233], v[92:95]
	v_mfma_f32_16x16x32_bf16 v[84:87], v[172:175], v[230:233], v[84:87]
	v_mfma_f32_16x16x32_bf16 v[76:79], v[140:143], v[238:241], v[76:79]
	v_mfma_f32_16x16x32_bf16 v[68:71], v[172:175], v[238:241], v[68:71]
	v_mfma_f32_16x16x32_bf16 v[124:127], v[168:171], v[218:221], v[124:127]
	v_mfma_f32_16x16x32_bf16 v[116:119], v[176:179], v[218:221], v[116:119]
	v_mfma_f32_16x16x32_bf16 v[108:111], v[168:171], v[226:229], v[108:111]
	v_mfma_f32_16x16x32_bf16 v[100:103], v[176:179], v[226:229], v[100:103]
	v_mfma_f32_16x16x32_bf16 v[92:95], v[168:171], v[234:237], v[92:95]
	v_mfma_f32_16x16x32_bf16 v[84:87], v[176:179], v[234:237], v[84:87]
	v_mfma_f32_16x16x32_bf16 v[76:79], v[168:171], v[242:245], v[76:79]
	v_mfma_f32_16x16x32_bf16 v[68:71], v[176:179], v[242:245], v[68:71]
	v_mfma_f32_16x16x32_bf16 v[120:123], v[180:183], v[214:217], v[120:123]
	v_mfma_f32_16x16x32_bf16 v[112:115], v[188:191], v[214:217], v[112:115]
	v_mfma_f32_16x16x32_bf16 v[104:107], v[180:183], v[222:225], v[104:107]
	v_mfma_f32_16x16x32_bf16 v[96:99], v[188:191], v[222:225], v[96:99]
	v_mfma_f32_16x16x32_bf16 v[88:91], v[180:183], v[230:233], v[88:91]
	v_mfma_f32_16x16x32_bf16 v[80:83], v[188:191], v[230:233], v[80:83]
	v_mfma_f32_16x16x32_bf16 v[72:75], v[180:183], v[238:241], v[72:75]
	v_mfma_f32_16x16x32_bf16 v[64:67], v[188:191], v[238:241], v[64:67]
	v_mfma_f32_16x16x32_bf16 v[120:123], v[184:187], v[218:221], v[120:123]
	v_mfma_f32_16x16x32_bf16 v[112:115], v[210:213], v[218:221], v[112:115]
	v_mfma_f32_16x16x32_bf16 v[104:107], v[184:187], v[226:229], v[104:107]
	v_mfma_f32_16x16x32_bf16 v[96:99], v[210:213], v[226:229], v[96:99]
	v_mfma_f32_16x16x32_bf16 v[88:91], v[184:187], v[234:237], v[88:91]
	v_mfma_f32_16x16x32_bf16 v[80:83], v[210:213], v[234:237], v[80:83]
	v_mfma_f32_16x16x32_bf16 v[72:75], v[184:187], v[242:245], v[72:75]
	v_mfma_f32_16x16x32_bf16 v[64:67], v[210:213], v[242:245], v[64:67]
	s_barrier
	s_setprio 0
	s_mov_b32 m0, s37
	s_add_u32 s16, s16, 0x40080
	s_addc_u32 s17, s17, 0
	ds_read_b128 v[214:217], v165 offset:49152
	ds_read_b128 v[218:221], v165 offset:50176
	ds_read_b128 v[222:225], v165 offset:51200
	ds_read_b128 v[226:229], v165 offset:52224
	ds_read_b128 v[230:233], v165 offset:53248
	ds_read_b128 v[234:237], v165 offset:54272
	ds_read_b128 v[238:241], v165 offset:55296
	ds_read_b128 v[242:245], v165 offset:56320
	s_add_u32 s98, s16, 0xfffc0000
	s_addc_u32 s99, s17, -1
	global_load_lds_dwordx4 v132, s[98:99]
	s_mov_b32 m0, s38
	s_nop 0
	global_load_lds_dwordx4 v128, s[98:99]
	s_mov_b32 m0, s41
	s_nop 0
	global_load_lds_dwordx4 v132, s[16:17]
	s_mov_b32 m0, s42
	s_nop 0
	global_load_lds_dwordx4 v128, s[16:17]
	s_mov_b32 m0, s39
	s_nop 0
	s_add_u32 s100, s18, 0xfffc0080
	s_addc_u32 s101, s19, -1
	global_load_lds_dwordx4 v134, s[100:101]
	s_mov_b32 m0, s40
	s_nop 0
	global_load_lds_dwordx4 v130, s[100:101]
	s_waitcnt vmcnt(8)
	s_waitcnt lgkmcnt(0)
	s_setprio 1
	s_barrier
	v_mfma_f32_16x16x32_bf16 v[60:63], v[140:143], v[214:217], v[60:63]
	v_mfma_f32_16x16x32_bf16 v[52:55], v[172:175], v[214:217], v[52:55]
	v_mfma_f32_16x16x32_bf16 v[44:47], v[140:143], v[222:225], v[44:47]
	v_mfma_f32_16x16x32_bf16 v[36:39], v[172:175], v[222:225], v[36:39]
	v_mfma_f32_16x16x32_bf16 v[28:31], v[140:143], v[230:233], v[28:31]
	v_mfma_f32_16x16x32_bf16 v[20:23], v[172:175], v[230:233], v[20:23]
	v_mfma_f32_16x16x32_bf16 v[12:15], v[140:143], v[238:241], v[12:15]
	v_mfma_f32_16x16x32_bf16 v[4:7], v[172:175], v[238:241], v[4:7]
	v_mfma_f32_16x16x32_bf16 v[60:63], v[168:171], v[218:221], v[60:63]
	v_mfma_f32_16x16x32_bf16 v[52:55], v[176:179], v[218:221], v[52:55]
	v_mfma_f32_16x16x32_bf16 v[44:47], v[168:171], v[226:229], v[44:47]
	v_mfma_f32_16x16x32_bf16 v[36:39], v[176:179], v[226:229], v[36:39]
	v_mfma_f32_16x16x32_bf16 v[28:31], v[168:171], v[234:237], v[28:31]
	v_mfma_f32_16x16x32_bf16 v[20:23], v[176:179], v[234:237], v[20:23]
	v_mfma_f32_16x16x32_bf16 v[12:15], v[168:171], v[242:245], v[12:15]
	v_mfma_f32_16x16x32_bf16 v[4:7], v[176:179], v[242:245], v[4:7]
	v_mfma_f32_16x16x32_bf16 v[56:59], v[180:183], v[214:217], v[56:59]
	v_mfma_f32_16x16x32_bf16 v[48:51], v[188:191], v[214:217], v[48:51]
	v_mfma_f32_16x16x32_bf16 v[40:43], v[180:183], v[222:225], v[40:43]
	v_mfma_f32_16x16x32_bf16 v[32:35], v[188:191], v[222:225], v[32:35]
	v_mfma_f32_16x16x32_bf16 v[24:27], v[180:183], v[230:233], v[24:27]
	v_mfma_f32_16x16x32_bf16 v[16:19], v[188:191], v[230:233], v[16:19]
	v_mfma_f32_16x16x32_bf16 v[8:11], v[180:183], v[238:241], v[8:11]
	v_mfma_f32_16x16x32_bf16 v[0:3], v[188:191], v[238:241], v[0:3]
	v_mfma_f32_16x16x32_bf16 v[56:59], v[184:187], v[218:221], v[56:59]
	v_mfma_f32_16x16x32_bf16 v[48:51], v[210:213], v[218:221], v[48:51]
	v_mfma_f32_16x16x32_bf16 v[40:43], v[184:187], v[226:229], v[40:43]
	v_mfma_f32_16x16x32_bf16 v[32:35], v[210:213], v[226:229], v[32:35]
	v_mfma_f32_16x16x32_bf16 v[24:27], v[184:187], v[234:237], v[24:27]
	v_mfma_f32_16x16x32_bf16 v[16:19], v[210:213], v[234:237], v[16:19]
	v_mfma_f32_16x16x32_bf16 v[8:11], v[184:187], v[242:245], v[8:11]
	v_mfma_f32_16x16x32_bf16 v[0:3], v[210:213], v[242:245], v[0:3]
	s_barrier
	s_setprio 0
	s_add_i32 s53, s53, 2
	s_add_u32 s14, s14, 0x100
	s_addc_u32 s15, s15, 0
	s_add_u32 s51, s51, 0x100
	s_addc_u32 s52, s52, 0
	s_cmp_gt_u32 s53, 13
; #define PG8_STAGE(bufoff, gbase, voff) do { _Pragma("unroll") for (int _i = 0; _i < 2; ++_i) \
;         __builtin_amdgcn_global_load_lds((const unsigned*)((const char*)(gbase) + (voff)[_i]), (PG8_LAS unsigned*)(lds + (bufoff) + ldsw + _i * 8192), 16, 0, 0); } while (0)
; #define PG8_LDA(dst, b, h) do { _Pragma("unroll") for (int m = 0; m < 4; ++m) _Pragma("unroll") for (int k = 0; k < 2; ++k) dst[m][k] = *(const PG8_LAS bf16x8*)(lds + PG8_SA(b, h) + aoff + m * 2048 + k * 1024); } while (0)
; #define PG8_LDB(dst, b, h) do { _Pragma("unroll") for (int n = 0; n < 2; ++n) _Pragma("unroll") for (int k = 0; k < 2; ++k) dst[n][k] = *(const PG8_LAS bf16x8*)(lds + PG8_SB(b, h) + boff + n * 2048 + k * 1024); } while (0)
; #define PG8_MMA(ai, bj, At, Bt) do { __builtin_amdgcn_s_setprio(1); _Pragma("unroll") for (int m = 0; m < 4; ++m) _Pragma("unroll") for (int n = 0; n < 2; ++n) _Pragma("unroll") for (int k = 0; k < 2; ++k) \
;         acc[ai][bj][m][n] = __builtin_amdgcn_mfma_f32_16x16x32_bf16(Bt[n][k], At[m][k], acc[ai][bj][m][n], 0, 0, 0); __builtin_amdgcn_s_setprio(0); } while (0)
; #define PG8_WAIT_V(n) asm volatile("s_waitcnt vmcnt(" #n ")" ::: "memory")
; #define PG8_WAIT_L(n) asm volatile("s_waitcnt lgkmcnt(" #n ")" ::: "memory")
; #define PG8_BAR __builtin_amdgcn_s_barrier()
; #define PG8_SCHED __builtin_amdgcn_sched_barrier(0)
; template <class Epi, class Sched, bool ALIGN_EPI = false, bool SP2 = false>
; __device__ __forceinline__ void gemm_phase(PG8_LAS unsigned char* lds, const Gemm g, const Sched& S, const Epi& E) {
;     ...
;             PG8_LDB(B0, 0, 0); PG8_LDB(B1, 0, 1); PG8_SCHED; PG8_LDA(At, 0, 0); PG8_STAGE(PG8_SA(1, 1), a1 + hstep, voffA);
;             PG8_WAIT_V(8); PG8_WAIT_L(0); PG8_BAR; PG8_MMA(0, 0, At, B0); PG8_MMA(0, 1, At, B1); PG8_BAR; PG8_SCHED;
;             PG8_LDA(At, 0, 1); PG8_STAGE(PG8_SB(0, 0), b2, voffB); PG8_STAGE(PG8_SB(0, 1), b2 + hstep, voffB); PG8_STAGE(PG8_SA(0, 0), a2, voffA);
;             PG8_WAIT_V(8); PG8_WAIT_L(0); PG8_BAR; PG8_MMA(1, 0, At, B0); PG8_MMA(1, 1, At, B1); PG8_BAR; PG8_SCHED;
.LBB0_446:
	ds_read_b128 v[140:143], v254
	ds_read_b128 v[168:171], v254 offset:1024
	ds_read_b128 v[172:175], v254 offset:2048
	ds_read_b128 v[176:179], v254 offset:3072
	ds_read_b128 v[180:183], v254 offset:16384
	ds_read_b128 v[184:187], v254 offset:17408
	ds_read_b128 v[188:191], v254 offset:18432
	ds_read_b128 v[210:213], v254 offset:19456
	s_add_u32 s16, s14, 0xfffc0080
	s_addc_u32 s17, s15, -1
	s_cmp_eq_u32 s53, 12
	s_cselect_b32 s19, s7, s17
	s_cselect_b32 s18, s49, s16
	s_cselect_b32 s17, s5, s52
	s_cselect_b32 s16, s50, s51
	s_mov_b32 m0, s43
	ds_read_b128 v[214:217], v165
	ds_read_b128 v[218:221], v165 offset:1024
	ds_read_b128 v[222:225], v165 offset:2048
	ds_read_b128 v[226:229], v165 offset:3072
	ds_read_b128 v[230:233], v165 offset:4096
	ds_read_b128 v[234:237], v165 offset:5120
	ds_read_b128 v[238:241], v165 offset:6144
	ds_read_b128 v[242:245], v165 offset:7168
	global_load_lds_dwordx4 v136, s[14:15]
	s_mov_b32 m0, s44
	s_nop 0
	global_load_lds_dwordx4 v138, s[14:15]
	s_waitcnt vmcnt(8)
	s_waitcnt lgkmcnt(0)
	s_setprio 1
	s_barrier
	v_mfma_f32_16x16x32_bf16 v[124:127], v[140:143], v[214:217], v[124:127]
	v_mfma_f32_16x16x32_bf16 v[116:119], v[172:175], v[214:217], v[116:119]
	v_mfma_f32_16x16x32_bf16 v[108:111], v[140:143], v[222:225], v[108:111]
	v_mfma_f32_16x16x32_bf16 v[100:103], v[172:175], v[222:225], v[100:103]
	v_mfma_f32_16x16x32_bf16 v[92:95], v[140:143], v[230:233], v[92:95]
	v_mfma_f32_16x16x32_bf16 v[84:87], v[172:175], v[230:233], v[84:87]
	v_mfma_f32_16x16x32_bf16 v[76:79], v[140:143], v[238:241], v[76:79]
	v_mfma_f32_16x16x32_bf16 v[68:71], v[172:175], v[238:241], v[68:71]
	v_mfma_f32_16x16x32_bf16 v[124:127], v[168:171], v[218:221], v[124:127]
	v_mfma_f32_16x16x32_bf16 v[116:119], v[176:179], v[218:221], v[116:119]
	v_mfma_f32_16x16x32_bf16 v[108:111], v[168:171], v[226:229], v[108:111]
	v_mfma_f32_16x16x32_bf16 v[100:103], v[176:179], v[226:229], v[100:103]
	v_mfma_f32_16x16x32_bf16 v[92:95], v[168:171], v[234:237], v[92:95]
	v_mfma_f32_16x16x32_bf16 v[84:87], v[176:179], v[234:237], v[84:87]
	v_mfma_f32_16x16x32_bf16 v[76:79], v[168:171], v[242:245], v[76:79]
	v_mfma_f32_16x16x32_bf16 v[68:71], v[176:179], v[242:245], v[68:71]
	v_mfma_f32_16x16x32_bf16 v[120:123], v[180:183], v[214:217], v[120:123]
	v_mfma_f32_16x16x32_bf16 v[112:115], v[188:191], v[214:217], v[112:115]
	v_mfma_f32_16x16x32_bf16 v[104:107], v[180:183], v[222:225], v[104:107]
	v_mfma_f32_16x16x32_bf16 v[96:99], v[188:191], v[222:225], v[96:99]
	v_mfma_f32_16x16x32_bf16 v[88:91], v[180:183], v[230:233], v[88:91]
	v_mfma_f32_16x16x32_bf16 v[80:83], v[188:191], v[230:233], v[80:83]
	v_mfma_f32_16x16x32_bf16 v[72:75], v[180:183], v[238:241], v[72:75]
	v_mfma_f32_16x16x32_bf16 v[64:67], v[188:191], v[238:241], v[64:67]
	v_mfma_f32_16x16x32_bf16 v[120:123], v[184:187], v[218:221], v[120:123]
	v_mfma_f32_16x16x32_bf16 v[112:115], v[210:213], v[218:221], v[112:115]
	v_mfma_f32_16x16x32_bf16 v[104:107], v[184:187], v[226:229], v[104:107]
	v_mfma_f32_16x16x32_bf16 v[96:99], v[210:213], v[226:229], v[96:99]
	v_mfma_f32_16x16x32_bf16 v[88:91], v[184:187], v[234:237], v[88:91]
	v_mfma_f32_16x16x32_bf16 v[80:83], v[210:213], v[234:237], v[80:83]
	v_mfma_f32_16x16x32_bf16 v[72:75], v[184:187], v[242:245], v[72:75]
	v_mfma_f32_16x16x32_bf16 v[64:67], v[210:213], v[242:245], v[64:67]
	s_barrier
	s_setprio 0
	s_mov_b32 m0, s27
	s_add_u32 s54, s16, 0x40000
	s_addc_u32 s55, s17, 0
	ds_read_b128 v[214:217], v165 offset:16384
	ds_read_b128 v[218:221], v165 offset:17408
	ds_read_b128 v[222:225], v165 offset:18432
	ds_read_b128 v[226:229], v165 offset:19456
	ds_read_b128 v[230:233], v165 offset:20480
	ds_read_b128 v[234:237], v165 offset:21504
	ds_read_b128 v[238:241], v165 offset:22528
	ds_read_b128 v[242:245], v165 offset:23552
	global_load_lds_dwordx4 v132, s[16:17]
	s_mov_b32 m0, s28
	s_nop 0
	global_load_lds_dwordx4 v128, s[16:17]
	s_mov_b32 m0, s29
	s_nop 0
	global_load_lds_dwordx4 v132, s[54:55]
	s_mov_b32 m0, s30
	s_nop 0
	global_load_lds_dwordx4 v128, s[54:55]
	s_mov_b32 m0, s22
	s_nop 0
	global_load_lds_dwordx4 v134, s[18:19]
	s_mov_b32 m0, s31
	s_nop 0
	global_load_lds_dwordx4 v130, s[18:19]
	s_waitcnt vmcnt(8)
	s_waitcnt lgkmcnt(0)
	s_setprio 1
	s_barrier
	v_mfma_f32_16x16x32_bf16 v[60:63], v[140:143], v[214:217], v[60:63]
	v_mfma_f32_16x16x32_bf16 v[52:55], v[172:175], v[214:217], v[52:55]
	v_mfma_f32_16x16x32_bf16 v[44:47], v[140:143], v[222:225], v[44:47]
	v_mfma_f32_16x16x32_bf16 v[36:39], v[172:175], v[222:225], v[36:39]
	v_mfma_f32_16x16x32_bf16 v[28:31], v[140:143], v[230:233], v[28:31]
	v_mfma_f32_16x16x32_bf16 v[20:23], v[172:175], v[230:233], v[20:23]
	v_mfma_f32_16x16x32_bf16 v[12:15], v[140:143], v[238:241], v[12:15]
	v_mfma_f32_16x16x32_bf16 v[4:7], v[172:175], v[238:241], v[4:7]
	v_mfma_f32_16x16x32_bf16 v[60:63], v[168:171], v[218:221], v[60:63]
	v_mfma_f32_16x16x32_bf16 v[52:55], v[176:179], v[218:221], v[52:55]
	v_mfma_f32_16x16x32_bf16 v[44:47], v[168:171], v[226:229], v[44:47]
	v_mfma_f32_16x16x32_bf16 v[36:39], v[176:179], v[226:229], v[36:39]
	v_mfma_f32_16x16x32_bf16 v[28:31], v[168:171], v[234:237], v[28:31]
	v_mfma_f32_16x16x32_bf16 v[20:23], v[176:179], v[234:237], v[20:23]
	v_mfma_f32_16x16x32_bf16 v[12:15], v[168:171], v[242:245], v[12:15]
	v_mfma_f32_16x16x32_bf16 v[4:7], v[176:179], v[242:245], v[4:7]
	v_mfma_f32_16x16x32_bf16 v[56:59], v[180:183], v[214:217], v[56:59]
	v_mfma_f32_16x16x32_bf16 v[48:51], v[188:191], v[214:217], v[48:51]
	v_mfma_f32_16x16x32_bf16 v[40:43], v[180:183], v[222:225], v[40:43]
	v_mfma_f32_16x16x32_bf16 v[32:35], v[188:191], v[222:225], v[32:35]
	v_mfma_f32_16x16x32_bf16 v[24:27], v[180:183], v[230:233], v[24:27]
	v_mfma_f32_16x16x32_bf16 v[16:19], v[188:191], v[230:233], v[16:19]
	v_mfma_f32_16x16x32_bf16 v[8:11], v[180:183], v[238:241], v[8:11]
	v_mfma_f32_16x16x32_bf16 v[0:3], v[188:191], v[238:241], v[0:3]
	v_mfma_f32_16x16x32_bf16 v[56:59], v[184:187], v[218:221], v[56:59]
	v_mfma_f32_16x16x32_bf16 v[48:51], v[210:213], v[218:221], v[48:51]
	v_mfma_f32_16x16x32_bf16 v[40:43], v[184:187], v[226:229], v[40:43]
	v_mfma_f32_16x16x32_bf16 v[32:35], v[210:213], v[226:229], v[32:35]
	v_mfma_f32_16x16x32_bf16 v[24:27], v[184:187], v[234:237], v[24:27]
	v_mfma_f32_16x16x32_bf16 v[16:19], v[210:213], v[234:237], v[16:19]
	v_mfma_f32_16x16x32_bf16 v[8:11], v[184:187], v[242:245], v[8:11]
	v_mfma_f32_16x16x32_bf16 v[0:3], v[210:213], v[242:245], v[0:3]
	s_barrier
; #define PG8_STAGE(bufoff, gbase, voff) do { _Pragma("unroll") for (int _i = 0; _i < 2; ++_i) \
;         __builtin_amdgcn_global_load_lds((const unsigned*)((const char*)(gbase) + (voff)[_i]), (PG8_LAS unsigned*)(lds + (bufoff) + ldsw + _i * 8192), 16, 0, 0); } while (0)
; #define PG8_LDA(dst, b, h) do { _Pragma("unroll") for (int m = 0; m < 4; ++m) _Pragma("unroll") for (int k = 0; k < 2; ++k) dst[m][k] = *(const PG8_LAS bf16x8*)(lds + PG8_SA(b, h) + aoff + m * 2048 + k * 1024); } while (0)
; #define PG8_LDB(dst, b, h) do { _Pragma("unroll") for (int n = 0; n < 2; ++n) _Pragma("unroll") for (int k = 0; k < 2; ++k) dst[n][k] = *(const PG8_LAS bf16x8*)(lds + PG8_SB(b, h) + boff + n * 2048 + k * 1024); } while (0)
; #define PG8_MMA(ai, bj, At, Bt) do { __builtin_amdgcn_s_setprio(1); _Pragma("unroll") for (int m = 0; m < 4; ++m) _Pragma("unroll") for (int n = 0; n < 2; ++n) _Pragma("unroll") for (int k = 0; k < 2; ++k) \
;         acc[ai][bj][m][n] = __builtin_amdgcn_mfma_f32_16x16x32_bf16(Bt[n][k], At[m][k], acc[ai][bj][m][n], 0, 0, 0); __builtin_amdgcn_s_setprio(0); } while (0)
; #define PG8_WAIT_V(n) asm volatile("s_waitcnt vmcnt(" #n ")" ::: "memory")
; #define PG8_WAIT_L(n) asm volatile("s_waitcnt lgkmcnt(" #n ")" ::: "memory")
; #define PG8_BAR __builtin_amdgcn_s_barrier()
; #define PG8_SCHED __builtin_amdgcn_sched_barrier(0)
; template <class Epi, class Sched, bool ALIGN_EPI = false, bool SP2 = false>
; __device__ __forceinline__ void gemm_phase(PG8_LAS unsigned char* lds, const Gemm g, const Sched& S, const Epi& E) {
;     ...
;             PG8_LDB(B0, 1, 0); PG8_LDB(B1, 1, 1); PG8_SCHED; PG8_LDA(At, 1, 0); PG8_STAGE(PG8_SA(0, 1), a2 + hstep, voffA);
;             PG8_WAIT_V(8); PG8_WAIT_L(0); PG8_BAR; PG8_MMA(0, 0, At, B0); PG8_MMA(0, 1, At, B1); PG8_BAR; PG8_SCHED;
;             PG8_LDA(At, 1, 1); PG8_STAGE(PG8_SB(1, 0), b3, voffB); PG8_STAGE(PG8_SB(1, 1), b3 + hstep, voffB); PG8_STAGE(PG8_SA(1, 0), a3, voffA);
;             PG8_WAIT_V(8); PG8_WAIT_L(0); PG8_BAR; PG8_MMA(1, 0, At, B0); PG8_MMA(1, 1, At, B1); PG8_BAR; PG8_SCHED;
;     ...
;         if constexpr (ALIGN_EPI) { if (wr == 0) PG8_BAR; }
	s_setprio 0
	ds_read_b128 v[140:143], v254 offset:32768
	ds_read_b128 v[168:171], v254 offset:33792
	ds_read_b128 v[172:175], v254 offset:34816
	ds_read_b128 v[176:179], v254 offset:35840
	ds_read_b128 v[180:183], v254 offset:49152
	ds_read_b128 v[184:187], v254 offset:50176
	ds_read_b128 v[188:191], v254 offset:51200
	ds_read_b128 v[210:213], v254 offset:52224
	s_add_u32 s18, s18, 0x40000
	s_addc_u32 s19, s19, 0
	s_mov_b32 m0, s33
	ds_read_b128 v[214:217], v165 offset:32768
	ds_read_b128 v[218:221], v165 offset:33792
	ds_read_b128 v[222:225], v165 offset:34816
	ds_read_b128 v[226:229], v165 offset:35840
	ds_read_b128 v[230:233], v165 offset:36864
	ds_read_b128 v[234:237], v165 offset:37888
	ds_read_b128 v[238:241], v165 offset:38912
	ds_read_b128 v[242:245], v165 offset:39936
	global_load_lds_dwordx4 v134, s[18:19]
	s_mov_b32 m0, s34
	s_nop 0
	global_load_lds_dwordx4 v130, s[18:19]
	s_waitcnt vmcnt(8)
	s_waitcnt lgkmcnt(0)
	s_setprio 1
	s_barrier
	v_mfma_f32_16x16x32_bf16 v[124:127], v[140:143], v[214:217], v[124:127]
	v_mfma_f32_16x16x32_bf16 v[116:119], v[172:175], v[214:217], v[116:119]
	v_mfma_f32_16x16x32_bf16 v[108:111], v[140:143], v[222:225], v[108:111]
	v_mfma_f32_16x16x32_bf16 v[100:103], v[172:175], v[222:225], v[100:103]
	v_mfma_f32_16x16x32_bf16 v[92:95], v[140:143], v[230:233], v[92:95]
	v_mfma_f32_16x16x32_bf16 v[84:87], v[172:175], v[230:233], v[84:87]
	v_mfma_f32_16x16x32_bf16 v[76:79], v[140:143], v[238:241], v[76:79]
	v_mfma_f32_16x16x32_bf16 v[68:71], v[172:175], v[238:241], v[68:71]
	v_mfma_f32_16x16x32_bf16 v[124:127], v[168:171], v[218:221], v[124:127]
	v_mfma_f32_16x16x32_bf16 v[116:119], v[176:179], v[218:221], v[116:119]
	v_mfma_f32_16x16x32_bf16 v[108:111], v[168:171], v[226:229], v[108:111]
	v_mfma_f32_16x16x32_bf16 v[100:103], v[176:179], v[226:229], v[100:103]
	v_mfma_f32_16x16x32_bf16 v[92:95], v[168:171], v[234:237], v[92:95]
	v_mfma_f32_16x16x32_bf16 v[84:87], v[176:179], v[234:237], v[84:87]
	v_mfma_f32_16x16x32_bf16 v[76:79], v[168:171], v[242:245], v[76:79]
	v_mfma_f32_16x16x32_bf16 v[68:71], v[176:179], v[242:245], v[68:71]
	v_mfma_f32_16x16x32_bf16 v[120:123], v[180:183], v[214:217], v[120:123]
	v_mfma_f32_16x16x32_bf16 v[112:115], v[188:191], v[214:217], v[112:115]
	v_mfma_f32_16x16x32_bf16 v[104:107], v[180:183], v[222:225], v[104:107]
	v_mfma_f32_16x16x32_bf16 v[96:99], v[188:191], v[222:225], v[96:99]
	v_mfma_f32_16x16x32_bf16 v[88:91], v[180:183], v[230:233], v[88:91]
	v_mfma_f32_16x16x32_bf16 v[80:83], v[188:191], v[230:233], v[80:83]
	v_mfma_f32_16x16x32_bf16 v[72:75], v[180:183], v[238:241], v[72:75]
	v_mfma_f32_16x16x32_bf16 v[64:67], v[188:191], v[238:241], v[64:67]
	v_mfma_f32_16x16x32_bf16 v[120:123], v[184:187], v[218:221], v[120:123]
	v_mfma_f32_16x16x32_bf16 v[112:115], v[210:213], v[218:221], v[112:115]
	v_mfma_f32_16x16x32_bf16 v[104:107], v[184:187], v[226:229], v[104:107]
	v_mfma_f32_16x16x32_bf16 v[96:99], v[210:213], v[226:229], v[96:99]
	v_mfma_f32_16x16x32_bf16 v[88:91], v[184:187], v[234:237], v[88:91]
	v_mfma_f32_16x16x32_bf16 v[80:83], v[210:213], v[234:237], v[80:83]
	v_mfma_f32_16x16x32_bf16 v[72:75], v[184:187], v[242:245], v[72:75]
	v_mfma_f32_16x16x32_bf16 v[64:67], v[210:213], v[242:245], v[64:67]
	s_barrier
	s_setprio 0
	s_mov_b32 m0, s37
	s_add_u32 s16, s16, 0x40080
	s_addc_u32 s17, s17, 0
	ds_read_b128 v[214:217], v165 offset:49152
	ds_read_b128 v[218:221], v165 offset:50176
	ds_read_b128 v[222:225], v165 offset:51200
	ds_read_b128 v[226:229], v165 offset:52224
	ds_read_b128 v[230:233], v165 offset:53248
	ds_read_b128 v[234:237], v165 offset:54272
	ds_read_b128 v[238:241], v165 offset:55296
	ds_read_b128 v[242:245], v165 offset:56320
	s_add_u32 s98, s16, 0xfffc0000
	s_addc_u32 s99, s17, -1
	global_load_lds_dwordx4 v132, s[98:99]
	s_mov_b32 m0, s38
	s_nop 0
	global_load_lds_dwordx4 v128, s[98:99]
	s_mov_b32 m0, s41
	s_nop 0
	global_load_lds_dwordx4 v132, s[16:17]
	s_mov_b32 m0, s42
	s_nop 0
	global_load_lds_dwordx4 v128, s[16:17]
	s_mov_b32 m0, s39
	s_nop 0
	s_add_u32 s100, s18, 0xfffc0080
	s_addc_u32 s101, s19, -1
	global_load_lds_dwordx4 v134, s[100:101]
	s_mov_b32 m0, s40
	s_nop 0
	global_load_lds_dwordx4 v130, s[100:101]
	s_waitcnt vmcnt(8)
	s_waitcnt lgkmcnt(0)
	s_setprio 1
	s_barrier
	v_mfma_f32_16x16x32_bf16 v[60:63], v[140:143], v[214:217], v[60:63]
	v_mfma_f32_16x16x32_bf16 v[52:55], v[172:175], v[214:217], v[52:55]
	v_mfma_f32_16x16x32_bf16 v[44:47], v[140:143], v[222:225], v[44:47]
	v_mfma_f32_16x16x32_bf16 v[36:39], v[172:175], v[222:225], v[36:39]
	v_mfma_f32_16x16x32_bf16 v[28:31], v[140:143], v[230:233], v[28:31]
	v_mfma_f32_16x16x32_bf16 v[20:23], v[172:175], v[230:233], v[20:23]
	v_mfma_f32_16x16x32_bf16 v[12:15], v[140:143], v[238:241], v[12:15]
	v_mfma_f32_16x16x32_bf16 v[4:7], v[172:175], v[238:241], v[4:7]
	v_mfma_f32_16x16x32_bf16 v[60:63], v[168:171], v[218:221], v[60:63]
	v_mfma_f32_16x16x32_bf16 v[52:55], v[176:179], v[218:221], v[52:55]
	v_mfma_f32_16x16x32_bf16 v[44:47], v[168:171], v[226:229], v[44:47]
	v_mfma_f32_16x16x32_bf16 v[36:39], v[176:179], v[226:229], v[36:39]
	v_mfma_f32_16x16x32_bf16 v[28:31], v[168:171], v[234:237], v[28:31]
	v_mfma_f32_16x16x32_bf16 v[20:23], v[176:179], v[234:237], v[20:23]
	v_mfma_f32_16x16x32_bf16 v[12:15], v[168:171], v[242:245], v[12:15]
	v_mfma_f32_16x16x32_bf16 v[4:7], v[176:179], v[242:245], v[4:7]
	v_mfma_f32_16x16x32_bf16 v[56:59], v[180:183], v[214:217], v[56:59]
	v_mfma_f32_16x16x32_bf16 v[48:51], v[188:191], v[214:217], v[48:51]
	v_mfma_f32_16x16x32_bf16 v[40:43], v[180:183], v[222:225], v[40:43]
	v_mfma_f32_16x16x32_bf16 v[32:35], v[188:191], v[222:225], v[32:35]
	v_mfma_f32_16x16x32_bf16 v[24:27], v[180:183], v[230:233], v[24:27]
	v_mfma_f32_16x16x32_bf16 v[16:19], v[188:191], v[230:233], v[16:19]
	v_mfma_f32_16x16x32_bf16 v[8:11], v[180:183], v[238:241], v[8:11]
	v_mfma_f32_16x16x32_bf16 v[0:3], v[188:191], v[238:241], v[0:3]
	v_mfma_f32_16x16x32_bf16 v[56:59], v[184:187], v[218:221], v[56:59]
	v_mfma_f32_16x16x32_bf16 v[48:51], v[210:213], v[218:221], v[48:51]
	v_mfma_f32_16x16x32_bf16 v[40:43], v[184:187], v[226:229], v[40:43]
	v_mfma_f32_16x16x32_bf16 v[32:35], v[210:213], v[226:229], v[32:35]
	v_mfma_f32_16x16x32_bf16 v[24:27], v[184:187], v[234:237], v[24:27]
	v_mfma_f32_16x16x32_bf16 v[16:19], v[210:213], v[234:237], v[16:19]
	v_mfma_f32_16x16x32_bf16 v[8:11], v[184:187], v[242:245], v[8:11]
	v_mfma_f32_16x16x32_bf16 v[0:3], v[210:213], v[242:245], v[0:3]
	s_barrier
	s_setprio 0
	s_add_i32 s53, s53, 2
	s_add_u32 s14, s14, 0x100
	s_addc_u32 s15, s15, 0
	s_add_u32 s51, s51, 0x100
	s_addc_u32 s52, s52, 0
	s_cmp_gt_u32 s53, 13
	s_cbranch_scc0 .LBB0_446
	s_and_b64 vcc, exec, s[2:3]
	s_cbranch_vccz .LBB0_449
	s_barrier

; #define PG8_STAGE(bufoff, gbase, voff) do { _Pragma("unroll") for (int _i = 0; _i < 2; ++_i) \
;         __builtin_amdgcn_global_load_lds((const unsigned*)((const char*)(gbase) + (voff)[_i]), (PG8_LAS unsigned*)(lds + (bufoff) + ldsw + _i * 8192), 16, 0, 0); } while (0)
; #define PG8_LDA(dst, b, h) do { _Pragma("unroll") for (int m = 0; m < 4; ++m) _Pragma("unroll") for (int k = 0; k < 2; ++k) dst[m][k] = *(const PG8_LAS bf16x8*)(lds + PG8_SA(b, h) + aoff + m * 2048 + k * 1024); } while (0)
; #define PG8_LDB(dst, b, h) do { _Pragma("unroll") for (int n = 0; n < 2; ++n) _Pragma("unroll") for (int k = 0; k < 2; ++k) dst[n][k] = *(const PG8_LAS bf16x8*)(lds + PG8_SB(b, h) + boff + n * 2048 + k * 1024); } while (0)
; #define PG8_MMA(ai, bj, At, Bt) do { __builtin_amdgcn_s_setprio(1); _Pragma("unroll") for (int m = 0; m < 4; ++m) _Pragma("unroll") for (int n = 0; n < 2; ++n) _Pragma("unroll") for (int k = 0; k < 2; ++k) \
;         acc[ai][bj][m][n] = __builtin_amdgcn_mfma_f32_16x16x32_bf16(Bt[n][k], At[m][k], acc[ai][bj][m][n], 0, 0, 0); __builtin_amdgcn_s_setprio(0); } while (0)
; #define PG8_WAIT_V(n) asm volatile("s_waitcnt vmcnt(" #n ")" ::: "memory")
; #define PG8_WAIT_L(n) asm volatile("s_waitcnt lgkmcnt(" #n ")" ::: "memory")
; #define PG8_BAR __builtin_amdgcn_s_barrier()
; #define PG8_SCHED __builtin_amdgcn_sched_barrier(0)
; template <class Epi, class Sched, bool ALIGN_EPI = false, bool SP2 = false>
; __device__ __forceinline__ void gemm_phase(PG8_LAS unsigned char* lds, const Gemm g, const Sched& S, const Epi& E) {
;     ...
;             PG8_LDB(B0, 0, 0); PG8_LDB(B1, 0, 1); PG8_SCHED; PG8_LDA(At, 0, 0); PG8_STAGE(PG8_SA(1, 1), a1 + hstep, voffA);
;             PG8_WAIT_V(8); PG8_WAIT_L(0); PG8_BAR; PG8_MMA(0, 0, At, B0); PG8_MMA(0, 1, At, B1); PG8_BAR; PG8_SCHED;
;             PG8_LDA(At, 0, 1); PG8_STAGE(PG8_SB(0, 0), b2, voffB); PG8_STAGE(PG8_SB(0, 1), b2 + hstep, voffB); PG8_STAGE(PG8_SA(0, 0), a2, voffA);
;             PG8_WAIT_V(8); PG8_WAIT_L(0); PG8_BAR; PG8_MMA(1, 0, At, B0); PG8_MMA(1, 1, At, B1); PG8_BAR; PG8_SCHED;
.Ldn_peel:
	ds_read_b128 v[128:131], v254
	ds_read_b128 v[132:135], v254 offset:1024
	ds_read_b128 v[136:139], v254 offset:2048
	ds_read_b128 v[140:143], v254 offset:3072
	ds_read_b128 v[174:177], v254 offset:16384
	ds_read_b128 v[184:187], v254 offset:17408
	ds_read_b128 v[188:191], v254 offset:18432
	ds_read_b128 v[210:213], v254 offset:19456
	s_add_u32 s2, s0, 0x100
	s_addc_u32 s3, s1, 0
	s_cmp_eq_u32 s13, 40
	s_cselect_b32 s7, s27, s3
	s_cselect_b32 s6, s26, s2
	s_cselect_b32 s5, s37, s11
	s_cselect_b32 s4, s36, s10
	s_add_i32 m0, s29, 0xc000
	ds_read_b128 v[214:217], v181
	ds_read_b128 v[218:221], v181 offset:1024
	ds_read_b128 v[222:225], v181 offset:2048
	ds_read_b128 v[226:229], v181 offset:3072
	ds_read_b128 v[230:233], v181 offset:4096
	ds_read_b128 v[234:237], v181 offset:5120
	ds_read_b128 v[238:241], v181 offset:6144
	ds_read_b128 v[242:245], v181 offset:7168
	global_load_lds_dwordx4 v170, s[0:1]
	s_add_i32 m0, s29, 0xe000
	s_nop 0
	global_load_lds_dwordx4 v172, s[0:1]
	s_waitcnt vmcnt(8)
	s_waitcnt lgkmcnt(0)
	s_setprio 1
	s_barrier
	v_mfma_f32_16x16x32_bf16 v[124:127], v[128:131], v[214:217], 0
	v_mfma_f32_16x16x32_bf16 v[120:123], v[136:139], v[214:217], 0
	v_mfma_f32_16x16x32_bf16 v[108:111], v[128:131], v[222:225], 0
	v_mfma_f32_16x16x32_bf16 v[104:107], v[136:139], v[222:225], 0
	v_mfma_f32_16x16x32_bf16 v[92:95], v[128:131], v[230:233], 0
	v_mfma_f32_16x16x32_bf16 v[88:91], v[136:139], v[230:233], 0
	v_mfma_f32_16x16x32_bf16 v[76:79], v[128:131], v[238:241], 0
	v_mfma_f32_16x16x32_bf16 v[72:75], v[136:139], v[238:241], 0
	v_mfma_f32_16x16x32_bf16 v[124:127], v[132:135], v[218:221], v[124:127]
	v_mfma_f32_16x16x32_bf16 v[120:123], v[140:143], v[218:221], v[120:123]
	v_mfma_f32_16x16x32_bf16 v[108:111], v[132:135], v[226:229], v[108:111]
	v_mfma_f32_16x16x32_bf16 v[104:107], v[140:143], v[226:229], v[104:107]
	v_mfma_f32_16x16x32_bf16 v[92:95], v[132:135], v[234:237], v[92:95]
	v_mfma_f32_16x16x32_bf16 v[88:91], v[140:143], v[234:237], v[88:91]
	v_mfma_f32_16x16x32_bf16 v[76:79], v[132:135], v[242:245], v[76:79]
	v_mfma_f32_16x16x32_bf16 v[72:75], v[140:143], v[242:245], v[72:75]
	v_mfma_f32_16x16x32_bf16 v[116:119], v[174:177], v[214:217], 0
	v_mfma_f32_16x16x32_bf16 v[112:115], v[188:191], v[214:217], 0
	v_mfma_f32_16x16x32_bf16 v[100:103], v[174:177], v[222:225], 0
	v_mfma_f32_16x16x32_bf16 v[96:99], v[188:191], v[222:225], 0
	v_mfma_f32_16x16x32_bf16 v[84:87], v[174:177], v[230:233], 0
	v_mfma_f32_16x16x32_bf16 v[80:83], v[188:191], v[230:233], 0
	v_mfma_f32_16x16x32_bf16 v[68:71], v[174:177], v[238:241], 0
	v_mfma_f32_16x16x32_bf16 v[64:67], v[188:191], v[238:241], 0
	v_mfma_f32_16x16x32_bf16 v[116:119], v[184:187], v[218:221], v[116:119]
	v_mfma_f32_16x16x32_bf16 v[112:115], v[210:213], v[218:221], v[112:115]
	v_mfma_f32_16x16x32_bf16 v[100:103], v[184:187], v[226:229], v[100:103]
	v_mfma_f32_16x16x32_bf16 v[96:99], v[210:213], v[226:229], v[96:99]
	v_mfma_f32_16x16x32_bf16 v[84:87], v[184:187], v[234:237], v[84:87]
	v_mfma_f32_16x16x32_bf16 v[80:83], v[210:213], v[234:237], v[80:83]
	v_mfma_f32_16x16x32_bf16 v[68:71], v[184:187], v[242:245], v[68:71]
	v_mfma_f32_16x16x32_bf16 v[64:67], v[210:213], v[242:245], v[64:67]
	s_barrier
	s_setprio 0
	s_mov_b32 m0, s35
	s_add_u32 s0, s4, 0xb0000
	s_addc_u32 s1, s5, 0
	ds_read_b128 v[214:217], v181 offset:16384
	ds_read_b128 v[218:221], v181 offset:17408
	ds_read_b128 v[222:225], v181 offset:18432
	ds_read_b128 v[226:229], v181 offset:19456
	ds_read_b128 v[230:233], v181 offset:20480
	ds_read_b128 v[234:237], v181 offset:21504
	ds_read_b128 v[238:241], v181 offset:22528
	ds_read_b128 v[242:245], v181 offset:23552
	global_load_lds_dwordx4 v166, s[4:5]
	s_mov_b32 m0, s38
	s_nop 0
	global_load_lds_dwordx4 v162, s[4:5]
	s_mov_b32 m0, s39
	s_nop 0
	global_load_lds_dwordx4 v166, s[0:1]
	s_mov_b32 m0, s40
	s_nop 0
	global_load_lds_dwordx4 v162, s[0:1]
	s_mov_b32 m0, s29
	s_nop 0
	global_load_lds_dwordx4 v168, s[6:7]
	s_mov_b32 m0, s41
	s_nop 0
	global_load_lds_dwordx4 v164, s[6:7]
	s_waitcnt vmcnt(8)
	s_waitcnt lgkmcnt(0)
	s_setprio 1
	s_barrier
	v_mfma_f32_16x16x32_bf16 v[60:63], v[128:131], v[214:217], 0
	v_mfma_f32_16x16x32_bf16 v[56:59], v[136:139], v[214:217], 0
	v_mfma_f32_16x16x32_bf16 v[44:47], v[128:131], v[222:225], 0
	v_mfma_f32_16x16x32_bf16 v[40:43], v[136:139], v[222:225], 0
	v_mfma_f32_16x16x32_bf16 v[28:31], v[128:131], v[230:233], 0
	v_mfma_f32_16x16x32_bf16 v[24:27], v[136:139], v[230:233], 0
	v_mfma_f32_16x16x32_bf16 v[12:15], v[128:131], v[238:241], 0
	v_mfma_f32_16x16x32_bf16 v[8:11], v[136:139], v[238:241], 0
	v_mfma_f32_16x16x32_bf16 v[60:63], v[132:135], v[218:221], v[60:63]
	v_mfma_f32_16x16x32_bf16 v[56:59], v[140:143], v[218:221], v[56:59]
	v_mfma_f32_16x16x32_bf16 v[44:47], v[132:135], v[226:229], v[44:47]
	v_mfma_f32_16x16x32_bf16 v[40:43], v[140:143], v[226:229], v[40:43]
	v_mfma_f32_16x16x32_bf16 v[28:31], v[132:135], v[234:237], v[28:31]
	v_mfma_f32_16x16x32_bf16 v[24:27], v[140:143], v[234:237], v[24:27]
	v_mfma_f32_16x16x32_bf16 v[12:15], v[132:135], v[242:245], v[12:15]
	v_mfma_f32_16x16x32_bf16 v[8:11], v[140:143], v[242:245], v[8:11]
	v_mfma_f32_16x16x32_bf16 v[52:55], v[174:177], v[214:217], 0
	v_mfma_f32_16x16x32_bf16 v[48:51], v[188:191], v[214:217], 0
	v_mfma_f32_16x16x32_bf16 v[36:39], v[174:177], v[222:225], 0
	v_mfma_f32_16x16x32_bf16 v[32:35], v[188:191], v[222:225], 0
	v_mfma_f32_16x16x32_bf16 v[20:23], v[174:177], v[230:233], 0
	v_mfma_f32_16x16x32_bf16 v[16:19], v[188:191], v[230:233], 0
	v_mfma_f32_16x16x32_bf16 v[4:7], v[174:177], v[238:241], 0
	v_mfma_f32_16x16x32_bf16 v[0:3], v[188:191], v[238:241], 0
	v_mfma_f32_16x16x32_bf16 v[52:55], v[184:187], v[218:221], v[52:55]
	v_mfma_f32_16x16x32_bf16 v[48:51], v[210:213], v[218:221], v[48:51]
	v_mfma_f32_16x16x32_bf16 v[36:39], v[184:187], v[226:229], v[36:39]
	v_mfma_f32_16x16x32_bf16 v[32:35], v[210:213], v[226:229], v[32:35]
	v_mfma_f32_16x16x32_bf16 v[20:23], v[184:187], v[234:237], v[20:23]
	v_mfma_f32_16x16x32_bf16 v[16:19], v[210:213], v[234:237], v[16:19]
	v_mfma_f32_16x16x32_bf16 v[4:7], v[184:187], v[242:245], v[4:7]
	v_mfma_f32_16x16x32_bf16 v[0:3], v[210:213], v[242:245], v[0:3]
	s_barrier
; #define PG8_STAGE(bufoff, gbase, voff) do { _Pragma("unroll") for (int _i = 0; _i < 2; ++_i) \
;         __builtin_amdgcn_global_load_lds((const unsigned*)((const char*)(gbase) + (voff)[_i]), (PG8_LAS unsigned*)(lds + (bufoff) + ldsw + _i * 8192), 16, 0, 0); } while (0)
; #define PG8_LDA(dst, b, h) do { _Pragma("unroll") for (int m = 0; m < 4; ++m) _Pragma("unroll") for (int k = 0; k < 2; ++k) dst[m][k] = *(const PG8_LAS bf16x8*)(lds + PG8_SA(b, h) + aoff + m * 2048 + k * 1024); } while (0)
; #define PG8_LDB(dst, b, h) do { _Pragma("unroll") for (int n = 0; n < 2; ++n) _Pragma("unroll") for (int k = 0; k < 2; ++k) dst[n][k] = *(const PG8_LAS bf16x8*)(lds + PG8_SB(b, h) + boff + n * 2048 + k * 1024); } while (0)
; #define PG8_MMA(ai, bj, At, Bt) do { __builtin_amdgcn_s_setprio(1); _Pragma("unroll") for (int m = 0; m < 4; ++m) _Pragma("unroll") for (int n = 0; n < 2; ++n) _Pragma("unroll") for (int k = 0; k < 2; ++k) \
;         acc[ai][bj][m][n] = __builtin_amdgcn_mfma_f32_16x16x32_bf16(Bt[n][k], At[m][k], acc[ai][bj][m][n], 0, 0, 0); __builtin_amdgcn_s_setprio(0); } while (0)
; #define PG8_WAIT_V(n) asm volatile("s_waitcnt vmcnt(" #n ")" ::: "memory")
; #define PG8_WAIT_L(n) asm volatile("s_waitcnt lgkmcnt(" #n ")" ::: "memory")
; #define PG8_BAR __builtin_amdgcn_s_barrier()
; #define PG8_SCHED __builtin_amdgcn_sched_barrier(0)
; template <class Epi, class Sched, bool ALIGN_EPI = false, bool SP2 = false>
; __device__ __forceinline__ void gemm_phase(PG8_LAS unsigned char* lds, const Gemm g, const Sched& S, const Epi& E) {
;     ...
;             PG8_LDB(B0, 1, 0); PG8_LDB(B1, 1, 1); PG8_SCHED; PG8_LDA(At, 1, 0); PG8_STAGE(PG8_SA(0, 1), a2 + hstep, voffA);
;             PG8_WAIT_V(8); PG8_WAIT_L(0); PG8_BAR; PG8_MMA(0, 0, At, B0); PG8_MMA(0, 1, At, B1); PG8_BAR; PG8_SCHED;
;             PG8_LDA(At, 1, 1); PG8_STAGE(PG8_SB(1, 0), b3, voffB); PG8_STAGE(PG8_SB(1, 1), b3 + hstep, voffB); PG8_STAGE(PG8_SA(1, 0), a3, voffA);
;             PG8_WAIT_V(8); PG8_WAIT_L(0); PG8_BAR; PG8_MMA(1, 0, At, B0); PG8_MMA(1, 1, At, B1); PG8_BAR; PG8_SCHED;
	s_setprio 0
	ds_read_b128 v[128:131], v254 offset:32768
	ds_read_b128 v[132:135], v254 offset:33792
	ds_read_b128 v[136:139], v254 offset:34816
	ds_read_b128 v[140:143], v254 offset:35840
	ds_read_b128 v[174:177], v254 offset:49152
	ds_read_b128 v[184:187], v254 offset:50176
	ds_read_b128 v[188:191], v254 offset:51200
	ds_read_b128 v[210:213], v254 offset:52224
	s_add_u32 s0, s6, 0xb0000
	s_addc_u32 s1, s7, 0
	s_mov_b32 m0, s42
	ds_read_b128 v[214:217], v181 offset:32768
	ds_read_b128 v[218:221], v181 offset:33792
	ds_read_b128 v[222:225], v181 offset:34816
	ds_read_b128 v[226:229], v181 offset:35840
	ds_read_b128 v[230:233], v181 offset:36864
	ds_read_b128 v[234:237], v181 offset:37888
	ds_read_b128 v[238:241], v181 offset:38912
	ds_read_b128 v[242:245], v181 offset:39936
	global_load_lds_dwordx4 v168, s[0:1]
	s_mov_b32 m0, s43
	s_nop 0
	global_load_lds_dwordx4 v164, s[0:1]
	s_waitcnt vmcnt(8)
	s_waitcnt lgkmcnt(0)
	s_setprio 1
	s_barrier
	v_mfma_f32_16x16x32_bf16 v[124:127], v[128:131], v[214:217], v[124:127]
	v_mfma_f32_16x16x32_bf16 v[120:123], v[136:139], v[214:217], v[120:123]
	v_mfma_f32_16x16x32_bf16 v[108:111], v[128:131], v[222:225], v[108:111]
	v_mfma_f32_16x16x32_bf16 v[104:107], v[136:139], v[222:225], v[104:107]
	v_mfma_f32_16x16x32_bf16 v[92:95], v[128:131], v[230:233], v[92:95]
	v_mfma_f32_16x16x32_bf16 v[88:91], v[136:139], v[230:233], v[88:91]
	v_mfma_f32_16x16x32_bf16 v[76:79], v[128:131], v[238:241], v[76:79]
	v_mfma_f32_16x16x32_bf16 v[72:75], v[136:139], v[238:241], v[72:75]
	v_mfma_f32_16x16x32_bf16 v[124:127], v[132:135], v[218:221], v[124:127]
	v_mfma_f32_16x16x32_bf16 v[120:123], v[140:143], v[218:221], v[120:123]
	v_mfma_f32_16x16x32_bf16 v[108:111], v[132:135], v[226:229], v[108:111]
	v_mfma_f32_16x16x32_bf16 v[104:107], v[140:143], v[226:229], v[104:107]
	v_mfma_f32_16x16x32_bf16 v[92:95], v[132:135], v[234:237], v[92:95]
	v_mfma_f32_16x16x32_bf16 v[88:91], v[140:143], v[234:237], v[88:91]
	v_mfma_f32_16x16x32_bf16 v[76:79], v[132:135], v[242:245], v[76:79]
	v_mfma_f32_16x16x32_bf16 v[72:75], v[140:143], v[242:245], v[72:75]
	v_mfma_f32_16x16x32_bf16 v[116:119], v[174:177], v[214:217], v[116:119]
	v_mfma_f32_16x16x32_bf16 v[112:115], v[188:191], v[214:217], v[112:115]
	v_mfma_f32_16x16x32_bf16 v[100:103], v[174:177], v[222:225], v[100:103]
	v_mfma_f32_16x16x32_bf16 v[96:99], v[188:191], v[222:225], v[96:99]
	v_mfma_f32_16x16x32_bf16 v[84:87], v[174:177], v[230:233], v[84:87]
	v_mfma_f32_16x16x32_bf16 v[80:83], v[188:191], v[230:233], v[80:83]
	v_mfma_f32_16x16x32_bf16 v[68:71], v[174:177], v[238:241], v[68:71]
	v_mfma_f32_16x16x32_bf16 v[64:67], v[188:191], v[238:241], v[64:67]
	v_mfma_f32_16x16x32_bf16 v[116:119], v[184:187], v[218:221], v[116:119]
	v_mfma_f32_16x16x32_bf16 v[112:115], v[210:213], v[218:221], v[112:115]
	v_mfma_f32_16x16x32_bf16 v[100:103], v[184:187], v[226:229], v[100:103]
	v_mfma_f32_16x16x32_bf16 v[96:99], v[210:213], v[226:229], v[96:99]
	v_mfma_f32_16x16x32_bf16 v[84:87], v[184:187], v[234:237], v[84:87]
	v_mfma_f32_16x16x32_bf16 v[80:83], v[210:213], v[234:237], v[80:83]
	v_mfma_f32_16x16x32_bf16 v[68:71], v[184:187], v[242:245], v[68:71]
	v_mfma_f32_16x16x32_bf16 v[64:67], v[210:213], v[242:245], v[64:67]
	s_barrier
	s_setprio 0
	s_mov_b32 m0, s47
	s_add_u32 s0, s4, 0xb0080
	s_addc_u32 s1, s5, 0
	ds_read_b128 v[214:217], v181 offset:49152
	ds_read_b128 v[218:221], v181 offset:50176
	ds_read_b128 v[222:225], v181 offset:51200
	ds_read_b128 v[226:229], v181 offset:52224
	ds_read_b128 v[230:233], v181 offset:53248
	ds_read_b128 v[234:237], v181 offset:54272
	ds_read_b128 v[238:241], v181 offset:55296
	ds_read_b128 v[242:245], v181 offset:56320
	s_add_u32 s98, s4, 0x80
	s_addc_u32 s99, s5, 0
	global_load_lds_dwordx4 v166, s[98:99]
	s_mov_b32 m0, s48
	s_nop 0
	global_load_lds_dwordx4 v162, s[98:99]
	s_mov_b32 m0, s51
	s_nop 0
	global_load_lds_dwordx4 v166, s[0:1]
	s_mov_b32 m0, s52
	s_nop 0
	global_load_lds_dwordx4 v162, s[0:1]
	s_mov_b32 m0, s49
	s_nop 0
	s_add_u32 s100, s6, 0x80
	s_addc_u32 s101, s7, 0
	global_load_lds_dwordx4 v168, s[100:101]
	s_mov_b32 m0, s50
	s_nop 0
	global_load_lds_dwordx4 v164, s[100:101]
	s_waitcnt vmcnt(8)
	s_waitcnt lgkmcnt(0)
	s_setprio 1
	s_barrier
	v_mfma_f32_16x16x32_bf16 v[60:63], v[128:131], v[214:217], v[60:63]
	v_mfma_f32_16x16x32_bf16 v[56:59], v[136:139], v[214:217], v[56:59]
	v_mfma_f32_16x16x32_bf16 v[44:47], v[128:131], v[222:225], v[44:47]
	v_mfma_f32_16x16x32_bf16 v[40:43], v[136:139], v[222:225], v[40:43]
	v_mfma_f32_16x16x32_bf16 v[28:31], v[128:131], v[230:233], v[28:31]
	v_mfma_f32_16x16x32_bf16 v[24:27], v[136:139], v[230:233], v[24:27]
	v_mfma_f32_16x16x32_bf16 v[12:15], v[128:131], v[238:241], v[12:15]
	v_mfma_f32_16x16x32_bf16 v[8:11], v[136:139], v[238:241], v[8:11]
	v_mfma_f32_16x16x32_bf16 v[60:63], v[132:135], v[218:221], v[60:63]
	v_mfma_f32_16x16x32_bf16 v[56:59], v[140:143], v[218:221], v[56:59]
	v_mfma_f32_16x16x32_bf16 v[44:47], v[132:135], v[226:229], v[44:47]
	v_mfma_f32_16x16x32_bf16 v[40:43], v[140:143], v[226:229], v[40:43]
	v_mfma_f32_16x16x32_bf16 v[28:31], v[132:135], v[234:237], v[28:31]
	v_mfma_f32_16x16x32_bf16 v[24:27], v[140:143], v[234:237], v[24:27]
	v_mfma_f32_16x16x32_bf16 v[12:15], v[132:135], v[242:245], v[12:15]
	v_mfma_f32_16x16x32_bf16 v[8:11], v[140:143], v[242:245], v[8:11]
	v_mfma_f32_16x16x32_bf16 v[52:55], v[174:177], v[214:217], v[52:55]
	v_mfma_f32_16x16x32_bf16 v[48:51], v[188:191], v[214:217], v[48:51]
	v_mfma_f32_16x16x32_bf16 v[36:39], v[174:177], v[222:225], v[36:39]
	v_mfma_f32_16x16x32_bf16 v[32:35], v[188:191], v[222:225], v[32:35]
	v_mfma_f32_16x16x32_bf16 v[20:23], v[174:177], v[230:233], v[20:23]
	v_mfma_f32_16x16x32_bf16 v[16:19], v[188:191], v[230:233], v[16:19]
	v_mfma_f32_16x16x32_bf16 v[4:7], v[174:177], v[238:241], v[4:7]
	v_mfma_f32_16x16x32_bf16 v[0:3], v[188:191], v[238:241], v[0:3]
	v_mfma_f32_16x16x32_bf16 v[52:55], v[184:187], v[218:221], v[52:55]
	v_mfma_f32_16x16x32_bf16 v[48:51], v[210:213], v[218:221], v[48:51]
	v_mfma_f32_16x16x32_bf16 v[36:39], v[184:187], v[226:229], v[36:39]
	v_mfma_f32_16x16x32_bf16 v[32:35], v[210:213], v[226:229], v[32:35]
	v_mfma_f32_16x16x32_bf16 v[20:23], v[184:187], v[234:237], v[20:23]
	v_mfma_f32_16x16x32_bf16 v[16:19], v[210:213], v[234:237], v[16:19]
	v_mfma_f32_16x16x32_bf16 v[4:7], v[184:187], v[242:245], v[4:7]
	v_mfma_f32_16x16x32_bf16 v[0:3], v[210:213], v[242:245], v[0:3]
	s_barrier
	s_setprio 0
	s_add_i32 s13, s13, 2
	s_add_u32 s10, s10, 0x100
	s_addc_u32 s11, s11, 0
	s_cmp_gt_u32 s13, 41
	s_mov_b64 s[0:1], s[2:3]
; #define PG8_STAGE(bufoff, gbase, voff) do { _Pragma("unroll") for (int _i = 0; _i < 2; ++_i) \
;         __builtin_amdgcn_global_load_lds((const unsigned*)((const char*)(gbase) + (voff)[_i]), (PG8_LAS unsigned*)(lds + (bufoff) + ldsw + _i * 8192), 16, 0, 0); } while (0)
; #define PG8_LDA(dst, b, h) do { _Pragma("unroll") for (int m = 0; m < 4; ++m) _Pragma("unroll") for (int k = 0; k < 2; ++k) dst[m][k] = *(const PG8_LAS bf16x8*)(lds + PG8_SA(b, h) + aoff + m * 2048 + k * 1024); } while (0)
; #define PG8_LDB(dst, b, h) do { _Pragma("unroll") for (int n = 0; n < 2; ++n) _Pragma("unroll") for (int k = 0; k < 2; ++k) dst[n][k] = *(const PG8_LAS bf16x8*)(lds + PG8_SB(b, h) + boff + n * 2048 + k * 1024); } while (0)
; #define PG8_MMA(ai, bj, At, Bt) do { __builtin_amdgcn_s_setprio(1); _Pragma("unroll") for (int m = 0; m < 4; ++m) _Pragma("unroll") for (int n = 0; n < 2; ++n) _Pragma("unroll") for (int k = 0; k < 2; ++k) \
;         acc[ai][bj][m][n] = __builtin_amdgcn_mfma_f32_16x16x32_bf16(Bt[n][k], At[m][k], acc[ai][bj][m][n], 0, 0, 0); __builtin_amdgcn_s_setprio(0); } while (0)
; #define PG8_WAIT_V(n) asm volatile("s_waitcnt vmcnt(" #n ")" ::: "memory")
; #define PG8_WAIT_L(n) asm volatile("s_waitcnt lgkmcnt(" #n ")" ::: "memory")
; #define PG8_BAR __builtin_amdgcn_s_barrier()
; #define PG8_SCHED __builtin_amdgcn_sched_barrier(0)
; template <class Epi, class Sched, bool ALIGN_EPI = false, bool SP2 = false>
; __device__ __forceinline__ void gemm_phase(PG8_LAS unsigned char* lds, const Gemm g, const Sched& S, const Epi& E) {
;     ...
;             PG8_LDB(B0, 0, 0); PG8_LDB(B1, 0, 1); PG8_SCHED; PG8_LDA(At, 0, 0); PG8_STAGE(PG8_SA(1, 1), a1 + hstep, voffA);
;             PG8_WAIT_V(8); PG8_WAIT_L(0); PG8_BAR; PG8_MMA(0, 0, At, B0); PG8_MMA(0, 1, At, B1); PG8_BAR; PG8_SCHED;
;             PG8_LDA(At, 0, 1); PG8_STAGE(PG8_SB(0, 0), b2, voffB); PG8_STAGE(PG8_SB(0, 1), b2 + hstep, voffB); PG8_STAGE(PG8_SA(0, 0), a2, voffA);
;             PG8_WAIT_V(8); PG8_WAIT_L(0); PG8_BAR; PG8_MMA(1, 0, At, B0); PG8_MMA(1, 1, At, B1); PG8_BAR; PG8_SCHED;
.LBB0_545:
	ds_read_b128 v[128:131], v254
	ds_read_b128 v[132:135], v254 offset:1024
	ds_read_b128 v[136:139], v254 offset:2048
	ds_read_b128 v[140:143], v254 offset:3072
	ds_read_b128 v[174:177], v254 offset:16384
	ds_read_b128 v[184:187], v254 offset:17408
	ds_read_b128 v[188:191], v254 offset:18432
	ds_read_b128 v[210:213], v254 offset:19456
	s_add_u32 s2, s0, 0x100
	s_addc_u32 s3, s1, 0
	s_cmp_eq_u32 s13, 40
	s_cselect_b32 s7, s27, s3
	s_cselect_b32 s6, s26, s2
	s_cselect_b32 s5, s37, s11
	s_cselect_b32 s4, s36, s10
	s_add_i32 m0, s29, 0xc000
	ds_read_b128 v[214:217], v181
	ds_read_b128 v[218:221], v181 offset:1024
	ds_read_b128 v[222:225], v181 offset:2048
	ds_read_b128 v[226:229], v181 offset:3072
	ds_read_b128 v[230:233], v181 offset:4096
	ds_read_b128 v[234:237], v181 offset:5120
	ds_read_b128 v[238:241], v181 offset:6144
	ds_read_b128 v[242:245], v181 offset:7168
	global_load_lds_dwordx4 v170, s[0:1]
	s_add_i32 m0, s29, 0xe000
	s_nop 0
	global_load_lds_dwordx4 v172, s[0:1]
	s_waitcnt vmcnt(8)
	s_waitcnt lgkmcnt(0)
	s_setprio 1
	s_barrier
	v_mfma_f32_16x16x32_bf16 v[124:127], v[128:131], v[214:217], v[124:127]
	v_mfma_f32_16x16x32_bf16 v[120:123], v[136:139], v[214:217], v[120:123]
	v_mfma_f32_16x16x32_bf16 v[108:111], v[128:131], v[222:225], v[108:111]
	v_mfma_f32_16x16x32_bf16 v[104:107], v[136:139], v[222:225], v[104:107]
	v_mfma_f32_16x16x32_bf16 v[92:95], v[128:131], v[230:233], v[92:95]
	v_mfma_f32_16x16x32_bf16 v[88:91], v[136:139], v[230:233], v[88:91]
	v_mfma_f32_16x16x32_bf16 v[76:79], v[128:131], v[238:241], v[76:79]
	v_mfma_f32_16x16x32_bf16 v[72:75], v[136:139], v[238:241], v[72:75]
	v_mfma_f32_16x16x32_bf16 v[124:127], v[132:135], v[218:221], v[124:127]
	v_mfma_f32_16x16x32_bf16 v[120:123], v[140:143], v[218:221], v[120:123]
	v_mfma_f32_16x16x32_bf16 v[108:111], v[132:135], v[226:229], v[108:111]
	v_mfma_f32_16x16x32_bf16 v[104:107], v[140:143], v[226:229], v[104:107]
	v_mfma_f32_16x16x32_bf16 v[92:95], v[132:135], v[234:237], v[92:95]
	v_mfma_f32_16x16x32_bf16 v[88:91], v[140:143], v[234:237], v[88:91]
	v_mfma_f32_16x16x32_bf16 v[76:79], v[132:135], v[242:245], v[76:79]
	v_mfma_f32_16x16x32_bf16 v[72:75], v[140:143], v[242:245], v[72:75]
	v_mfma_f32_16x16x32_bf16 v[116:119], v[174:177], v[214:217], v[116:119]
	v_mfma_f32_16x16x32_bf16 v[112:115], v[188:191], v[214:217], v[112:115]
	v_mfma_f32_16x16x32_bf16 v[100:103], v[174:177], v[222:225], v[100:103]
	v_mfma_f32_16x16x32_bf16 v[96:99], v[188:191], v[222:225], v[96:99]
	v_mfma_f32_16x16x32_bf16 v[84:87], v[174:177], v[230:233], v[84:87]
	v_mfma_f32_16x16x32_bf16 v[80:83], v[188:191], v[230:233], v[80:83]
	v_mfma_f32_16x16x32_bf16 v[68:71], v[174:177], v[238:241], v[68:71]
	v_mfma_f32_16x16x32_bf16 v[64:67], v[188:191], v[238:241], v[64:67]
	v_mfma_f32_16x16x32_bf16 v[116:119], v[184:187], v[218:221], v[116:119]
	v_mfma_f32_16x16x32_bf16 v[112:115], v[210:213], v[218:221], v[112:115]
	v_mfma_f32_16x16x32_bf16 v[100:103], v[184:187], v[226:229], v[100:103]
	v_mfma_f32_16x16x32_bf16 v[96:99], v[210:213], v[226:229], v[96:99]
	v_mfma_f32_16x16x32_bf16 v[84:87], v[184:187], v[234:237], v[84:87]
	v_mfma_f32_16x16x32_bf16 v[80:83], v[210:213], v[234:237], v[80:83]
	v_mfma_f32_16x16x32_bf16 v[68:71], v[184:187], v[242:245], v[68:71]
	v_mfma_f32_16x16x32_bf16 v[64:67], v[210:213], v[242:245], v[64:67]
	s_barrier
	s_setprio 0
	s_mov_b32 m0, s35
	s_add_u32 s0, s4, 0xb0000
	s_addc_u32 s1, s5, 0
	ds_read_b128 v[214:217], v181 offset:16384
	ds_read_b128 v[218:221], v181 offset:17408
	ds_read_b128 v[222:225], v181 offset:18432
	ds_read_b128 v[226:229], v181 offset:19456
	ds_read_b128 v[230:233], v181 offset:20480
	ds_read_b128 v[234:237], v181 offset:21504
	ds_read_b128 v[238:241], v181 offset:22528
	ds_read_b128 v[242:245], v181 offset:23552
	global_load_lds_dwordx4 v166, s[4:5]
	s_mov_b32 m0, s38
	s_nop 0
	global_load_lds_dwordx4 v162, s[4:5]
	s_mov_b32 m0, s39
	s_nop 0
	global_load_lds_dwordx4 v166, s[0:1]
	s_mov_b32 m0, s40
	s_nop 0
	global_load_lds_dwordx4 v162, s[0:1]
	s_mov_b32 m0, s29
	s_nop 0
	global_load_lds_dwordx4 v168, s[6:7]
	s_mov_b32 m0, s41
	s_nop 0
	global_load_lds_dwordx4 v164, s[6:7]
	s_waitcnt vmcnt(8)
	s_waitcnt lgkmcnt(0)
	s_setprio 1
	s_barrier
	v_mfma_f32_16x16x32_bf16 v[60:63], v[128:131], v[214:217], v[60:63]
	v_mfma_f32_16x16x32_bf16 v[56:59], v[136:139], v[214:217], v[56:59]
	v_mfma_f32_16x16x32_bf16 v[44:47], v[128:131], v[222:225], v[44:47]
	v_mfma_f32_16x16x32_bf16 v[40:43], v[136:139], v[222:225], v[40:43]
	v_mfma_f32_16x16x32_bf16 v[28:31], v[128:131], v[230:233], v[28:31]
	v_mfma_f32_16x16x32_bf16 v[24:27], v[136:139], v[230:233], v[24:27]
	v_mfma_f32_16x16x32_bf16 v[12:15], v[128:131], v[238:241], v[12:15]
	v_mfma_f32_16x16x32_bf16 v[8:11], v[136:139], v[238:241], v[8:11]
	v_mfma_f32_16x16x32_bf16 v[60:63], v[132:135], v[218:221], v[60:63]
	v_mfma_f32_16x16x32_bf16 v[56:59], v[140:143], v[218:221], v[56:59]
	v_mfma_f32_16x16x32_bf16 v[44:47], v[132:135], v[226:229], v[44:47]
	v_mfma_f32_16x16x32_bf16 v[40:43], v[140:143], v[226:229], v[40:43]
	v_mfma_f32_16x16x32_bf16 v[28:31], v[132:135], v[234:237], v[28:31]
	v_mfma_f32_16x16x32_bf16 v[24:27], v[140:143], v[234:237], v[24:27]
	v_mfma_f32_16x16x32_bf16 v[12:15], v[132:135], v[242:245], v[12:15]
	v_mfma_f32_16x16x32_bf16 v[8:11], v[140:143], v[242:245], v[8:11]
	v_mfma_f32_16x16x32_bf16 v[52:55], v[174:177], v[214:217], v[52:55]
	v_mfma_f32_16x16x32_bf16 v[48:51], v[188:191], v[214:217], v[48:51]
	v_mfma_f32_16x16x32_bf16 v[36:39], v[174:177], v[222:225], v[36:39]
	v_mfma_f32_16x16x32_bf16 v[32:35], v[188:191], v[222:225], v[32:35]
	v_mfma_f32_16x16x32_bf16 v[20:23], v[174:177], v[230:233], v[20:23]
	v_mfma_f32_16x16x32_bf16 v[16:19], v[188:191], v[230:233], v[16:19]
	v_mfma_f32_16x16x32_bf16 v[4:7], v[174:177], v[238:241], v[4:7]
	v_mfma_f32_16x16x32_bf16 v[0:3], v[188:191], v[238:241], v[0:3]
	v_mfma_f32_16x16x32_bf16 v[52:55], v[184:187], v[218:221], v[52:55]
	v_mfma_f32_16x16x32_bf16 v[48:51], v[210:213], v[218:221], v[48:51]
	v_mfma_f32_16x16x32_bf16 v[36:39], v[184:187], v[226:229], v[36:39]
	v_mfma_f32_16x16x32_bf16 v[32:35], v[210:213], v[226:229], v[32:35]
	v_mfma_f32_16x16x32_bf16 v[20:23], v[184:187], v[234:237], v[20:23]
	v_mfma_f32_16x16x32_bf16 v[16:19], v[210:213], v[234:237], v[16:19]
	v_mfma_f32_16x16x32_bf16 v[4:7], v[184:187], v[242:245], v[4:7]
	v_mfma_f32_16x16x32_bf16 v[0:3], v[210:213], v[242:245], v[0:3]
	s_barrier
; #define PG8_STAGE(bufoff, gbase, voff) do { _Pragma("unroll") for (int _i = 0; _i < 2; ++_i) \
;         __builtin_amdgcn_global_load_lds((const unsigned*)((const char*)(gbase) + (voff)[_i]), (PG8_LAS unsigned*)(lds + (bufoff) + ldsw + _i * 8192), 16, 0, 0); } while (0)
; #define PG8_LDA(dst, b, h) do { _Pragma("unroll") for (int m = 0; m < 4; ++m) _Pragma("unroll") for (int k = 0; k < 2; ++k) dst[m][k] = *(const PG8_LAS bf16x8*)(lds + PG8_SA(b, h) + aoff + m * 2048 + k * 1024); } while (0)
; #define PG8_LDB(dst, b, h) do { _Pragma("unroll") for (int n = 0; n < 2; ++n) _Pragma("unroll") for (int k = 0; k < 2; ++k) dst[n][k] = *(const PG8_LAS bf16x8*)(lds + PG8_SB(b, h) + boff + n * 2048 + k * 1024); } while (0)
; #define PG8_MMA(ai, bj, At, Bt) do { __builtin_amdgcn_s_setprio(1); _Pragma("unroll") for (int m = 0; m < 4; ++m) _Pragma("unroll") for (int n = 0; n < 2; ++n) _Pragma("unroll") for (int k = 0; k < 2; ++k) \
;         acc[ai][bj][m][n] = __builtin_amdgcn_mfma_f32_16x16x32_bf16(Bt[n][k], At[m][k], acc[ai][bj][m][n], 0, 0, 0); __builtin_amdgcn_s_setprio(0); } while (0)
; #define PG8_WAIT_V(n) asm volatile("s_waitcnt vmcnt(" #n ")" ::: "memory")
; #define PG8_WAIT_L(n) asm volatile("s_waitcnt lgkmcnt(" #n ")" ::: "memory")
; #define PG8_BAR __builtin_amdgcn_s_barrier()
; #define PG8_SCHED __builtin_amdgcn_sched_barrier(0)
; template <class Epi, class Sched, bool ALIGN_EPI = false, bool SP2 = false>
; __device__ __forceinline__ void gemm_phase(PG8_LAS unsigned char* lds, const Gemm g, const Sched& S, const Epi& E) {
;     ...
;             PG8_LDB(B0, 1, 0); PG8_LDB(B1, 1, 1); PG8_SCHED; PG8_LDA(At, 1, 0); PG8_STAGE(PG8_SA(0, 1), a2 + hstep, voffA);
;             PG8_WAIT_V(8); PG8_WAIT_L(0); PG8_BAR; PG8_MMA(0, 0, At, B0); PG8_MMA(0, 1, At, B1); PG8_BAR; PG8_SCHED;
;             PG8_LDA(At, 1, 1); PG8_STAGE(PG8_SB(1, 0), b3, voffB); PG8_STAGE(PG8_SB(1, 1), b3 + hstep, voffB); PG8_STAGE(PG8_SA(1, 0), a3, voffA);
;             PG8_WAIT_V(8); PG8_WAIT_L(0); PG8_BAR; PG8_MMA(1, 0, At, B0); PG8_MMA(1, 1, At, B1); PG8_BAR; PG8_SCHED;
;     ...
;         if constexpr (ALIGN_EPI) { if (wr == 0) PG8_BAR; }
	s_setprio 0
	ds_read_b128 v[128:131], v254 offset:32768
	ds_read_b128 v[132:135], v254 offset:33792
	ds_read_b128 v[136:139], v254 offset:34816
	ds_read_b128 v[140:143], v254 offset:35840
	ds_read_b128 v[174:177], v254 offset:49152
	ds_read_b128 v[184:187], v254 offset:50176
	ds_read_b128 v[188:191], v254 offset:51200
	ds_read_b128 v[210:213], v254 offset:52224
	s_add_u32 s0, s6, 0xb0000
	s_addc_u32 s1, s7, 0
	s_mov_b32 m0, s42
	ds_read_b128 v[214:217], v181 offset:32768
	ds_read_b128 v[218:221], v181 offset:33792
	ds_read_b128 v[222:225], v181 offset:34816
	ds_read_b128 v[226:229], v181 offset:35840
	ds_read_b128 v[230:233], v181 offset:36864
	ds_read_b128 v[234:237], v181 offset:37888
	ds_read_b128 v[238:241], v181 offset:38912
	ds_read_b128 v[242:245], v181 offset:39936
	global_load_lds_dwordx4 v168, s[0:1]
	s_mov_b32 m0, s43
	s_nop 0
	global_load_lds_dwordx4 v164, s[0:1]
	s_waitcnt vmcnt(8)
	s_waitcnt lgkmcnt(0)
	s_setprio 1
	s_barrier
	v_mfma_f32_16x16x32_bf16 v[124:127], v[128:131], v[214:217], v[124:127]
	v_mfma_f32_16x16x32_bf16 v[120:123], v[136:139], v[214:217], v[120:123]
	v_mfma_f32_16x16x32_bf16 v[108:111], v[128:131], v[222:225], v[108:111]
	v_mfma_f32_16x16x32_bf16 v[104:107], v[136:139], v[222:225], v[104:107]
	v_mfma_f32_16x16x32_bf16 v[92:95], v[128:131], v[230:233], v[92:95]
	v_mfma_f32_16x16x32_bf16 v[88:91], v[136:139], v[230:233], v[88:91]
	v_mfma_f32_16x16x32_bf16 v[76:79], v[128:131], v[238:241], v[76:79]
	v_mfma_f32_16x16x32_bf16 v[72:75], v[136:139], v[238:241], v[72:75]
	v_mfma_f32_16x16x32_bf16 v[124:127], v[132:135], v[218:221], v[124:127]
	v_mfma_f32_16x16x32_bf16 v[120:123], v[140:143], v[218:221], v[120:123]
	v_mfma_f32_16x16x32_bf16 v[108:111], v[132:135], v[226:229], v[108:111]
	v_mfma_f32_16x16x32_bf16 v[104:107], v[140:143], v[226:229], v[104:107]
	v_mfma_f32_16x16x32_bf16 v[92:95], v[132:135], v[234:237], v[92:95]
	v_mfma_f32_16x16x32_bf16 v[88:91], v[140:143], v[234:237], v[88:91]
	v_mfma_f32_16x16x32_bf16 v[76:79], v[132:135], v[242:245], v[76:79]
	v_mfma_f32_16x16x32_bf16 v[72:75], v[140:143], v[242:245], v[72:75]
	v_mfma_f32_16x16x32_bf16 v[116:119], v[174:177], v[214:217], v[116:119]
	v_mfma_f32_16x16x32_bf16 v[112:115], v[188:191], v[214:217], v[112:115]
	v_mfma_f32_16x16x32_bf16 v[100:103], v[174:177], v[222:225], v[100:103]
	v_mfma_f32_16x16x32_bf16 v[96:99], v[188:191], v[222:225], v[96:99]
	v_mfma_f32_16x16x32_bf16 v[84:87], v[174:177], v[230:233], v[84:87]
	v_mfma_f32_16x16x32_bf16 v[80:83], v[188:191], v[230:233], v[80:83]
	v_mfma_f32_16x16x32_bf16 v[68:71], v[174:177], v[238:241], v[68:71]
	v_mfma_f32_16x16x32_bf16 v[64:67], v[188:191], v[238:241], v[64:67]
	v_mfma_f32_16x16x32_bf16 v[116:119], v[184:187], v[218:221], v[116:119]
	v_mfma_f32_16x16x32_bf16 v[112:115], v[210:213], v[218:221], v[112:115]
	v_mfma_f32_16x16x32_bf16 v[100:103], v[184:187], v[226:229], v[100:103]
	v_mfma_f32_16x16x32_bf16 v[96:99], v[210:213], v[226:229], v[96:99]
	v_mfma_f32_16x16x32_bf16 v[84:87], v[184:187], v[234:237], v[84:87]
	v_mfma_f32_16x16x32_bf16 v[80:83], v[210:213], v[234:237], v[80:83]
	v_mfma_f32_16x16x32_bf16 v[68:71], v[184:187], v[242:245], v[68:71]
	v_mfma_f32_16x16x32_bf16 v[64:67], v[210:213], v[242:245], v[64:67]
	s_barrier
	s_setprio 0
	s_mov_b32 m0, s47
	s_add_u32 s0, s4, 0xb0080
	s_addc_u32 s1, s5, 0
	ds_read_b128 v[214:217], v181 offset:49152
	ds_read_b128 v[218:221], v181 offset:50176
	ds_read_b128 v[222:225], v181 offset:51200
	ds_read_b128 v[226:229], v181 offset:52224
	ds_read_b128 v[230:233], v181 offset:53248
	ds_read_b128 v[234:237], v181 offset:54272
	ds_read_b128 v[238:241], v181 offset:55296
	ds_read_b128 v[242:245], v181 offset:56320
	s_add_u32 s98, s4, 0x80
	s_addc_u32 s99, s5, 0
	global_load_lds_dwordx4 v166, s[98:99]
	s_mov_b32 m0, s48
	s_nop 0
	global_load_lds_dwordx4 v162, s[98:99]
	s_mov_b32 m0, s51
	s_nop 0
	global_load_lds_dwordx4 v166, s[0:1]
	s_mov_b32 m0, s52
	s_nop 0
	global_load_lds_dwordx4 v162, s[0:1]
	s_mov_b32 m0, s49
	s_nop 0
	s_add_u32 s100, s6, 0x80
	s_addc_u32 s101, s7, 0
	global_load_lds_dwordx4 v168, s[100:101]
	s_mov_b32 m0, s50
	s_nop 0
	global_load_lds_dwordx4 v164, s[100:101]
	s_waitcnt vmcnt(8)
	s_waitcnt lgkmcnt(0)
	s_setprio 1
	s_barrier
	v_mfma_f32_16x16x32_bf16 v[60:63], v[128:131], v[214:217], v[60:63]
	v_mfma_f32_16x16x32_bf16 v[56:59], v[136:139], v[214:217], v[56:59]
	v_mfma_f32_16x16x32_bf16 v[44:47], v[128:131], v[222:225], v[44:47]
	v_mfma_f32_16x16x32_bf16 v[40:43], v[136:139], v[222:225], v[40:43]
	v_mfma_f32_16x16x32_bf16 v[28:31], v[128:131], v[230:233], v[28:31]
	v_mfma_f32_16x16x32_bf16 v[24:27], v[136:139], v[230:233], v[24:27]
	v_mfma_f32_16x16x32_bf16 v[12:15], v[128:131], v[238:241], v[12:15]
	v_mfma_f32_16x16x32_bf16 v[8:11], v[136:139], v[238:241], v[8:11]
	v_mfma_f32_16x16x32_bf16 v[60:63], v[132:135], v[218:221], v[60:63]
	v_mfma_f32_16x16x32_bf16 v[56:59], v[140:143], v[218:221], v[56:59]
	v_mfma_f32_16x16x32_bf16 v[44:47], v[132:135], v[226:229], v[44:47]
	v_mfma_f32_16x16x32_bf16 v[40:43], v[140:143], v[226:229], v[40:43]
	v_mfma_f32_16x16x32_bf16 v[28:31], v[132:135], v[234:237], v[28:31]
	v_mfma_f32_16x16x32_bf16 v[24:27], v[140:143], v[234:237], v[24:27]
	v_mfma_f32_16x16x32_bf16 v[12:15], v[132:135], v[242:245], v[12:15]
	v_mfma_f32_16x16x32_bf16 v[8:11], v[140:143], v[242:245], v[8:11]
	v_mfma_f32_16x16x32_bf16 v[52:55], v[174:177], v[214:217], v[52:55]
	v_mfma_f32_16x16x32_bf16 v[48:51], v[188:191], v[214:217], v[48:51]
	v_mfma_f32_16x16x32_bf16 v[36:39], v[174:177], v[222:225], v[36:39]
	v_mfma_f32_16x16x32_bf16 v[32:35], v[188:191], v[222:225], v[32:35]
	v_mfma_f32_16x16x32_bf16 v[20:23], v[174:177], v[230:233], v[20:23]
	v_mfma_f32_16x16x32_bf16 v[16:19], v[188:191], v[230:233], v[16:19]
	v_mfma_f32_16x16x32_bf16 v[4:7], v[174:177], v[238:241], v[4:7]
	v_mfma_f32_16x16x32_bf16 v[0:3], v[188:191], v[238:241], v[0:3]
	v_mfma_f32_16x16x32_bf16 v[52:55], v[184:187], v[218:221], v[52:55]
	v_mfma_f32_16x16x32_bf16 v[48:51], v[210:213], v[218:221], v[48:51]
	v_mfma_f32_16x16x32_bf16 v[36:39], v[184:187], v[226:229], v[36:39]
	v_mfma_f32_16x16x32_bf16 v[32:35], v[210:213], v[226:229], v[32:35]
	v_mfma_f32_16x16x32_bf16 v[20:23], v[184:187], v[234:237], v[20:23]
	v_mfma_f32_16x16x32_bf16 v[16:19], v[210:213], v[234:237], v[16:19]
	v_mfma_f32_16x16x32_bf16 v[4:7], v[184:187], v[242:245], v[4:7]
	v_mfma_f32_16x16x32_bf16 v[0:3], v[210:213], v[242:245], v[0:3]
	s_barrier
	s_setprio 0
	s_add_i32 s13, s13, 2
	s_add_u32 s10, s10, 0x100
	s_addc_u32 s11, s11, 0
	s_cmp_gt_u32 s13, 41
	s_mov_b64 s[0:1], s[2:3]
	s_cbranch_scc0 .LBB0_545
	s_and_b64 vcc, exec, s[22:23]
	s_cbranch_vccz .LBB0_548
	s_barrier

; #define PG8_STAGE(bufoff, gbase, voff) do { _Pragma("unroll") for (int _i = 0; _i < 2; ++_i) \
;         __builtin_amdgcn_global_load_lds((const unsigned*)((const char*)(gbase) + (voff)[_i]), (PG8_LAS unsigned*)(lds + (bufoff) + ldsw + _i * 8192), 16, 0, 0); } while (0)
; #define PG8_LDA(dst, b, h) do { _Pragma("unroll") for (int m = 0; m < 4; ++m) _Pragma("unroll") for (int k = 0; k < 2; ++k) dst[m][k] = *(const PG8_LAS bf16x8*)(lds + PG8_SA(b, h) + aoff + m * 2048 + k * 1024); } while (0)
; #define PG8_LDB(dst, b, h) do { _Pragma("unroll") for (int n = 0; n < 2; ++n) _Pragma("unroll") for (int k = 0; k < 2; ++k) dst[n][k] = *(const PG8_LAS bf16x8*)(lds + PG8_SB(b, h) + boff + n * 2048 + k * 1024); } while (0)
; #define PG8_MMA(ai, bj, At, Bt) do { __builtin_amdgcn_s_setprio(1); _Pragma("unroll") for (int m = 0; m < 4; ++m) _Pragma("unroll") for (int n = 0; n < 2; ++n) _Pragma("unroll") for (int k = 0; k < 2; ++k) \
;         acc[ai][bj][m][n] = __builtin_amdgcn_mfma_f32_16x16x32_bf16(Bt[n][k], At[m][k], acc[ai][bj][m][n], 0, 0, 0); __builtin_amdgcn_s_setprio(0); } while (0)
; #define PG8_WAIT_V(n) asm volatile("s_waitcnt vmcnt(" #n ")" ::: "memory")
; #define PG8_WAIT_L(n) asm volatile("s_waitcnt lgkmcnt(" #n ")" ::: "memory")
; #define PG8_BAR __builtin_amdgcn_s_barrier()
; #define PG8_SCHED __builtin_amdgcn_sched_barrier(0)
; template <class Epi, class Sched, bool ALIGN_EPI = false, bool SP2 = false>
; __device__ __forceinline__ void gemm_phase(PG8_LAS unsigned char* lds, const Gemm g, const Sched& S, const Epi& E) {
;     ...
;             PG8_LDB(B0, 0, 0); PG8_LDB(B1, 0, 1); PG8_SCHED; PG8_LDA(At, 0, 0); PG8_STAGE(PG8_SA(1, 1), a1 + hstep, voffA);
;             PG8_WAIT_V(8); PG8_WAIT_L(0); PG8_BAR; PG8_MMA(0, 0, At, B0); PG8_MMA(0, 1, At, B1); PG8_BAR; PG8_SCHED;
;             PG8_LDA(At, 0, 1); PG8_STAGE(PG8_SB(0, 0), b2, voffB); PG8_STAGE(PG8_SB(0, 1), b2 + hstep, voffB); PG8_STAGE(PG8_SA(0, 0), a2, voffA);
;             PG8_WAIT_V(8); PG8_WAIT_L(0); PG8_BAR; PG8_MMA(1, 0, At, B0); PG8_MMA(1, 1, At, B1); PG8_BAR; PG8_SCHED;
.Lsgi_peel:
	ds_read_b128 v[140:143], v254
	ds_read_b128 v[162:165], v254 offset:1024
	ds_read_b128 v[166:169], v254 offset:2048
	ds_read_b128 v[170:173], v254 offset:3072
	ds_read_b128 v[180:183], v254 offset:16384
	ds_read_b128 v[184:187], v254 offset:17408
	ds_read_b128 v[188:191], v254 offset:18432
	ds_read_b128 v[210:213], v254 offset:19456
	s_add_u32 s2, s0, 0xfffc0080
	s_addc_u32 s3, s1, -1
	s_cmp_eq_u32 s55, 12
	s_cselect_b32 s5, s13, s3
	s_cselect_b32 s4, s25, s2
	s_cselect_b32 s3, s23, s39
	s_cselect_b32 s2, s33, s38
	s_add_i32 m0, s6, 0xc000
	ds_read_b128 v[214:217], v178
	ds_read_b128 v[218:221], v178 offset:1024
	ds_read_b128 v[222:225], v178 offset:2048
	ds_read_b128 v[226:229], v178 offset:3072
	ds_read_b128 v[230:233], v178 offset:4096
	ds_read_b128 v[234:237], v178 offset:5120
	ds_read_b128 v[238:241], v178 offset:6144
	ds_read_b128 v[242:245], v178 offset:7168
	global_load_lds_dwordx4 v136, s[0:1]
	s_add_i32 m0, s6, 0xe000
	s_nop 0
	global_load_lds_dwordx4 v138, s[0:1]
	s_waitcnt vmcnt(8)
	s_waitcnt lgkmcnt(0)
	s_setprio 1
	s_barrier
	v_mfma_f32_16x16x32_bf16 v[124:127], v[140:143], v[214:217], 0
	v_mfma_f32_16x16x32_bf16 v[120:123], v[166:169], v[214:217], 0
	v_mfma_f32_16x16x32_bf16 v[108:111], v[140:143], v[222:225], 0
	v_mfma_f32_16x16x32_bf16 v[104:107], v[166:169], v[222:225], 0
	v_mfma_f32_16x16x32_bf16 v[92:95], v[140:143], v[230:233], 0
	v_mfma_f32_16x16x32_bf16 v[88:91], v[166:169], v[230:233], 0
	v_mfma_f32_16x16x32_bf16 v[76:79], v[140:143], v[238:241], 0
	v_mfma_f32_16x16x32_bf16 v[72:75], v[166:169], v[238:241], 0
	v_mfma_f32_16x16x32_bf16 v[124:127], v[162:165], v[218:221], v[124:127]
	v_mfma_f32_16x16x32_bf16 v[120:123], v[170:173], v[218:221], v[120:123]
	v_mfma_f32_16x16x32_bf16 v[108:111], v[162:165], v[226:229], v[108:111]
	v_mfma_f32_16x16x32_bf16 v[104:107], v[170:173], v[226:229], v[104:107]
	v_mfma_f32_16x16x32_bf16 v[92:95], v[162:165], v[234:237], v[92:95]
	v_mfma_f32_16x16x32_bf16 v[88:91], v[170:173], v[234:237], v[88:91]
	v_mfma_f32_16x16x32_bf16 v[76:79], v[162:165], v[242:245], v[76:79]
	v_mfma_f32_16x16x32_bf16 v[72:75], v[170:173], v[242:245], v[72:75]
	v_mfma_f32_16x16x32_bf16 v[116:119], v[180:183], v[214:217], 0
	v_mfma_f32_16x16x32_bf16 v[112:115], v[188:191], v[214:217], 0
	v_mfma_f32_16x16x32_bf16 v[100:103], v[180:183], v[222:225], 0
	v_mfma_f32_16x16x32_bf16 v[96:99], v[188:191], v[222:225], 0
	v_mfma_f32_16x16x32_bf16 v[84:87], v[180:183], v[230:233], 0
	v_mfma_f32_16x16x32_bf16 v[80:83], v[188:191], v[230:233], 0
	v_mfma_f32_16x16x32_bf16 v[68:71], v[180:183], v[238:241], 0
	v_mfma_f32_16x16x32_bf16 v[64:67], v[188:191], v[238:241], 0
	v_mfma_f32_16x16x32_bf16 v[116:119], v[184:187], v[218:221], v[116:119]
	v_mfma_f32_16x16x32_bf16 v[112:115], v[210:213], v[218:221], v[112:115]
	v_mfma_f32_16x16x32_bf16 v[100:103], v[184:187], v[226:229], v[100:103]
	v_mfma_f32_16x16x32_bf16 v[96:99], v[210:213], v[226:229], v[96:99]
	v_mfma_f32_16x16x32_bf16 v[84:87], v[184:187], v[234:237], v[84:87]
	v_mfma_f32_16x16x32_bf16 v[80:83], v[210:213], v[234:237], v[80:83]
	v_mfma_f32_16x16x32_bf16 v[68:71], v[184:187], v[242:245], v[68:71]
	v_mfma_f32_16x16x32_bf16 v[64:67], v[210:213], v[242:245], v[64:67]
	s_barrier
	s_setprio 0
	s_mov_b32 m0, s31
	s_add_u32 s56, s2, 0x40000
	s_addc_u32 s57, s3, 0
	ds_read_b128 v[214:217], v178 offset:16384
	ds_read_b128 v[218:221], v178 offset:17408
	ds_read_b128 v[222:225], v178 offset:18432
	ds_read_b128 v[226:229], v178 offset:19456
	ds_read_b128 v[230:233], v178 offset:20480
	ds_read_b128 v[234:237], v178 offset:21504
	ds_read_b128 v[238:241], v178 offset:22528
	ds_read_b128 v[242:245], v178 offset:23552
	global_load_lds_dwordx4 v132, s[2:3]
	s_mov_b32 m0, s34
	s_nop 0
	global_load_lds_dwordx4 v128, s[2:3]
	s_mov_b32 m0, s35
	s_nop 0
	global_load_lds_dwordx4 v132, s[56:57]
	s_mov_b32 m0, s40
	s_nop 0
	global_load_lds_dwordx4 v128, s[56:57]
	s_mov_b32 m0, s6
	s_nop 0
	global_load_lds_dwordx4 v134, s[4:5]
	s_mov_b32 m0, s41
	s_nop 0
	global_load_lds_dwordx4 v130, s[4:5]
	s_waitcnt vmcnt(8)
	s_waitcnt lgkmcnt(0)
	s_setprio 1
	s_barrier
	v_mfma_f32_16x16x32_bf16 v[60:63], v[140:143], v[214:217], 0
	v_mfma_f32_16x16x32_bf16 v[56:59], v[166:169], v[214:217], 0
	v_mfma_f32_16x16x32_bf16 v[44:47], v[140:143], v[222:225], 0
	v_mfma_f32_16x16x32_bf16 v[40:43], v[166:169], v[222:225], 0
	v_mfma_f32_16x16x32_bf16 v[28:31], v[140:143], v[230:233], 0
	v_mfma_f32_16x16x32_bf16 v[24:27], v[166:169], v[230:233], 0
	v_mfma_f32_16x16x32_bf16 v[12:15], v[140:143], v[238:241], 0
	v_mfma_f32_16x16x32_bf16 v[8:11], v[166:169], v[238:241], 0
	v_mfma_f32_16x16x32_bf16 v[60:63], v[162:165], v[218:221], v[60:63]
	v_mfma_f32_16x16x32_bf16 v[56:59], v[170:173], v[218:221], v[56:59]
	v_mfma_f32_16x16x32_bf16 v[44:47], v[162:165], v[226:229], v[44:47]
	v_mfma_f32_16x16x32_bf16 v[40:43], v[170:173], v[226:229], v[40:43]
	v_mfma_f32_16x16x32_bf16 v[28:31], v[162:165], v[234:237], v[28:31]
	v_mfma_f32_16x16x32_bf16 v[24:27], v[170:173], v[234:237], v[24:27]
	v_mfma_f32_16x16x32_bf16 v[12:15], v[162:165], v[242:245], v[12:15]
	v_mfma_f32_16x16x32_bf16 v[8:11], v[170:173], v[242:245], v[8:11]
	v_mfma_f32_16x16x32_bf16 v[52:55], v[180:183], v[214:217], 0
	v_mfma_f32_16x16x32_bf16 v[48:51], v[188:191], v[214:217], 0
	v_mfma_f32_16x16x32_bf16 v[36:39], v[180:183], v[222:225], 0
	v_mfma_f32_16x16x32_bf16 v[32:35], v[188:191], v[222:225], 0
	v_mfma_f32_16x16x32_bf16 v[20:23], v[180:183], v[230:233], 0
	v_mfma_f32_16x16x32_bf16 v[16:19], v[188:191], v[230:233], 0
	v_mfma_f32_16x16x32_bf16 v[4:7], v[180:183], v[238:241], 0
	v_mfma_f32_16x16x32_bf16 v[0:3], v[188:191], v[238:241], 0
	v_mfma_f32_16x16x32_bf16 v[52:55], v[184:187], v[218:221], v[52:55]
	v_mfma_f32_16x16x32_bf16 v[48:51], v[210:213], v[218:221], v[48:51]
	v_mfma_f32_16x16x32_bf16 v[36:39], v[184:187], v[226:229], v[36:39]
	v_mfma_f32_16x16x32_bf16 v[32:35], v[210:213], v[226:229], v[32:35]
	v_mfma_f32_16x16x32_bf16 v[20:23], v[184:187], v[234:237], v[20:23]
	v_mfma_f32_16x16x32_bf16 v[16:19], v[210:213], v[234:237], v[16:19]
	v_mfma_f32_16x16x32_bf16 v[4:7], v[184:187], v[242:245], v[4:7]
	v_mfma_f32_16x16x32_bf16 v[0:3], v[210:213], v[242:245], v[0:3]
	s_barrier
; #define PG8_STAGE(bufoff, gbase, voff) do { _Pragma("unroll") for (int _i = 0; _i < 2; ++_i) \
;         __builtin_amdgcn_global_load_lds((const unsigned*)((const char*)(gbase) + (voff)[_i]), (PG8_LAS unsigned*)(lds + (bufoff) + ldsw + _i * 8192), 16, 0, 0); } while (0)
; #define PG8_LDA(dst, b, h) do { _Pragma("unroll") for (int m = 0; m < 4; ++m) _Pragma("unroll") for (int k = 0; k < 2; ++k) dst[m][k] = *(const PG8_LAS bf16x8*)(lds + PG8_SA(b, h) + aoff + m * 2048 + k * 1024); } while (0)
; #define PG8_LDB(dst, b, h) do { _Pragma("unroll") for (int n = 0; n < 2; ++n) _Pragma("unroll") for (int k = 0; k < 2; ++k) dst[n][k] = *(const PG8_LAS bf16x8*)(lds + PG8_SB(b, h) + boff + n * 2048 + k * 1024); } while (0)
; #define PG8_MMA(ai, bj, At, Bt) do { __builtin_amdgcn_s_setprio(1); _Pragma("unroll") for (int m = 0; m < 4; ++m) _Pragma("unroll") for (int n = 0; n < 2; ++n) _Pragma("unroll") for (int k = 0; k < 2; ++k) \
;         acc[ai][bj][m][n] = __builtin_amdgcn_mfma_f32_16x16x32_bf16(Bt[n][k], At[m][k], acc[ai][bj][m][n], 0, 0, 0); __builtin_amdgcn_s_setprio(0); } while (0)
; #define PG8_WAIT_V(n) asm volatile("s_waitcnt vmcnt(" #n ")" ::: "memory")
; #define PG8_WAIT_L(n) asm volatile("s_waitcnt lgkmcnt(" #n ")" ::: "memory")
; #define PG8_BAR __builtin_amdgcn_s_barrier()
; #define PG8_SCHED __builtin_amdgcn_sched_barrier(0)
; template <class Epi, class Sched, bool ALIGN_EPI = false, bool SP2 = false>
; __device__ __forceinline__ void gemm_phase(PG8_LAS unsigned char* lds, const Gemm g, const Sched& S, const Epi& E) {
;     ...
;             PG8_LDB(B0, 1, 0); PG8_LDB(B1, 1, 1); PG8_SCHED; PG8_LDA(At, 1, 0); PG8_STAGE(PG8_SA(0, 1), a2 + hstep, voffA);
;             PG8_WAIT_V(8); PG8_WAIT_L(0); PG8_BAR; PG8_MMA(0, 0, At, B0); PG8_MMA(0, 1, At, B1); PG8_BAR; PG8_SCHED;
;             PG8_LDA(At, 1, 1); PG8_STAGE(PG8_SB(1, 0), b3, voffB); PG8_STAGE(PG8_SB(1, 1), b3 + hstep, voffB); PG8_STAGE(PG8_SA(1, 0), a3, voffA);
;             PG8_WAIT_V(8); PG8_WAIT_L(0); PG8_BAR; PG8_MMA(1, 0, At, B0); PG8_MMA(1, 1, At, B1); PG8_BAR; PG8_SCHED;
	s_setprio 0
	ds_read_b128 v[140:143], v254 offset:32768
	ds_read_b128 v[162:165], v254 offset:33792
	ds_read_b128 v[166:169], v254 offset:34816
	ds_read_b128 v[170:173], v254 offset:35840
	ds_read_b128 v[180:183], v254 offset:49152
	ds_read_b128 v[184:187], v254 offset:50176
	ds_read_b128 v[188:191], v254 offset:51200
	ds_read_b128 v[210:213], v254 offset:52224
	s_add_u32 s4, s4, 0x40000
	s_addc_u32 s5, s5, 0
	s_mov_b32 m0, s42
	ds_read_b128 v[214:217], v178 offset:32768
	ds_read_b128 v[218:221], v178 offset:33792
	ds_read_b128 v[222:225], v178 offset:34816
	ds_read_b128 v[226:229], v178 offset:35840
	ds_read_b128 v[230:233], v178 offset:36864
	ds_read_b128 v[234:237], v178 offset:37888
	ds_read_b128 v[238:241], v178 offset:38912
	ds_read_b128 v[242:245], v178 offset:39936
	global_load_lds_dwordx4 v134, s[4:5]
	s_mov_b32 m0, s43
	s_nop 0
	global_load_lds_dwordx4 v130, s[4:5]
	s_waitcnt vmcnt(8)
	s_waitcnt lgkmcnt(0)
	s_setprio 1
	s_barrier
	v_mfma_f32_16x16x32_bf16 v[124:127], v[140:143], v[214:217], v[124:127]
	v_mfma_f32_16x16x32_bf16 v[120:123], v[166:169], v[214:217], v[120:123]
	v_mfma_f32_16x16x32_bf16 v[108:111], v[140:143], v[222:225], v[108:111]
	v_mfma_f32_16x16x32_bf16 v[104:107], v[166:169], v[222:225], v[104:107]
	v_mfma_f32_16x16x32_bf16 v[92:95], v[140:143], v[230:233], v[92:95]
	v_mfma_f32_16x16x32_bf16 v[88:91], v[166:169], v[230:233], v[88:91]
	v_mfma_f32_16x16x32_bf16 v[76:79], v[140:143], v[238:241], v[76:79]
	v_mfma_f32_16x16x32_bf16 v[72:75], v[166:169], v[238:241], v[72:75]
	v_mfma_f32_16x16x32_bf16 v[124:127], v[162:165], v[218:221], v[124:127]
	v_mfma_f32_16x16x32_bf16 v[120:123], v[170:173], v[218:221], v[120:123]
	v_mfma_f32_16x16x32_bf16 v[108:111], v[162:165], v[226:229], v[108:111]
	v_mfma_f32_16x16x32_bf16 v[104:107], v[170:173], v[226:229], v[104:107]
	v_mfma_f32_16x16x32_bf16 v[92:95], v[162:165], v[234:237], v[92:95]
	v_mfma_f32_16x16x32_bf16 v[88:91], v[170:173], v[234:237], v[88:91]
	v_mfma_f32_16x16x32_bf16 v[76:79], v[162:165], v[242:245], v[76:79]
	v_mfma_f32_16x16x32_bf16 v[72:75], v[170:173], v[242:245], v[72:75]
	v_mfma_f32_16x16x32_bf16 v[116:119], v[180:183], v[214:217], v[116:119]
	v_mfma_f32_16x16x32_bf16 v[112:115], v[188:191], v[214:217], v[112:115]
	v_mfma_f32_16x16x32_bf16 v[100:103], v[180:183], v[222:225], v[100:103]
	v_mfma_f32_16x16x32_bf16 v[96:99], v[188:191], v[222:225], v[96:99]
	v_mfma_f32_16x16x32_bf16 v[84:87], v[180:183], v[230:233], v[84:87]
	v_mfma_f32_16x16x32_bf16 v[80:83], v[188:191], v[230:233], v[80:83]
	v_mfma_f32_16x16x32_bf16 v[68:71], v[180:183], v[238:241], v[68:71]
	v_mfma_f32_16x16x32_bf16 v[64:67], v[188:191], v[238:241], v[64:67]
	v_mfma_f32_16x16x32_bf16 v[116:119], v[184:187], v[218:221], v[116:119]
	v_mfma_f32_16x16x32_bf16 v[112:115], v[210:213], v[218:221], v[112:115]
	v_mfma_f32_16x16x32_bf16 v[100:103], v[184:187], v[226:229], v[100:103]
	v_mfma_f32_16x16x32_bf16 v[96:99], v[210:213], v[226:229], v[96:99]
	v_mfma_f32_16x16x32_bf16 v[84:87], v[184:187], v[234:237], v[84:87]
	v_mfma_f32_16x16x32_bf16 v[80:83], v[210:213], v[234:237], v[80:83]
	v_mfma_f32_16x16x32_bf16 v[68:71], v[184:187], v[242:245], v[68:71]
	v_mfma_f32_16x16x32_bf16 v[64:67], v[210:213], v[242:245], v[64:67]
	s_barrier
	s_setprio 0
	s_mov_b32 m0, s48
	s_add_u32 s2, s2, 0x40080
	s_addc_u32 s3, s3, 0
	ds_read_b128 v[214:217], v178 offset:49152
	ds_read_b128 v[218:221], v178 offset:50176
	ds_read_b128 v[222:225], v178 offset:51200
	ds_read_b128 v[226:229], v178 offset:52224
	ds_read_b128 v[230:233], v178 offset:53248
	ds_read_b128 v[234:237], v178 offset:54272
	ds_read_b128 v[238:241], v178 offset:55296
	ds_read_b128 v[242:245], v178 offset:56320
	s_add_u32 s98, s2, 0xfffc0000
	s_addc_u32 s99, s3, -1
	global_load_lds_dwordx4 v132, s[98:99]
	s_mov_b32 m0, s49
	s_nop 0
	global_load_lds_dwordx4 v128, s[98:99]
	s_mov_b32 m0, s52
	s_nop 0
	global_load_lds_dwordx4 v132, s[2:3]
	s_mov_b32 m0, s53
	s_nop 0
	global_load_lds_dwordx4 v128, s[2:3]
	s_mov_b32 m0, s50
	s_nop 0
	s_add_u32 s100, s4, 0xfffc0080
	s_addc_u32 s101, s5, -1
	global_load_lds_dwordx4 v134, s[100:101]
	s_mov_b32 m0, s51
	s_nop 0
	global_load_lds_dwordx4 v130, s[100:101]
	s_waitcnt vmcnt(8)
	s_waitcnt lgkmcnt(0)
	s_setprio 1
	s_barrier
	v_mfma_f32_16x16x32_bf16 v[60:63], v[140:143], v[214:217], v[60:63]
	v_mfma_f32_16x16x32_bf16 v[56:59], v[166:169], v[214:217], v[56:59]
	v_mfma_f32_16x16x32_bf16 v[44:47], v[140:143], v[222:225], v[44:47]
	v_mfma_f32_16x16x32_bf16 v[40:43], v[166:169], v[222:225], v[40:43]
	v_mfma_f32_16x16x32_bf16 v[28:31], v[140:143], v[230:233], v[28:31]
	v_mfma_f32_16x16x32_bf16 v[24:27], v[166:169], v[230:233], v[24:27]
	v_mfma_f32_16x16x32_bf16 v[12:15], v[140:143], v[238:241], v[12:15]
	v_mfma_f32_16x16x32_bf16 v[8:11], v[166:169], v[238:241], v[8:11]
	v_mfma_f32_16x16x32_bf16 v[60:63], v[162:165], v[218:221], v[60:63]
	v_mfma_f32_16x16x32_bf16 v[56:59], v[170:173], v[218:221], v[56:59]
	v_mfma_f32_16x16x32_bf16 v[44:47], v[162:165], v[226:229], v[44:47]
	v_mfma_f32_16x16x32_bf16 v[40:43], v[170:173], v[226:229], v[40:43]
	v_mfma_f32_16x16x32_bf16 v[28:31], v[162:165], v[234:237], v[28:31]
	v_mfma_f32_16x16x32_bf16 v[24:27], v[170:173], v[234:237], v[24:27]
	v_mfma_f32_16x16x32_bf16 v[12:15], v[162:165], v[242:245], v[12:15]
	v_mfma_f32_16x16x32_bf16 v[8:11], v[170:173], v[242:245], v[8:11]
	v_mfma_f32_16x16x32_bf16 v[52:55], v[180:183], v[214:217], v[52:55]
	v_mfma_f32_16x16x32_bf16 v[48:51], v[188:191], v[214:217], v[48:51]
	v_mfma_f32_16x16x32_bf16 v[36:39], v[180:183], v[222:225], v[36:39]
	v_mfma_f32_16x16x32_bf16 v[32:35], v[188:191], v[222:225], v[32:35]
	v_mfma_f32_16x16x32_bf16 v[20:23], v[180:183], v[230:233], v[20:23]
	v_mfma_f32_16x16x32_bf16 v[16:19], v[188:191], v[230:233], v[16:19]
	v_mfma_f32_16x16x32_bf16 v[4:7], v[180:183], v[238:241], v[4:7]
	v_mfma_f32_16x16x32_bf16 v[0:3], v[188:191], v[238:241], v[0:3]
	v_mfma_f32_16x16x32_bf16 v[52:55], v[184:187], v[218:221], v[52:55]
	v_mfma_f32_16x16x32_bf16 v[48:51], v[210:213], v[218:221], v[48:51]
	v_mfma_f32_16x16x32_bf16 v[36:39], v[184:187], v[226:229], v[36:39]
	v_mfma_f32_16x16x32_bf16 v[32:35], v[210:213], v[226:229], v[32:35]
	v_mfma_f32_16x16x32_bf16 v[20:23], v[184:187], v[234:237], v[20:23]
	v_mfma_f32_16x16x32_bf16 v[16:19], v[210:213], v[234:237], v[16:19]
	v_mfma_f32_16x16x32_bf16 v[4:7], v[184:187], v[242:245], v[4:7]
	v_mfma_f32_16x16x32_bf16 v[0:3], v[210:213], v[242:245], v[0:3]
	s_barrier
	s_setprio 0
	s_add_i32 s55, s55, 2
	s_add_u32 s0, s0, 0x100
	s_addc_u32 s1, s1, 0
	s_add_u32 s38, s38, 0x100
	s_addc_u32 s39, s39, 0
	s_cmp_gt_u32 s55, 13
; #define PG8_STAGE(bufoff, gbase, voff) do { _Pragma("unroll") for (int _i = 0; _i < 2; ++_i) \
;         __builtin_amdgcn_global_load_lds((const unsigned*)((const char*)(gbase) + (voff)[_i]), (PG8_LAS unsigned*)(lds + (bufoff) + ldsw + _i * 8192), 16, 0, 0); } while (0)
; #define PG8_LDA(dst, b, h) do { _Pragma("unroll") for (int m = 0; m < 4; ++m) _Pragma("unroll") for (int k = 0; k < 2; ++k) dst[m][k] = *(const PG8_LAS bf16x8*)(lds + PG8_SA(b, h) + aoff + m * 2048 + k * 1024); } while (0)
; #define PG8_LDB(dst, b, h) do { _Pragma("unroll") for (int n = 0; n < 2; ++n) _Pragma("unroll") for (int k = 0; k < 2; ++k) dst[n][k] = *(const PG8_LAS bf16x8*)(lds + PG8_SB(b, h) + boff + n * 2048 + k * 1024); } while (0)
; #define PG8_MMA(ai, bj, At, Bt) do { __builtin_amdgcn_s_setprio(1); _Pragma("unroll") for (int m = 0; m < 4; ++m) _Pragma("unroll") for (int n = 0; n < 2; ++n) _Pragma("unroll") for (int k = 0; k < 2; ++k) \
;         acc[ai][bj][m][n] = __builtin_amdgcn_mfma_f32_16x16x32_bf16(Bt[n][k], At[m][k], acc[ai][bj][m][n], 0, 0, 0); __builtin_amdgcn_s_setprio(0); } while (0)
; #define PG8_WAIT_V(n) asm volatile("s_waitcnt vmcnt(" #n ")" ::: "memory")
; #define PG8_WAIT_L(n) asm volatile("s_waitcnt lgkmcnt(" #n ")" ::: "memory")
; #define PG8_BAR __builtin_amdgcn_s_barrier()
; #define PG8_SCHED __builtin_amdgcn_sched_barrier(0)
; template <class Epi, class Sched, bool ALIGN_EPI = false, bool SP2 = false>
; __device__ __forceinline__ void gemm_phase(PG8_LAS unsigned char* lds, const Gemm g, const Sched& S, const Epi& E) {
;     ...
;             PG8_LDB(B0, 0, 0); PG8_LDB(B1, 0, 1); PG8_SCHED; PG8_LDA(At, 0, 0); PG8_STAGE(PG8_SA(1, 1), a1 + hstep, voffA);
;             PG8_WAIT_V(8); PG8_WAIT_L(0); PG8_BAR; PG8_MMA(0, 0, At, B0); PG8_MMA(0, 1, At, B1); PG8_BAR; PG8_SCHED;
;             PG8_LDA(At, 0, 1); PG8_STAGE(PG8_SB(0, 0), b2, voffB); PG8_STAGE(PG8_SB(0, 1), b2 + hstep, voffB); PG8_STAGE(PG8_SA(0, 0), a2, voffA);
;             PG8_WAIT_V(8); PG8_WAIT_L(0); PG8_BAR; PG8_MMA(1, 0, At, B0); PG8_MMA(1, 1, At, B1); PG8_BAR; PG8_SCHED;
.LBB0_749:
	ds_read_b128 v[140:143], v254
	ds_read_b128 v[162:165], v254 offset:1024
	ds_read_b128 v[166:169], v254 offset:2048
	ds_read_b128 v[170:173], v254 offset:3072
	ds_read_b128 v[180:183], v254 offset:16384
	ds_read_b128 v[184:187], v254 offset:17408
	ds_read_b128 v[188:191], v254 offset:18432
	ds_read_b128 v[210:213], v254 offset:19456
	s_add_u32 s2, s0, 0xfffc0080
	s_addc_u32 s3, s1, -1
	s_cmp_eq_u32 s55, 12
	s_cselect_b32 s5, s13, s3
	s_cselect_b32 s4, s25, s2
	s_cselect_b32 s3, s23, s39
	s_cselect_b32 s2, s33, s38
	s_add_i32 m0, s6, 0xc000
	ds_read_b128 v[214:217], v178
	ds_read_b128 v[218:221], v178 offset:1024
	ds_read_b128 v[222:225], v178 offset:2048
	ds_read_b128 v[226:229], v178 offset:3072
	ds_read_b128 v[230:233], v178 offset:4096
	ds_read_b128 v[234:237], v178 offset:5120
	ds_read_b128 v[238:241], v178 offset:6144
	ds_read_b128 v[242:245], v178 offset:7168
	global_load_lds_dwordx4 v136, s[0:1]
	s_add_i32 m0, s6, 0xe000
	s_nop 0
	global_load_lds_dwordx4 v138, s[0:1]
	s_waitcnt vmcnt(8)
	s_waitcnt lgkmcnt(0)
	s_setprio 1
	s_barrier
	v_mfma_f32_16x16x32_bf16 v[124:127], v[140:143], v[214:217], v[124:127]
	v_mfma_f32_16x16x32_bf16 v[120:123], v[166:169], v[214:217], v[120:123]
	v_mfma_f32_16x16x32_bf16 v[108:111], v[140:143], v[222:225], v[108:111]
	v_mfma_f32_16x16x32_bf16 v[104:107], v[166:169], v[222:225], v[104:107]
	v_mfma_f32_16x16x32_bf16 v[92:95], v[140:143], v[230:233], v[92:95]
	v_mfma_f32_16x16x32_bf16 v[88:91], v[166:169], v[230:233], v[88:91]
	v_mfma_f32_16x16x32_bf16 v[76:79], v[140:143], v[238:241], v[76:79]
	v_mfma_f32_16x16x32_bf16 v[72:75], v[166:169], v[238:241], v[72:75]
	v_mfma_f32_16x16x32_bf16 v[124:127], v[162:165], v[218:221], v[124:127]
	v_mfma_f32_16x16x32_bf16 v[120:123], v[170:173], v[218:221], v[120:123]
	v_mfma_f32_16x16x32_bf16 v[108:111], v[162:165], v[226:229], v[108:111]
	v_mfma_f32_16x16x32_bf16 v[104:107], v[170:173], v[226:229], v[104:107]
	v_mfma_f32_16x16x32_bf16 v[92:95], v[162:165], v[234:237], v[92:95]
	v_mfma_f32_16x16x32_bf16 v[88:91], v[170:173], v[234:237], v[88:91]
	v_mfma_f32_16x16x32_bf16 v[76:79], v[162:165], v[242:245], v[76:79]
	v_mfma_f32_16x16x32_bf16 v[72:75], v[170:173], v[242:245], v[72:75]
	v_mfma_f32_16x16x32_bf16 v[116:119], v[180:183], v[214:217], v[116:119]
	v_mfma_f32_16x16x32_bf16 v[112:115], v[188:191], v[214:217], v[112:115]
	v_mfma_f32_16x16x32_bf16 v[100:103], v[180:183], v[222:225], v[100:103]
	v_mfma_f32_16x16x32_bf16 v[96:99], v[188:191], v[222:225], v[96:99]
	v_mfma_f32_16x16x32_bf16 v[84:87], v[180:183], v[230:233], v[84:87]
	v_mfma_f32_16x16x32_bf16 v[80:83], v[188:191], v[230:233], v[80:83]
	v_mfma_f32_16x16x32_bf16 v[68:71], v[180:183], v[238:241], v[68:71]
	v_mfma_f32_16x16x32_bf16 v[64:67], v[188:191], v[238:241], v[64:67]
	v_mfma_f32_16x16x32_bf16 v[116:119], v[184:187], v[218:221], v[116:119]
	v_mfma_f32_16x16x32_bf16 v[112:115], v[210:213], v[218:221], v[112:115]
	v_mfma_f32_16x16x32_bf16 v[100:103], v[184:187], v[226:229], v[100:103]
	v_mfma_f32_16x16x32_bf16 v[96:99], v[210:213], v[226:229], v[96:99]
	v_mfma_f32_16x16x32_bf16 v[84:87], v[184:187], v[234:237], v[84:87]
	v_mfma_f32_16x16x32_bf16 v[80:83], v[210:213], v[234:237], v[80:83]
	v_mfma_f32_16x16x32_bf16 v[68:71], v[184:187], v[242:245], v[68:71]
	v_mfma_f32_16x16x32_bf16 v[64:67], v[210:213], v[242:245], v[64:67]
	s_barrier
	s_setprio 0
	s_mov_b32 m0, s31
	s_add_u32 s56, s2, 0x40000
	s_addc_u32 s57, s3, 0
	ds_read_b128 v[214:217], v178 offset:16384
	ds_read_b128 v[218:221], v178 offset:17408
	ds_read_b128 v[222:225], v178 offset:18432
	ds_read_b128 v[226:229], v178 offset:19456
	ds_read_b128 v[230:233], v178 offset:20480
	ds_read_b128 v[234:237], v178 offset:21504
	ds_read_b128 v[238:241], v178 offset:22528
	ds_read_b128 v[242:245], v178 offset:23552
	global_load_lds_dwordx4 v132, s[2:3]
	s_mov_b32 m0, s34
	s_nop 0
	global_load_lds_dwordx4 v128, s[2:3]
	s_mov_b32 m0, s35
	s_nop 0
	global_load_lds_dwordx4 v132, s[56:57]
	s_mov_b32 m0, s40
	s_nop 0
	global_load_lds_dwordx4 v128, s[56:57]
	s_mov_b32 m0, s6
	s_nop 0
	global_load_lds_dwordx4 v134, s[4:5]
	s_mov_b32 m0, s41
	s_nop 0
	global_load_lds_dwordx4 v130, s[4:5]
	s_waitcnt vmcnt(8)
	s_waitcnt lgkmcnt(0)
	s_setprio 1
	s_barrier
	v_mfma_f32_16x16x32_bf16 v[60:63], v[140:143], v[214:217], v[60:63]
	v_mfma_f32_16x16x32_bf16 v[56:59], v[166:169], v[214:217], v[56:59]
	v_mfma_f32_16x16x32_bf16 v[44:47], v[140:143], v[222:225], v[44:47]
	v_mfma_f32_16x16x32_bf16 v[40:43], v[166:169], v[222:225], v[40:43]
	v_mfma_f32_16x16x32_bf16 v[28:31], v[140:143], v[230:233], v[28:31]
	v_mfma_f32_16x16x32_bf16 v[24:27], v[166:169], v[230:233], v[24:27]
	v_mfma_f32_16x16x32_bf16 v[12:15], v[140:143], v[238:241], v[12:15]
	v_mfma_f32_16x16x32_bf16 v[8:11], v[166:169], v[238:241], v[8:11]
	v_mfma_f32_16x16x32_bf16 v[60:63], v[162:165], v[218:221], v[60:63]
	v_mfma_f32_16x16x32_bf16 v[56:59], v[170:173], v[218:221], v[56:59]
	v_mfma_f32_16x16x32_bf16 v[44:47], v[162:165], v[226:229], v[44:47]
	v_mfma_f32_16x16x32_bf16 v[40:43], v[170:173], v[226:229], v[40:43]
	v_mfma_f32_16x16x32_bf16 v[28:31], v[162:165], v[234:237], v[28:31]
	v_mfma_f32_16x16x32_bf16 v[24:27], v[170:173], v[234:237], v[24:27]
	v_mfma_f32_16x16x32_bf16 v[12:15], v[162:165], v[242:245], v[12:15]
	v_mfma_f32_16x16x32_bf16 v[8:11], v[170:173], v[242:245], v[8:11]
	v_mfma_f32_16x16x32_bf16 v[52:55], v[180:183], v[214:217], v[52:55]
	v_mfma_f32_16x16x32_bf16 v[48:51], v[188:191], v[214:217], v[48:51]
	v_mfma_f32_16x16x32_bf16 v[36:39], v[180:183], v[222:225], v[36:39]
	v_mfma_f32_16x16x32_bf16 v[32:35], v[188:191], v[222:225], v[32:35]
	v_mfma_f32_16x16x32_bf16 v[20:23], v[180:183], v[230:233], v[20:23]
	v_mfma_f32_16x16x32_bf16 v[16:19], v[188:191], v[230:233], v[16:19]
	v_mfma_f32_16x16x32_bf16 v[4:7], v[180:183], v[238:241], v[4:7]
	v_mfma_f32_16x16x32_bf16 v[0:3], v[188:191], v[238:241], v[0:3]
	v_mfma_f32_16x16x32_bf16 v[52:55], v[184:187], v[218:221], v[52:55]
	v_mfma_f32_16x16x32_bf16 v[48:51], v[210:213], v[218:221], v[48:51]
	v_mfma_f32_16x16x32_bf16 v[36:39], v[184:187], v[226:229], v[36:39]
	v_mfma_f32_16x16x32_bf16 v[32:35], v[210:213], v[226:229], v[32:35]
	v_mfma_f32_16x16x32_bf16 v[20:23], v[184:187], v[234:237], v[20:23]
	v_mfma_f32_16x16x32_bf16 v[16:19], v[210:213], v[234:237], v[16:19]
	v_mfma_f32_16x16x32_bf16 v[4:7], v[184:187], v[242:245], v[4:7]
	v_mfma_f32_16x16x32_bf16 v[0:3], v[210:213], v[242:245], v[0:3]
	s_barrier
; #define PG8_STAGE(bufoff, gbase, voff) do { _Pragma("unroll") for (int _i = 0; _i < 2; ++_i) \
;         __builtin_amdgcn_global_load_lds((const unsigned*)((const char*)(gbase) + (voff)[_i]), (PG8_LAS unsigned*)(lds + (bufoff) + ldsw + _i * 8192), 16, 0, 0); } while (0)
; #define PG8_LDA(dst, b, h) do { _Pragma("unroll") for (int m = 0; m < 4; ++m) _Pragma("unroll") for (int k = 0; k < 2; ++k) dst[m][k] = *(const PG8_LAS bf16x8*)(lds + PG8_SA(b, h) + aoff + m * 2048 + k * 1024); } while (0)
; #define PG8_LDB(dst, b, h) do { _Pragma("unroll") for (int n = 0; n < 2; ++n) _Pragma("unroll") for (int k = 0; k < 2; ++k) dst[n][k] = *(const PG8_LAS bf16x8*)(lds + PG8_SB(b, h) + boff + n * 2048 + k * 1024); } while (0)
; #define PG8_MMA(ai, bj, At, Bt) do { __builtin_amdgcn_s_setprio(1); _Pragma("unroll") for (int m = 0; m < 4; ++m) _Pragma("unroll") for (int n = 0; n < 2; ++n) _Pragma("unroll") for (int k = 0; k < 2; ++k) \
;         acc[ai][bj][m][n] = __builtin_amdgcn_mfma_f32_16x16x32_bf16(Bt[n][k], At[m][k], acc[ai][bj][m][n], 0, 0, 0); __builtin_amdgcn_s_setprio(0); } while (0)
; #define PG8_WAIT_V(n) asm volatile("s_waitcnt vmcnt(" #n ")" ::: "memory")
; #define PG8_WAIT_L(n) asm volatile("s_waitcnt lgkmcnt(" #n ")" ::: "memory")
; #define PG8_BAR __builtin_amdgcn_s_barrier()
; #define PG8_SCHED __builtin_amdgcn_sched_barrier(0)
; template <class Epi, class Sched, bool ALIGN_EPI = false, bool SP2 = false>
; __device__ __forceinline__ void gemm_phase(PG8_LAS unsigned char* lds, const Gemm g, const Sched& S, const Epi& E) {
;     ...
;             PG8_LDB(B0, 1, 0); PG8_LDB(B1, 1, 1); PG8_SCHED; PG8_LDA(At, 1, 0); PG8_STAGE(PG8_SA(0, 1), a2 + hstep, voffA);
;             PG8_WAIT_V(8); PG8_WAIT_L(0); PG8_BAR; PG8_MMA(0, 0, At, B0); PG8_MMA(0, 1, At, B1); PG8_BAR; PG8_SCHED;
;             PG8_LDA(At, 1, 1); PG8_STAGE(PG8_SB(1, 0), b3, voffB); PG8_STAGE(PG8_SB(1, 1), b3 + hstep, voffB); PG8_STAGE(PG8_SA(1, 0), a3, voffA);
;             PG8_WAIT_V(8); PG8_WAIT_L(0); PG8_BAR; PG8_MMA(1, 0, At, B0); PG8_MMA(1, 1, At, B1); PG8_BAR; PG8_SCHED;
;     ...
;         if constexpr (ALIGN_EPI) { if (wr == 0) PG8_BAR; }
	s_setprio 0
	ds_read_b128 v[140:143], v254 offset:32768
	ds_read_b128 v[162:165], v254 offset:33792
	ds_read_b128 v[166:169], v254 offset:34816
	ds_read_b128 v[170:173], v254 offset:35840
	ds_read_b128 v[180:183], v254 offset:49152
	ds_read_b128 v[184:187], v254 offset:50176
	ds_read_b128 v[188:191], v254 offset:51200
	ds_read_b128 v[210:213], v254 offset:52224
	s_add_u32 s4, s4, 0x40000
	s_addc_u32 s5, s5, 0
	s_mov_b32 m0, s42
	ds_read_b128 v[214:217], v178 offset:32768
	ds_read_b128 v[218:221], v178 offset:33792
	ds_read_b128 v[222:225], v178 offset:34816
	ds_read_b128 v[226:229], v178 offset:35840
	ds_read_b128 v[230:233], v178 offset:36864
	ds_read_b128 v[234:237], v178 offset:37888
	ds_read_b128 v[238:241], v178 offset:38912
	ds_read_b128 v[242:245], v178 offset:39936
	global_load_lds_dwordx4 v134, s[4:5]
	s_mov_b32 m0, s43
	s_nop 0
	global_load_lds_dwordx4 v130, s[4:5]
	s_waitcnt vmcnt(8)
	s_waitcnt lgkmcnt(0)
	s_setprio 1
	s_barrier
	v_mfma_f32_16x16x32_bf16 v[124:127], v[140:143], v[214:217], v[124:127]
	v_mfma_f32_16x16x32_bf16 v[120:123], v[166:169], v[214:217], v[120:123]
	v_mfma_f32_16x16x32_bf16 v[108:111], v[140:143], v[222:225], v[108:111]
	v_mfma_f32_16x16x32_bf16 v[104:107], v[166:169], v[222:225], v[104:107]
	v_mfma_f32_16x16x32_bf16 v[92:95], v[140:143], v[230:233], v[92:95]
	v_mfma_f32_16x16x32_bf16 v[88:91], v[166:169], v[230:233], v[88:91]
	v_mfma_f32_16x16x32_bf16 v[76:79], v[140:143], v[238:241], v[76:79]
	v_mfma_f32_16x16x32_bf16 v[72:75], v[166:169], v[238:241], v[72:75]
	v_mfma_f32_16x16x32_bf16 v[124:127], v[162:165], v[218:221], v[124:127]
	v_mfma_f32_16x16x32_bf16 v[120:123], v[170:173], v[218:221], v[120:123]
	v_mfma_f32_16x16x32_bf16 v[108:111], v[162:165], v[226:229], v[108:111]
	v_mfma_f32_16x16x32_bf16 v[104:107], v[170:173], v[226:229], v[104:107]
	v_mfma_f32_16x16x32_bf16 v[92:95], v[162:165], v[234:237], v[92:95]
	v_mfma_f32_16x16x32_bf16 v[88:91], v[170:173], v[234:237], v[88:91]
	v_mfma_f32_16x16x32_bf16 v[76:79], v[162:165], v[242:245], v[76:79]
	v_mfma_f32_16x16x32_bf16 v[72:75], v[170:173], v[242:245], v[72:75]
	v_mfma_f32_16x16x32_bf16 v[116:119], v[180:183], v[214:217], v[116:119]
	v_mfma_f32_16x16x32_bf16 v[112:115], v[188:191], v[214:217], v[112:115]
	v_mfma_f32_16x16x32_bf16 v[100:103], v[180:183], v[222:225], v[100:103]
	v_mfma_f32_16x16x32_bf16 v[96:99], v[188:191], v[222:225], v[96:99]
	v_mfma_f32_16x16x32_bf16 v[84:87], v[180:183], v[230:233], v[84:87]
	v_mfma_f32_16x16x32_bf16 v[80:83], v[188:191], v[230:233], v[80:83]
	v_mfma_f32_16x16x32_bf16 v[68:71], v[180:183], v[238:241], v[68:71]
	v_mfma_f32_16x16x32_bf16 v[64:67], v[188:191], v[238:241], v[64:67]
	v_mfma_f32_16x16x32_bf16 v[116:119], v[184:187], v[218:221], v[116:119]
	v_mfma_f32_16x16x32_bf16 v[112:115], v[210:213], v[218:221], v[112:115]
	v_mfma_f32_16x16x32_bf16 v[100:103], v[184:187], v[226:229], v[100:103]
	v_mfma_f32_16x16x32_bf16 v[96:99], v[210:213], v[226:229], v[96:99]
	v_mfma_f32_16x16x32_bf16 v[84:87], v[184:187], v[234:237], v[84:87]
	v_mfma_f32_16x16x32_bf16 v[80:83], v[210:213], v[234:237], v[80:83]
	v_mfma_f32_16x16x32_bf16 v[68:71], v[184:187], v[242:245], v[68:71]
	v_mfma_f32_16x16x32_bf16 v[64:67], v[210:213], v[242:245], v[64:67]
	s_barrier
	s_setprio 0
	s_mov_b32 m0, s48
	s_add_u32 s2, s2, 0x40080
	s_addc_u32 s3, s3, 0
	ds_read_b128 v[214:217], v178 offset:49152
	ds_read_b128 v[218:221], v178 offset:50176
	ds_read_b128 v[222:225], v178 offset:51200
	ds_read_b128 v[226:229], v178 offset:52224
	ds_read_b128 v[230:233], v178 offset:53248
	ds_read_b128 v[234:237], v178 offset:54272
	ds_read_b128 v[238:241], v178 offset:55296
	ds_read_b128 v[242:245], v178 offset:56320
	s_add_u32 s98, s2, 0xfffc0000
	s_addc_u32 s99, s3, -1
	global_load_lds_dwordx4 v132, s[98:99]
	s_mov_b32 m0, s49
	s_nop 0
	global_load_lds_dwordx4 v128, s[98:99]
	s_mov_b32 m0, s52
	s_nop 0
	global_load_lds_dwordx4 v132, s[2:3]
	s_mov_b32 m0, s53
	s_nop 0
	global_load_lds_dwordx4 v128, s[2:3]
	s_mov_b32 m0, s50
	s_nop 0
	s_add_u32 s100, s4, 0xfffc0080
	s_addc_u32 s101, s5, -1
	global_load_lds_dwordx4 v134, s[100:101]
	s_mov_b32 m0, s51
	s_nop 0
	global_load_lds_dwordx4 v130, s[100:101]
	s_waitcnt vmcnt(8)
	s_waitcnt lgkmcnt(0)
	s_setprio 1
	s_barrier
	v_mfma_f32_16x16x32_bf16 v[60:63], v[140:143], v[214:217], v[60:63]
	v_mfma_f32_16x16x32_bf16 v[56:59], v[166:169], v[214:217], v[56:59]
	v_mfma_f32_16x16x32_bf16 v[44:47], v[140:143], v[222:225], v[44:47]
	v_mfma_f32_16x16x32_bf16 v[40:43], v[166:169], v[222:225], v[40:43]
	v_mfma_f32_16x16x32_bf16 v[28:31], v[140:143], v[230:233], v[28:31]
	v_mfma_f32_16x16x32_bf16 v[24:27], v[166:169], v[230:233], v[24:27]
	v_mfma_f32_16x16x32_bf16 v[12:15], v[140:143], v[238:241], v[12:15]
	v_mfma_f32_16x16x32_bf16 v[8:11], v[166:169], v[238:241], v[8:11]
	v_mfma_f32_16x16x32_bf16 v[60:63], v[162:165], v[218:221], v[60:63]
	v_mfma_f32_16x16x32_bf16 v[56:59], v[170:173], v[218:221], v[56:59]
	v_mfma_f32_16x16x32_bf16 v[44:47], v[162:165], v[226:229], v[44:47]
	v_mfma_f32_16x16x32_bf16 v[40:43], v[170:173], v[226:229], v[40:43]
	v_mfma_f32_16x16x32_bf16 v[28:31], v[162:165], v[234:237], v[28:31]
	v_mfma_f32_16x16x32_bf16 v[24:27], v[170:173], v[234:237], v[24:27]
	v_mfma_f32_16x16x32_bf16 v[12:15], v[162:165], v[242:245], v[12:15]
	v_mfma_f32_16x16x32_bf16 v[8:11], v[170:173], v[242:245], v[8:11]
	v_mfma_f32_16x16x32_bf16 v[52:55], v[180:183], v[214:217], v[52:55]
	v_mfma_f32_16x16x32_bf16 v[48:51], v[188:191], v[214:217], v[48:51]
	v_mfma_f32_16x16x32_bf16 v[36:39], v[180:183], v[222:225], v[36:39]
	v_mfma_f32_16x16x32_bf16 v[32:35], v[188:191], v[222:225], v[32:35]
	v_mfma_f32_16x16x32_bf16 v[20:23], v[180:183], v[230:233], v[20:23]
	v_mfma_f32_16x16x32_bf16 v[16:19], v[188:191], v[230:233], v[16:19]
	v_mfma_f32_16x16x32_bf16 v[4:7], v[180:183], v[238:241], v[4:7]
	v_mfma_f32_16x16x32_bf16 v[0:3], v[188:191], v[238:241], v[0:3]
	v_mfma_f32_16x16x32_bf16 v[52:55], v[184:187], v[218:221], v[52:55]
	v_mfma_f32_16x16x32_bf16 v[48:51], v[210:213], v[218:221], v[48:51]
	v_mfma_f32_16x16x32_bf16 v[36:39], v[184:187], v[226:229], v[36:39]
	v_mfma_f32_16x16x32_bf16 v[32:35], v[210:213], v[226:229], v[32:35]
	v_mfma_f32_16x16x32_bf16 v[20:23], v[184:187], v[234:237], v[20:23]
	v_mfma_f32_16x16x32_bf16 v[16:19], v[210:213], v[234:237], v[16:19]
	v_mfma_f32_16x16x32_bf16 v[4:7], v[184:187], v[242:245], v[4:7]
	v_mfma_f32_16x16x32_bf16 v[0:3], v[210:213], v[242:245], v[0:3]
	s_barrier
	s_setprio 0
	s_add_i32 s55, s55, 2
	s_add_u32 s0, s0, 0x100
	s_addc_u32 s1, s1, 0
	s_add_u32 s38, s38, 0x100
	s_addc_u32 s39, s39, 0
	s_cmp_gt_u32 s55, 13
	s_cbranch_scc0 .LBB0_749
	s_and_b64 vcc, exec, s[18:19]
	s_cbranch_vccz .LBB0_752
	s_barrier

; #define PG8_STAGE(bufoff, gbase, voff) do { _Pragma("unroll") for (int _i = 0; _i < 2; ++_i) \
;         __builtin_amdgcn_global_load_lds((const unsigned*)((const char*)(gbase) + (voff)[_i]), (PG8_LAS unsigned*)(lds + (bufoff) + ldsw + _i * 8192), 16, 0, 0); } while (0)
; #define PG8_LDA(dst, b, h) do { _Pragma("unroll") for (int m = 0; m < 4; ++m) _Pragma("unroll") for (int k = 0; k < 2; ++k) dst[m][k] = *(const PG8_LAS bf16x8*)(lds + PG8_SA(b, h) + aoff + m * 2048 + k * 1024); } while (0)
; #define PG8_LDB(dst, b, h) do { _Pragma("unroll") for (int n = 0; n < 2; ++n) _Pragma("unroll") for (int k = 0; k < 2; ++k) dst[n][k] = *(const PG8_LAS bf16x8*)(lds + PG8_SB(b, h) + boff + n * 2048 + k * 1024); } while (0)
; #define PG8_MMA(ai, bj, At, Bt) do { __builtin_amdgcn_s_setprio(1); _Pragma("unroll") for (int m = 0; m < 4; ++m) _Pragma("unroll") for (int n = 0; n < 2; ++n) _Pragma("unroll") for (int k = 0; k < 2; ++k) \
;         acc[ai][bj][m][n] = __builtin_amdgcn_mfma_f32_16x16x32_bf16(Bt[n][k], At[m][k], acc[ai][bj][m][n], 0, 0, 0); __builtin_amdgcn_s_setprio(0); } while (0)
; #define PG8_WAIT_V(n) asm volatile("s_waitcnt vmcnt(" #n ")" ::: "memory")
; #define PG8_WAIT_L(n) asm volatile("s_waitcnt lgkmcnt(" #n ")" ::: "memory")
; #define PG8_BAR __builtin_amdgcn_s_barrier()
; #define PG8_SCHED __builtin_amdgcn_sched_barrier(0)
; template <class Epi, class Sched, bool ALIGN_EPI = false, bool SP2 = false>
; __device__ __forceinline__ void gemm_phase(PG8_LAS unsigned char* lds, const Gemm g, const Sched& S, const Epi& E) {
;     ...
;             PG8_LDB(B0, 0, 0); PG8_LDB(B1, 0, 1); PG8_SCHED; PG8_LDA(At, 0, 0); PG8_STAGE(PG8_SA(1, 1), a1 + hstep, voffA);
;             PG8_WAIT_V(8); PG8_WAIT_L(0); PG8_BAR; PG8_MMA(0, 0, At, B0); PG8_MMA(0, 1, At, B1); PG8_BAR; PG8_SCHED;
;             PG8_LDA(At, 0, 1); PG8_STAGE(PG8_SB(0, 0), b2, voffB); PG8_STAGE(PG8_SB(0, 1), b2 + hstep, voffB); PG8_STAGE(PG8_SA(0, 0), a2, voffA);
;             PG8_WAIT_V(8); PG8_WAIT_L(0); PG8_BAR; PG8_MMA(1, 0, At, B0); PG8_MMA(1, 1, At, B1); PG8_BAR; PG8_SCHED;
.Labi_peel:
	s_waitcnt lgkmcnt(0)
	ds_read_b128 v[140:143], v254
	ds_read_b128 v[162:165], v254 offset:1024
	ds_read_b128 v[166:169], v254 offset:2048
	ds_read_b128 v[176:179], v254 offset:3072
	ds_read_b128 v[180:183], v254 offset:16384
	ds_read_b128 v[184:187], v254 offset:17408
	ds_read_b128 v[188:191], v254 offset:18432
	ds_read_b128 v[210:213], v254 offset:19456
	s_add_u32 s2, s0, 0xfffc0080
	s_addc_u32 s3, s1, -1
	s_cmp_eq_u32 s52, 12
	s_cselect_b32 s5, s17, s3
	s_cselect_b32 s4, s48, s2
	s_cselect_b32 s3, s15, s51
	s_cselect_b32 s2, s49, s50
	s_add_i32 m0, s6, 0xc000
	ds_read_b128 v[214:217], v173
	ds_read_b128 v[218:221], v173 offset:1024
	ds_read_b128 v[222:225], v173 offset:2048
	ds_read_b128 v[226:229], v173 offset:3072
	ds_read_b128 v[230:233], v173 offset:4096
	ds_read_b128 v[234:237], v173 offset:5120
	ds_read_b128 v[238:241], v173 offset:6144
	ds_read_b128 v[242:245], v173 offset:7168
	global_load_lds_dwordx4 v136, s[0:1]
	s_add_i32 m0, s6, 0xe000
	s_nop 0
	global_load_lds_dwordx4 v138, s[0:1]
	s_waitcnt vmcnt(8)
	s_waitcnt lgkmcnt(0)
	s_setprio 1
	s_barrier
	v_mfma_f32_16x16x32_bf16 v[124:127], v[140:143], v[214:217], 0
	v_mfma_f32_16x16x32_bf16 v[120:123], v[166:169], v[214:217], 0
	v_mfma_f32_16x16x32_bf16 v[112:115], v[140:143], v[222:225], 0
	v_mfma_f32_16x16x32_bf16 v[104:107], v[166:169], v[222:225], 0
	v_mfma_f32_16x16x32_bf16 v[96:99], v[140:143], v[230:233], 0
	v_mfma_f32_16x16x32_bf16 v[88:91], v[166:169], v[230:233], 0
	v_mfma_f32_16x16x32_bf16 v[80:83], v[140:143], v[238:241], 0
	v_mfma_f32_16x16x32_bf16 v[72:75], v[166:169], v[238:241], 0
	v_mfma_f32_16x16x32_bf16 v[124:127], v[162:165], v[218:221], v[124:127]
	v_mfma_f32_16x16x32_bf16 v[120:123], v[176:179], v[218:221], v[120:123]
	v_mfma_f32_16x16x32_bf16 v[112:115], v[162:165], v[226:229], v[112:115]
	v_mfma_f32_16x16x32_bf16 v[104:107], v[176:179], v[226:229], v[104:107]
	v_mfma_f32_16x16x32_bf16 v[96:99], v[162:165], v[234:237], v[96:99]
	v_mfma_f32_16x16x32_bf16 v[88:91], v[176:179], v[234:237], v[88:91]
	v_mfma_f32_16x16x32_bf16 v[80:83], v[162:165], v[242:245], v[80:83]
	v_mfma_f32_16x16x32_bf16 v[72:75], v[176:179], v[242:245], v[72:75]
	v_mfma_f32_16x16x32_bf16 v[116:119], v[180:183], v[214:217], 0
	v_mfma_f32_16x16x32_bf16 v[108:111], v[188:191], v[214:217], 0
	v_mfma_f32_16x16x32_bf16 v[100:103], v[180:183], v[222:225], 0
	v_mfma_f32_16x16x32_bf16 v[92:95], v[188:191], v[222:225], 0
	v_mfma_f32_16x16x32_bf16 v[84:87], v[180:183], v[230:233], 0
	v_mfma_f32_16x16x32_bf16 v[76:79], v[188:191], v[230:233], 0
	v_mfma_f32_16x16x32_bf16 v[68:71], v[180:183], v[238:241], 0
	v_mfma_f32_16x16x32_bf16 v[64:67], v[188:191], v[238:241], 0
	v_mfma_f32_16x16x32_bf16 v[116:119], v[184:187], v[218:221], v[116:119]
	v_mfma_f32_16x16x32_bf16 v[108:111], v[210:213], v[218:221], v[108:111]
	v_mfma_f32_16x16x32_bf16 v[100:103], v[184:187], v[226:229], v[100:103]
	v_mfma_f32_16x16x32_bf16 v[92:95], v[210:213], v[226:229], v[92:95]
	v_mfma_f32_16x16x32_bf16 v[84:87], v[184:187], v[234:237], v[84:87]
	v_mfma_f32_16x16x32_bf16 v[76:79], v[210:213], v[234:237], v[76:79]
	v_mfma_f32_16x16x32_bf16 v[68:71], v[184:187], v[242:245], v[68:71]
	v_mfma_f32_16x16x32_bf16 v[64:67], v[210:213], v[242:245], v[64:67]
	s_barrier
	s_setprio 0
	s_mov_b32 m0, s27
	s_add_u32 s54, s2, 0x40000
	s_addc_u32 s55, s3, 0
	ds_read_b128 v[214:217], v173 offset:16384
	ds_read_b128 v[218:221], v173 offset:17408
	ds_read_b128 v[222:225], v173 offset:18432
	ds_read_b128 v[226:229], v173 offset:19456
	ds_read_b128 v[230:233], v173 offset:20480
	ds_read_b128 v[234:237], v173 offset:21504
	ds_read_b128 v[238:241], v173 offset:22528
	ds_read_b128 v[242:245], v173 offset:23552
	global_load_lds_dwordx4 v132, s[2:3]
	s_mov_b32 m0, s28
	s_nop 0
	global_load_lds_dwordx4 v128, s[2:3]
	s_mov_b32 m0, s29
	s_nop 0
	global_load_lds_dwordx4 v132, s[54:55]
	s_mov_b32 m0, s30
	s_nop 0
	global_load_lds_dwordx4 v128, s[54:55]
	s_mov_b32 m0, s6
	s_nop 0
	global_load_lds_dwordx4 v134, s[4:5]
	s_mov_b32 m0, s31
	s_nop 0
	global_load_lds_dwordx4 v130, s[4:5]
	s_waitcnt vmcnt(8)
	s_waitcnt lgkmcnt(0)
	s_setprio 1
	s_barrier
	v_mfma_f32_16x16x32_bf16 v[60:63], v[140:143], v[214:217], 0
	v_mfma_f32_16x16x32_bf16 v[56:59], v[166:169], v[214:217], 0
	v_mfma_f32_16x16x32_bf16 v[48:51], v[140:143], v[222:225], 0
	v_mfma_f32_16x16x32_bf16 v[40:43], v[166:169], v[222:225], 0
	v_mfma_f32_16x16x32_bf16 v[32:35], v[140:143], v[230:233], 0
	v_mfma_f32_16x16x32_bf16 v[24:27], v[166:169], v[230:233], 0
	v_mfma_f32_16x16x32_bf16 v[16:19], v[140:143], v[238:241], 0
	v_mfma_f32_16x16x32_bf16 v[8:11], v[166:169], v[238:241], 0
	v_mfma_f32_16x16x32_bf16 v[60:63], v[162:165], v[218:221], v[60:63]
	v_mfma_f32_16x16x32_bf16 v[56:59], v[176:179], v[218:221], v[56:59]
	v_mfma_f32_16x16x32_bf16 v[48:51], v[162:165], v[226:229], v[48:51]
	v_mfma_f32_16x16x32_bf16 v[40:43], v[176:179], v[226:229], v[40:43]
	v_mfma_f32_16x16x32_bf16 v[32:35], v[162:165], v[234:237], v[32:35]
	v_mfma_f32_16x16x32_bf16 v[24:27], v[176:179], v[234:237], v[24:27]
	v_mfma_f32_16x16x32_bf16 v[16:19], v[162:165], v[242:245], v[16:19]
	v_mfma_f32_16x16x32_bf16 v[8:11], v[176:179], v[242:245], v[8:11]
	v_mfma_f32_16x16x32_bf16 v[52:55], v[180:183], v[214:217], 0
	v_mfma_f32_16x16x32_bf16 v[44:47], v[188:191], v[214:217], 0
	v_mfma_f32_16x16x32_bf16 v[36:39], v[180:183], v[222:225], 0
	v_mfma_f32_16x16x32_bf16 v[28:31], v[188:191], v[222:225], 0
	v_mfma_f32_16x16x32_bf16 v[20:23], v[180:183], v[230:233], 0
	v_mfma_f32_16x16x32_bf16 v[12:15], v[188:191], v[230:233], 0
	v_mfma_f32_16x16x32_bf16 v[4:7], v[180:183], v[238:241], 0
	v_mfma_f32_16x16x32_bf16 v[0:3], v[188:191], v[238:241], 0
	v_mfma_f32_16x16x32_bf16 v[52:55], v[184:187], v[218:221], v[52:55]
	v_mfma_f32_16x16x32_bf16 v[44:47], v[210:213], v[218:221], v[44:47]
	v_mfma_f32_16x16x32_bf16 v[36:39], v[184:187], v[226:229], v[36:39]
	v_mfma_f32_16x16x32_bf16 v[28:31], v[210:213], v[226:229], v[28:31]
	v_mfma_f32_16x16x32_bf16 v[20:23], v[184:187], v[234:237], v[20:23]
	v_mfma_f32_16x16x32_bf16 v[12:15], v[210:213], v[234:237], v[12:15]
	v_mfma_f32_16x16x32_bf16 v[4:7], v[184:187], v[242:245], v[4:7]
	v_mfma_f32_16x16x32_bf16 v[0:3], v[210:213], v[242:245], v[0:3]
	s_barrier
; #define PG8_STAGE(bufoff, gbase, voff) do { _Pragma("unroll") for (int _i = 0; _i < 2; ++_i) \
;         __builtin_amdgcn_global_load_lds((const unsigned*)((const char*)(gbase) + (voff)[_i]), (PG8_LAS unsigned*)(lds + (bufoff) + ldsw + _i * 8192), 16, 0, 0); } while (0)
; #define PG8_LDA(dst, b, h) do { _Pragma("unroll") for (int m = 0; m < 4; ++m) _Pragma("unroll") for (int k = 0; k < 2; ++k) dst[m][k] = *(const PG8_LAS bf16x8*)(lds + PG8_SA(b, h) + aoff + m * 2048 + k * 1024); } while (0)
; #define PG8_LDB(dst, b, h) do { _Pragma("unroll") for (int n = 0; n < 2; ++n) _Pragma("unroll") for (int k = 0; k < 2; ++k) dst[n][k] = *(const PG8_LAS bf16x8*)(lds + PG8_SB(b, h) + boff + n * 2048 + k * 1024); } while (0)
; #define PG8_MMA(ai, bj, At, Bt) do { __builtin_amdgcn_s_setprio(1); _Pragma("unroll") for (int m = 0; m < 4; ++m) _Pragma("unroll") for (int n = 0; n < 2; ++n) _Pragma("unroll") for (int k = 0; k < 2; ++k) \
;         acc[ai][bj][m][n] = __builtin_amdgcn_mfma_f32_16x16x32_bf16(Bt[n][k], At[m][k], acc[ai][bj][m][n], 0, 0, 0); __builtin_amdgcn_s_setprio(0); } while (0)
; #define PG8_WAIT_V(n) asm volatile("s_waitcnt vmcnt(" #n ")" ::: "memory")
; template <class Epi, class Sched, bool ALIGN_EPI = false, bool SP2 = false>
; __device__ __forceinline__ void gemm_phase(PG8_LAS unsigned char* lds, const Gemm g, const Sched& S, const Epi& E) {
;     ...
;             PG8_LDB(B0, 0, 0); PG8_LDB(B1, 0, 1); PG8_SCHED; PG8_LDA(At, 0, 0); PG8_STAGE(PG8_SA(1, 1), a1 + hstep, voffA);
;             PG8_WAIT_V(8); PG8_WAIT_L(0); PG8_BAR; PG8_MMA(0, 0, At, B0); PG8_MMA(0, 1, At, B1); PG8_BAR; PG8_SCHED;
;             PG8_LDA(At, 0, 1); PG8_STAGE(PG8_SB(0, 0), b2, voffB); PG8_STAGE(PG8_SB(0, 1), b2 + hstep, voffB); PG8_STAGE(PG8_SA(0, 0), a2, voffA);
;             PG8_WAIT_V(8); PG8_WAIT_L(0); PG8_BAR; PG8_MMA(1, 0, At, B0); PG8_MMA(1, 1, At, B1); PG8_BAR; PG8_SCHED;
;             PG8_LDB(B0, 1, 0); PG8_LDB(B1, 1, 1); PG8_SCHED; PG8_LDA(At, 1, 0); PG8_STAGE(PG8_SA(0, 1), a2 + hstep, voffA);
;             PG8_WAIT_V(8); PG8_WAIT_L(0); PG8_BAR; PG8_MMA(0, 0, At, B0); PG8_MMA(0, 1, At, B1); PG8_BAR; PG8_SCHED;
;             PG8_LDA(At, 1, 1); PG8_STAGE(PG8_SB(1, 0), b3, voffB); PG8_STAGE(PG8_SB(1, 1), b3 + hstep, voffB); PG8_STAGE(PG8_SA(1, 0), a3, voffA);
;             PG8_WAIT_V(8); PG8_WAIT_L(0); PG8_BAR; PG8_MMA(1, 0, At, B0); PG8_MMA(1, 1, At, B1); PG8_BAR; PG8_SCHED;
	s_setprio 0
	ds_read_b128 v[140:143], v254 offset:32768
	ds_read_b128 v[162:165], v254 offset:33792
	ds_read_b128 v[166:169], v254 offset:34816
	ds_read_b128 v[176:179], v254 offset:35840
	ds_read_b128 v[180:183], v254 offset:49152
	ds_read_b128 v[184:187], v254 offset:50176
	ds_read_b128 v[188:191], v254 offset:51200
	ds_read_b128 v[210:213], v254 offset:52224
	s_add_u32 s4, s4, 0x40000
	s_addc_u32 s5, s5, 0
	s_mov_b32 m0, s33
	ds_read_b128 v[214:217], v173 offset:32768
	ds_read_b128 v[218:221], v173 offset:33792
	ds_read_b128 v[222:225], v173 offset:34816
	ds_read_b128 v[226:229], v173 offset:35840
	ds_read_b128 v[230:233], v173 offset:36864
	ds_read_b128 v[234:237], v173 offset:37888
	ds_read_b128 v[238:241], v173 offset:38912
	ds_read_b128 v[242:245], v173 offset:39936
	global_load_lds_dwordx4 v134, s[4:5]
	s_mov_b32 m0, s34
	s_nop 0
	global_load_lds_dwordx4 v130, s[4:5]
	s_waitcnt vmcnt(8)
	s_waitcnt lgkmcnt(0)
	s_setprio 1
	s_barrier
	v_mfma_f32_16x16x32_bf16 v[124:127], v[140:143], v[214:217], v[124:127]
	v_mfma_f32_16x16x32_bf16 v[120:123], v[166:169], v[214:217], v[120:123]
	v_mfma_f32_16x16x32_bf16 v[112:115], v[140:143], v[222:225], v[112:115]
	v_mfma_f32_16x16x32_bf16 v[104:107], v[166:169], v[222:225], v[104:107]
	v_mfma_f32_16x16x32_bf16 v[96:99], v[140:143], v[230:233], v[96:99]
	v_mfma_f32_16x16x32_bf16 v[88:91], v[166:169], v[230:233], v[88:91]
	v_mfma_f32_16x16x32_bf16 v[80:83], v[140:143], v[238:241], v[80:83]
	v_mfma_f32_16x16x32_bf16 v[72:75], v[166:169], v[238:241], v[72:75]
	v_mfma_f32_16x16x32_bf16 v[124:127], v[162:165], v[218:221], v[124:127]
	v_mfma_f32_16x16x32_bf16 v[120:123], v[176:179], v[218:221], v[120:123]
	v_mfma_f32_16x16x32_bf16 v[112:115], v[162:165], v[226:229], v[112:115]
	v_mfma_f32_16x16x32_bf16 v[104:107], v[176:179], v[226:229], v[104:107]
	v_mfma_f32_16x16x32_bf16 v[96:99], v[162:165], v[234:237], v[96:99]
	v_mfma_f32_16x16x32_bf16 v[88:91], v[176:179], v[234:237], v[88:91]
	v_mfma_f32_16x16x32_bf16 v[80:83], v[162:165], v[242:245], v[80:83]
	v_mfma_f32_16x16x32_bf16 v[72:75], v[176:179], v[242:245], v[72:75]
	v_mfma_f32_16x16x32_bf16 v[116:119], v[180:183], v[214:217], v[116:119]
	v_mfma_f32_16x16x32_bf16 v[108:111], v[188:191], v[214:217], v[108:111]
	v_mfma_f32_16x16x32_bf16 v[100:103], v[180:183], v[222:225], v[100:103]
	v_mfma_f32_16x16x32_bf16 v[92:95], v[188:191], v[222:225], v[92:95]
	v_mfma_f32_16x16x32_bf16 v[84:87], v[180:183], v[230:233], v[84:87]
	v_mfma_f32_16x16x32_bf16 v[76:79], v[188:191], v[230:233], v[76:79]
	v_mfma_f32_16x16x32_bf16 v[68:71], v[180:183], v[238:241], v[68:71]
	v_mfma_f32_16x16x32_bf16 v[64:67], v[188:191], v[238:241], v[64:67]
	v_mfma_f32_16x16x32_bf16 v[116:119], v[184:187], v[218:221], v[116:119]
	v_mfma_f32_16x16x32_bf16 v[108:111], v[210:213], v[218:221], v[108:111]
	v_mfma_f32_16x16x32_bf16 v[100:103], v[184:187], v[226:229], v[100:103]
	v_mfma_f32_16x16x32_bf16 v[92:95], v[210:213], v[226:229], v[92:95]
	v_mfma_f32_16x16x32_bf16 v[84:87], v[184:187], v[234:237], v[84:87]
	v_mfma_f32_16x16x32_bf16 v[76:79], v[210:213], v[234:237], v[76:79]
	v_mfma_f32_16x16x32_bf16 v[68:71], v[184:187], v[242:245], v[68:71]
	v_mfma_f32_16x16x32_bf16 v[64:67], v[210:213], v[242:245], v[64:67]
	s_barrier
	s_setprio 0
	s_mov_b32 m0, s37
	s_add_u32 s2, s2, 0x40080
	s_addc_u32 s3, s3, 0
	ds_read_b128 v[214:217], v173 offset:49152
	ds_read_b128 v[218:221], v173 offset:50176
	ds_read_b128 v[222:225], v173 offset:51200
	ds_read_b128 v[226:229], v173 offset:52224
	ds_read_b128 v[230:233], v173 offset:53248
	ds_read_b128 v[234:237], v173 offset:54272
	ds_read_b128 v[238:241], v173 offset:55296
	ds_read_b128 v[242:245], v173 offset:56320
	s_add_u32 s98, s2, 0xfffc0000
	s_addc_u32 s99, s3, -1
	global_load_lds_dwordx4 v132, s[98:99]
	s_mov_b32 m0, s38
	s_nop 0
	global_load_lds_dwordx4 v128, s[98:99]
	s_mov_b32 m0, s41
	s_nop 0
	global_load_lds_dwordx4 v132, s[2:3]
	s_mov_b32 m0, s42
	s_nop 0
	global_load_lds_dwordx4 v128, s[2:3]
	s_mov_b32 m0, s39
	s_nop 0
	s_add_u32 s100, s4, 0xfffc0080
	s_addc_u32 s101, s5, -1
	global_load_lds_dwordx4 v134, s[100:101]
	s_mov_b32 m0, s40
	s_nop 0
	global_load_lds_dwordx4 v130, s[100:101]
	s_waitcnt vmcnt(8)
	s_waitcnt lgkmcnt(0)
	s_setprio 1
	s_barrier
	v_mfma_f32_16x16x32_bf16 v[60:63], v[140:143], v[214:217], v[60:63]
	v_mfma_f32_16x16x32_bf16 v[56:59], v[166:169], v[214:217], v[56:59]
	v_mfma_f32_16x16x32_bf16 v[48:51], v[140:143], v[222:225], v[48:51]
	v_mfma_f32_16x16x32_bf16 v[40:43], v[166:169], v[222:225], v[40:43]
	v_mfma_f32_16x16x32_bf16 v[32:35], v[140:143], v[230:233], v[32:35]
	v_mfma_f32_16x16x32_bf16 v[24:27], v[166:169], v[230:233], v[24:27]
	v_mfma_f32_16x16x32_bf16 v[16:19], v[140:143], v[238:241], v[16:19]
	v_mfma_f32_16x16x32_bf16 v[8:11], v[166:169], v[238:241], v[8:11]
	v_mfma_f32_16x16x32_bf16 v[60:63], v[162:165], v[218:221], v[60:63]
	v_mfma_f32_16x16x32_bf16 v[56:59], v[176:179], v[218:221], v[56:59]
	v_mfma_f32_16x16x32_bf16 v[48:51], v[162:165], v[226:229], v[48:51]
	v_mfma_f32_16x16x32_bf16 v[40:43], v[176:179], v[226:229], v[40:43]
	v_mfma_f32_16x16x32_bf16 v[32:35], v[162:165], v[234:237], v[32:35]
	v_mfma_f32_16x16x32_bf16 v[24:27], v[176:179], v[234:237], v[24:27]
	v_mfma_f32_16x16x32_bf16 v[16:19], v[162:165], v[242:245], v[16:19]
	v_mfma_f32_16x16x32_bf16 v[8:11], v[176:179], v[242:245], v[8:11]
	v_mfma_f32_16x16x32_bf16 v[52:55], v[180:183], v[214:217], v[52:55]
	v_mfma_f32_16x16x32_bf16 v[44:47], v[188:191], v[214:217], v[44:47]
	v_mfma_f32_16x16x32_bf16 v[36:39], v[180:183], v[222:225], v[36:39]
	v_mfma_f32_16x16x32_bf16 v[28:31], v[188:191], v[222:225], v[28:31]
	v_mfma_f32_16x16x32_bf16 v[20:23], v[180:183], v[230:233], v[20:23]
	v_mfma_f32_16x16x32_bf16 v[12:15], v[188:191], v[230:233], v[12:15]
	v_mfma_f32_16x16x32_bf16 v[4:7], v[180:183], v[238:241], v[4:7]
	v_mfma_f32_16x16x32_bf16 v[0:3], v[188:191], v[238:241], v[0:3]
	v_mfma_f32_16x16x32_bf16 v[52:55], v[184:187], v[218:221], v[52:55]
	v_mfma_f32_16x16x32_bf16 v[44:47], v[210:213], v[218:221], v[44:47]
	v_mfma_f32_16x16x32_bf16 v[36:39], v[184:187], v[226:229], v[36:39]
	v_mfma_f32_16x16x32_bf16 v[28:31], v[210:213], v[226:229], v[28:31]
	v_mfma_f32_16x16x32_bf16 v[20:23], v[184:187], v[234:237], v[20:23]
	v_mfma_f32_16x16x32_bf16 v[12:15], v[210:213], v[234:237], v[12:15]
	v_mfma_f32_16x16x32_bf16 v[4:7], v[184:187], v[242:245], v[4:7]
	v_mfma_f32_16x16x32_bf16 v[0:3], v[210:213], v[242:245], v[0:3]
	s_barrier
	s_setprio 0
	s_add_i32 s52, s52, 2
	s_add_u32 s0, s0, 0x100
	s_addc_u32 s1, s1, 0
	s_add_u32 s50, s50, 0x100
	s_addc_u32 s51, s51, 0
	s_cmp_gt_u32 s52, 13
; #define PG8_STAGE(bufoff, gbase, voff) do { _Pragma("unroll") for (int _i = 0; _i < 2; ++_i) \
;         __builtin_amdgcn_global_load_lds((const unsigned*)((const char*)(gbase) + (voff)[_i]), (PG8_LAS unsigned*)(lds + (bufoff) + ldsw + _i * 8192), 16, 0, 0); } while (0)
; #define PG8_LDA(dst, b, h) do { _Pragma("unroll") for (int m = 0; m < 4; ++m) _Pragma("unroll") for (int k = 0; k < 2; ++k) dst[m][k] = *(const PG8_LAS bf16x8*)(lds + PG8_SA(b, h) + aoff + m * 2048 + k * 1024); } while (0)
; #define PG8_LDB(dst, b, h) do { _Pragma("unroll") for (int n = 0; n < 2; ++n) _Pragma("unroll") for (int k = 0; k < 2; ++k) dst[n][k] = *(const PG8_LAS bf16x8*)(lds + PG8_SB(b, h) + boff + n * 2048 + k * 1024); } while (0)
; #define PG8_BAR __builtin_amdgcn_s_barrier()
; template <class Epi, class Sched, bool ALIGN_EPI = false, bool SP2 = false>
; __device__ __forceinline__ void gemm_phase(PG8_LAS unsigned char* lds, const Gemm g, const Sched& S, const Epi& E) {
;     ...
;             const bool last = (t == nt - 2);
;             const char* a1 = cA + (size_t)(t + 1) * kstep;
;             const char* a2 = last ? nA : cA + (size_t)(t + 2) * kstep; const char* b2 = last ? nB : cB + (size_t)(t + 2) * kstep;
;             const char* a3 = a2 + kstep; const char* b3 = b2 + kstep;
;             if (last && has_next) S.a_ready(nxt);
;             if constexpr (SP2) {
;             PG8_LDB(B0, 0, 0); PG8_LDB(B1, 0, 1); PG8_SCHED; PG8_LDA(At, 0, 0); PG8_STAGE(PG8_SA(1, 1), a1 + hstep, voffA);
;             PG8_WAIT_V(8); PG8_WAIT_L(0); PG8_BAR; PG8_MMA(0, 0, At, B0); PG8_MMA(0, 1, At, B1); PG8_BAR; PG8_SCHED;
;             PG8_LDA(At, 0, 1); PG8_STAGE(PG8_SB(0, 0), b2, voffB); PG8_STAGE(PG8_SB(0, 1), b2 + hstep, voffB); PG8_STAGE(PG8_SA(0, 0), a2, voffA);
;             PG8_WAIT_V(8); PG8_WAIT_L(0); PG8_BAR; PG8_MMA(1, 0, At, B0); PG8_MMA(1, 1, At, B1); PG8_BAR; PG8_SCHED;
;             PG8_LDB(B0, 1, 0); PG8_LDB(B1, 1, 1); PG8_SCHED; PG8_LDA(At, 1, 0); PG8_STAGE(PG8_SA(0, 1), a2 + hstep, voffA);
;             PG8_WAIT_V(8); PG8_WAIT_L(0); PG8_BAR; PG8_MMA(0, 0, At, B0); PG8_MMA(0, 1, At, B1); PG8_BAR; PG8_SCHED;
;             PG8_LDA(At, 1, 1); PG8_STAGE(PG8_SB(1, 0), b3, voffB); PG8_STAGE(PG8_SB(1, 1), b3 + hstep, voffB); PG8_STAGE(PG8_SA(1, 0), a3, voffA);
;             PG8_WAIT_V(8); PG8_WAIT_L(0); PG8_BAR; PG8_MMA(1, 0, At, B0); PG8_MMA(1, 1, At, B1); PG8_BAR; PG8_SCHED;
.LBB0_792:
	s_waitcnt lgkmcnt(0)
	ds_read_b128 v[140:143], v254
	ds_read_b128 v[162:165], v254 offset:1024
	ds_read_b128 v[166:169], v254 offset:2048
	ds_read_b128 v[176:179], v254 offset:3072
	ds_read_b128 v[180:183], v254 offset:16384
	ds_read_b128 v[184:187], v254 offset:17408
	ds_read_b128 v[188:191], v254 offset:18432
	ds_read_b128 v[210:213], v254 offset:19456
	s_add_u32 s2, s0, 0xfffc0080
	s_addc_u32 s3, s1, -1
	s_cmp_eq_u32 s52, 12
	s_cselect_b32 s5, s17, s3
	s_cselect_b32 s4, s48, s2
	s_cselect_b32 s3, s15, s51
	s_cselect_b32 s2, s49, s50
	s_add_i32 m0, s6, 0xc000
	ds_read_b128 v[214:217], v173
	ds_read_b128 v[218:221], v173 offset:1024
	ds_read_b128 v[222:225], v173 offset:2048
	ds_read_b128 v[226:229], v173 offset:3072
	ds_read_b128 v[230:233], v173 offset:4096
	ds_read_b128 v[234:237], v173 offset:5120
	ds_read_b128 v[238:241], v173 offset:6144
	ds_read_b128 v[242:245], v173 offset:7168
	global_load_lds_dwordx4 v136, s[0:1]
	s_add_i32 m0, s6, 0xe000
	s_nop 0
	global_load_lds_dwordx4 v138, s[0:1]
	s_waitcnt vmcnt(8)
	s_waitcnt lgkmcnt(0)
	s_setprio 1
	s_barrier
	v_mfma_f32_16x16x32_bf16 v[124:127], v[140:143], v[214:217], v[124:127]
	v_mfma_f32_16x16x32_bf16 v[120:123], v[166:169], v[214:217], v[120:123]
	v_mfma_f32_16x16x32_bf16 v[112:115], v[140:143], v[222:225], v[112:115]
	v_mfma_f32_16x16x32_bf16 v[104:107], v[166:169], v[222:225], v[104:107]
	v_mfma_f32_16x16x32_bf16 v[96:99], v[140:143], v[230:233], v[96:99]
	v_mfma_f32_16x16x32_bf16 v[88:91], v[166:169], v[230:233], v[88:91]
	v_mfma_f32_16x16x32_bf16 v[80:83], v[140:143], v[238:241], v[80:83]
	v_mfma_f32_16x16x32_bf16 v[72:75], v[166:169], v[238:241], v[72:75]
	v_mfma_f32_16x16x32_bf16 v[124:127], v[162:165], v[218:221], v[124:127]
	v_mfma_f32_16x16x32_bf16 v[120:123], v[176:179], v[218:221], v[120:123]
	v_mfma_f32_16x16x32_bf16 v[112:115], v[162:165], v[226:229], v[112:115]
	v_mfma_f32_16x16x32_bf16 v[104:107], v[176:179], v[226:229], v[104:107]
	v_mfma_f32_16x16x32_bf16 v[96:99], v[162:165], v[234:237], v[96:99]
	v_mfma_f32_16x16x32_bf16 v[88:91], v[176:179], v[234:237], v[88:91]
	v_mfma_f32_16x16x32_bf16 v[80:83], v[162:165], v[242:245], v[80:83]
	v_mfma_f32_16x16x32_bf16 v[72:75], v[176:179], v[242:245], v[72:75]
	v_mfma_f32_16x16x32_bf16 v[116:119], v[180:183], v[214:217], v[116:119]
	v_mfma_f32_16x16x32_bf16 v[108:111], v[188:191], v[214:217], v[108:111]
	v_mfma_f32_16x16x32_bf16 v[100:103], v[180:183], v[222:225], v[100:103]
	v_mfma_f32_16x16x32_bf16 v[92:95], v[188:191], v[222:225], v[92:95]
	v_mfma_f32_16x16x32_bf16 v[84:87], v[180:183], v[230:233], v[84:87]
	v_mfma_f32_16x16x32_bf16 v[76:79], v[188:191], v[230:233], v[76:79]
	v_mfma_f32_16x16x32_bf16 v[68:71], v[180:183], v[238:241], v[68:71]
	v_mfma_f32_16x16x32_bf16 v[64:67], v[188:191], v[238:241], v[64:67]
	v_mfma_f32_16x16x32_bf16 v[116:119], v[184:187], v[218:221], v[116:119]
	v_mfma_f32_16x16x32_bf16 v[108:111], v[210:213], v[218:221], v[108:111]
	v_mfma_f32_16x16x32_bf16 v[100:103], v[184:187], v[226:229], v[100:103]
	v_mfma_f32_16x16x32_bf16 v[92:95], v[210:213], v[226:229], v[92:95]
	v_mfma_f32_16x16x32_bf16 v[84:87], v[184:187], v[234:237], v[84:87]
	v_mfma_f32_16x16x32_bf16 v[76:79], v[210:213], v[234:237], v[76:79]
	v_mfma_f32_16x16x32_bf16 v[68:71], v[184:187], v[242:245], v[68:71]
	v_mfma_f32_16x16x32_bf16 v[64:67], v[210:213], v[242:245], v[64:67]
	s_barrier
	s_setprio 0
	s_mov_b32 m0, s27
	s_add_u32 s54, s2, 0x40000
	s_addc_u32 s55, s3, 0
	ds_read_b128 v[214:217], v173 offset:16384
	ds_read_b128 v[218:221], v173 offset:17408
	ds_read_b128 v[222:225], v173 offset:18432
	ds_read_b128 v[226:229], v173 offset:19456
	ds_read_b128 v[230:233], v173 offset:20480
	ds_read_b128 v[234:237], v173 offset:21504
	ds_read_b128 v[238:241], v173 offset:22528
	ds_read_b128 v[242:245], v173 offset:23552
	global_load_lds_dwordx4 v132, s[2:3]
	s_mov_b32 m0, s28
	s_nop 0
	global_load_lds_dwordx4 v128, s[2:3]
	s_mov_b32 m0, s29
	s_nop 0
	global_load_lds_dwordx4 v132, s[54:55]
	s_mov_b32 m0, s30
	s_nop 0
	global_load_lds_dwordx4 v128, s[54:55]
	s_mov_b32 m0, s6
	s_nop 0
	global_load_lds_dwordx4 v134, s[4:5]
	s_mov_b32 m0, s31
	s_nop 0
	global_load_lds_dwordx4 v130, s[4:5]
	s_waitcnt vmcnt(8)
	s_waitcnt lgkmcnt(0)
	s_setprio 1
	s_barrier
	v_mfma_f32_16x16x32_bf16 v[60:63], v[140:143], v[214:217], v[60:63]
	v_mfma_f32_16x16x32_bf16 v[56:59], v[166:169], v[214:217], v[56:59]
	v_mfma_f32_16x16x32_bf16 v[48:51], v[140:143], v[222:225], v[48:51]
	v_mfma_f32_16x16x32_bf16 v[40:43], v[166:169], v[222:225], v[40:43]
	v_mfma_f32_16x16x32_bf16 v[32:35], v[140:143], v[230:233], v[32:35]
	v_mfma_f32_16x16x32_bf16 v[24:27], v[166:169], v[230:233], v[24:27]
	v_mfma_f32_16x16x32_bf16 v[16:19], v[140:143], v[238:241], v[16:19]
	v_mfma_f32_16x16x32_bf16 v[8:11], v[166:169], v[238:241], v[8:11]
	v_mfma_f32_16x16x32_bf16 v[60:63], v[162:165], v[218:221], v[60:63]
	v_mfma_f32_16x16x32_bf16 v[56:59], v[176:179], v[218:221], v[56:59]
	v_mfma_f32_16x16x32_bf16 v[48:51], v[162:165], v[226:229], v[48:51]
	v_mfma_f32_16x16x32_bf16 v[40:43], v[176:179], v[226:229], v[40:43]
	v_mfma_f32_16x16x32_bf16 v[32:35], v[162:165], v[234:237], v[32:35]
	v_mfma_f32_16x16x32_bf16 v[24:27], v[176:179], v[234:237], v[24:27]
	v_mfma_f32_16x16x32_bf16 v[16:19], v[162:165], v[242:245], v[16:19]
	v_mfma_f32_16x16x32_bf16 v[8:11], v[176:179], v[242:245], v[8:11]
	v_mfma_f32_16x16x32_bf16 v[52:55], v[180:183], v[214:217], v[52:55]
	v_mfma_f32_16x16x32_bf16 v[44:47], v[188:191], v[214:217], v[44:47]
	v_mfma_f32_16x16x32_bf16 v[36:39], v[180:183], v[222:225], v[36:39]
	v_mfma_f32_16x16x32_bf16 v[28:31], v[188:191], v[222:225], v[28:31]
	v_mfma_f32_16x16x32_bf16 v[20:23], v[180:183], v[230:233], v[20:23]
	v_mfma_f32_16x16x32_bf16 v[12:15], v[188:191], v[230:233], v[12:15]
	v_mfma_f32_16x16x32_bf16 v[4:7], v[180:183], v[238:241], v[4:7]
	v_mfma_f32_16x16x32_bf16 v[0:3], v[188:191], v[238:241], v[0:3]
	v_mfma_f32_16x16x32_bf16 v[52:55], v[184:187], v[218:221], v[52:55]
	v_mfma_f32_16x16x32_bf16 v[44:47], v[210:213], v[218:221], v[44:47]
	v_mfma_f32_16x16x32_bf16 v[36:39], v[184:187], v[226:229], v[36:39]
	v_mfma_f32_16x16x32_bf16 v[28:31], v[210:213], v[226:229], v[28:31]
	v_mfma_f32_16x16x32_bf16 v[20:23], v[184:187], v[234:237], v[20:23]
	v_mfma_f32_16x16x32_bf16 v[12:15], v[210:213], v[234:237], v[12:15]
	v_mfma_f32_16x16x32_bf16 v[4:7], v[184:187], v[242:245], v[4:7]
	v_mfma_f32_16x16x32_bf16 v[0:3], v[210:213], v[242:245], v[0:3]
	s_barrier
; #define PG8_STAGE(bufoff, gbase, voff) do { _Pragma("unroll") for (int _i = 0; _i < 2; ++_i) \
;         __builtin_amdgcn_global_load_lds((const unsigned*)((const char*)(gbase) + (voff)[_i]), (PG8_LAS unsigned*)(lds + (bufoff) + ldsw + _i * 8192), 16, 0, 0); } while (0)
; #define PG8_LDA(dst, b, h) do { _Pragma("unroll") for (int m = 0; m < 4; ++m) _Pragma("unroll") for (int k = 0; k < 2; ++k) dst[m][k] = *(const PG8_LAS bf16x8*)(lds + PG8_SA(b, h) + aoff + m * 2048 + k * 1024); } while (0)
; #define PG8_LDB(dst, b, h) do { _Pragma("unroll") for (int n = 0; n < 2; ++n) _Pragma("unroll") for (int k = 0; k < 2; ++k) dst[n][k] = *(const PG8_LAS bf16x8*)(lds + PG8_SB(b, h) + boff + n * 2048 + k * 1024); } while (0)
; #define PG8_MMA(ai, bj, At, Bt) do { __builtin_amdgcn_s_setprio(1); _Pragma("unroll") for (int m = 0; m < 4; ++m) _Pragma("unroll") for (int n = 0; n < 2; ++n) _Pragma("unroll") for (int k = 0; k < 2; ++k) \
;         acc[ai][bj][m][n] = __builtin_amdgcn_mfma_f32_16x16x32_bf16(Bt[n][k], At[m][k], acc[ai][bj][m][n], 0, 0, 0); __builtin_amdgcn_s_setprio(0); } while (0)
; #define PG8_WAIT_V(n) asm volatile("s_waitcnt vmcnt(" #n ")" ::: "memory")
; #define PG8_WAIT_L(n) asm volatile("s_waitcnt lgkmcnt(" #n ")" ::: "memory")
; #define PG8_BAR __builtin_amdgcn_s_barrier()
; #define PG8_SCHED __builtin_amdgcn_sched_barrier(0)
; template <class Epi, class Sched, bool ALIGN_EPI = false, bool SP2 = false>
; __device__ __forceinline__ void gemm_phase(PG8_LAS unsigned char* lds, const Gemm g, const Sched& S, const Epi& E) {
;     ...
;             PG8_WAIT_V(8); PG8_WAIT_L(0); PG8_BAR; PG8_MMA(1, 0, At, B0); PG8_MMA(1, 1, At, B1); PG8_BAR; PG8_SCHED;
;             PG8_LDB(B0, 1, 0); PG8_LDB(B1, 1, 1); PG8_SCHED; PG8_LDA(At, 1, 0); PG8_STAGE(PG8_SA(0, 1), a2 + hstep, voffA);
;             PG8_WAIT_V(8); PG8_WAIT_L(0); PG8_BAR; PG8_MMA(0, 0, At, B0); PG8_MMA(0, 1, At, B1); PG8_BAR; PG8_SCHED;
;             PG8_LDA(At, 1, 1); PG8_STAGE(PG8_SB(1, 0), b3, voffB); PG8_STAGE(PG8_SB(1, 1), b3 + hstep, voffB); PG8_STAGE(PG8_SA(1, 0), a3, voffA);
;             PG8_WAIT_V(8); PG8_WAIT_L(0); PG8_BAR; PG8_MMA(1, 0, At, B0); PG8_MMA(1, 1, At, B1); PG8_BAR; PG8_SCHED;
;     ...
;         if constexpr (ALIGN_EPI) { if (wr == 0) PG8_BAR; }
	s_setprio 0
	ds_read_b128 v[140:143], v254 offset:32768
	ds_read_b128 v[162:165], v254 offset:33792
	ds_read_b128 v[166:169], v254 offset:34816
	ds_read_b128 v[176:179], v254 offset:35840
	ds_read_b128 v[180:183], v254 offset:49152
	ds_read_b128 v[184:187], v254 offset:50176
	ds_read_b128 v[188:191], v254 offset:51200
	ds_read_b128 v[210:213], v254 offset:52224
	s_add_u32 s4, s4, 0x40000
	s_addc_u32 s5, s5, 0
	s_mov_b32 m0, s33
	ds_read_b128 v[214:217], v173 offset:32768
	ds_read_b128 v[218:221], v173 offset:33792
	ds_read_b128 v[222:225], v173 offset:34816
	ds_read_b128 v[226:229], v173 offset:35840
	ds_read_b128 v[230:233], v173 offset:36864
	ds_read_b128 v[234:237], v173 offset:37888
	ds_read_b128 v[238:241], v173 offset:38912
	ds_read_b128 v[242:245], v173 offset:39936
	global_load_lds_dwordx4 v134, s[4:5]
	s_mov_b32 m0, s34
	s_nop 0
	global_load_lds_dwordx4 v130, s[4:5]
	s_waitcnt vmcnt(8)
	s_waitcnt lgkmcnt(0)
	s_setprio 1
	s_barrier
	v_mfma_f32_16x16x32_bf16 v[124:127], v[140:143], v[214:217], v[124:127]
	v_mfma_f32_16x16x32_bf16 v[120:123], v[166:169], v[214:217], v[120:123]
	v_mfma_f32_16x16x32_bf16 v[112:115], v[140:143], v[222:225], v[112:115]
	v_mfma_f32_16x16x32_bf16 v[104:107], v[166:169], v[222:225], v[104:107]
	v_mfma_f32_16x16x32_bf16 v[96:99], v[140:143], v[230:233], v[96:99]
	v_mfma_f32_16x16x32_bf16 v[88:91], v[166:169], v[230:233], v[88:91]
	v_mfma_f32_16x16x32_bf16 v[80:83], v[140:143], v[238:241], v[80:83]
	v_mfma_f32_16x16x32_bf16 v[72:75], v[166:169], v[238:241], v[72:75]
	v_mfma_f32_16x16x32_bf16 v[124:127], v[162:165], v[218:221], v[124:127]
	v_mfma_f32_16x16x32_bf16 v[120:123], v[176:179], v[218:221], v[120:123]
	v_mfma_f32_16x16x32_bf16 v[112:115], v[162:165], v[226:229], v[112:115]
	v_mfma_f32_16x16x32_bf16 v[104:107], v[176:179], v[226:229], v[104:107]
	v_mfma_f32_16x16x32_bf16 v[96:99], v[162:165], v[234:237], v[96:99]
	v_mfma_f32_16x16x32_bf16 v[88:91], v[176:179], v[234:237], v[88:91]
	v_mfma_f32_16x16x32_bf16 v[80:83], v[162:165], v[242:245], v[80:83]
	v_mfma_f32_16x16x32_bf16 v[72:75], v[176:179], v[242:245], v[72:75]
	v_mfma_f32_16x16x32_bf16 v[116:119], v[180:183], v[214:217], v[116:119]
	v_mfma_f32_16x16x32_bf16 v[108:111], v[188:191], v[214:217], v[108:111]
	v_mfma_f32_16x16x32_bf16 v[100:103], v[180:183], v[222:225], v[100:103]
	v_mfma_f32_16x16x32_bf16 v[92:95], v[188:191], v[222:225], v[92:95]
	v_mfma_f32_16x16x32_bf16 v[84:87], v[180:183], v[230:233], v[84:87]
	v_mfma_f32_16x16x32_bf16 v[76:79], v[188:191], v[230:233], v[76:79]
	v_mfma_f32_16x16x32_bf16 v[68:71], v[180:183], v[238:241], v[68:71]
	v_mfma_f32_16x16x32_bf16 v[64:67], v[188:191], v[238:241], v[64:67]
	v_mfma_f32_16x16x32_bf16 v[116:119], v[184:187], v[218:221], v[116:119]
	v_mfma_f32_16x16x32_bf16 v[108:111], v[210:213], v[218:221], v[108:111]
	v_mfma_f32_16x16x32_bf16 v[100:103], v[184:187], v[226:229], v[100:103]
	v_mfma_f32_16x16x32_bf16 v[92:95], v[210:213], v[226:229], v[92:95]
	v_mfma_f32_16x16x32_bf16 v[84:87], v[184:187], v[234:237], v[84:87]
	v_mfma_f32_16x16x32_bf16 v[76:79], v[210:213], v[234:237], v[76:79]
	v_mfma_f32_16x16x32_bf16 v[68:71], v[184:187], v[242:245], v[68:71]
	v_mfma_f32_16x16x32_bf16 v[64:67], v[210:213], v[242:245], v[64:67]
	s_barrier
	s_setprio 0
	s_mov_b32 m0, s37
	s_add_u32 s2, s2, 0x40080
	s_addc_u32 s3, s3, 0
	ds_read_b128 v[214:217], v173 offset:49152
	ds_read_b128 v[218:221], v173 offset:50176
	ds_read_b128 v[222:225], v173 offset:51200
	ds_read_b128 v[226:229], v173 offset:52224
	ds_read_b128 v[230:233], v173 offset:53248
	ds_read_b128 v[234:237], v173 offset:54272
	ds_read_b128 v[238:241], v173 offset:55296
	ds_read_b128 v[242:245], v173 offset:56320
	s_add_u32 s98, s2, 0xfffc0000
	s_addc_u32 s99, s3, -1
	global_load_lds_dwordx4 v132, s[98:99]
	s_mov_b32 m0, s38
	s_nop 0
	global_load_lds_dwordx4 v128, s[98:99]
	s_mov_b32 m0, s41
	s_nop 0
	global_load_lds_dwordx4 v132, s[2:3]
	s_mov_b32 m0, s42
	s_nop 0
	global_load_lds_dwordx4 v128, s[2:3]
	s_mov_b32 m0, s39
	s_nop 0
	s_add_u32 s100, s4, 0xfffc0080
	s_addc_u32 s101, s5, -1
	global_load_lds_dwordx4 v134, s[100:101]
	s_mov_b32 m0, s40
	s_nop 0
	global_load_lds_dwordx4 v130, s[100:101]
	s_waitcnt vmcnt(8)
	s_waitcnt lgkmcnt(0)
	s_setprio 1
	s_barrier
	v_mfma_f32_16x16x32_bf16 v[60:63], v[140:143], v[214:217], v[60:63]
	v_mfma_f32_16x16x32_bf16 v[56:59], v[166:169], v[214:217], v[56:59]
	v_mfma_f32_16x16x32_bf16 v[48:51], v[140:143], v[222:225], v[48:51]
	v_mfma_f32_16x16x32_bf16 v[40:43], v[166:169], v[222:225], v[40:43]
	v_mfma_f32_16x16x32_bf16 v[32:35], v[140:143], v[230:233], v[32:35]
	v_mfma_f32_16x16x32_bf16 v[24:27], v[166:169], v[230:233], v[24:27]
	v_mfma_f32_16x16x32_bf16 v[16:19], v[140:143], v[238:241], v[16:19]
	v_mfma_f32_16x16x32_bf16 v[8:11], v[166:169], v[238:241], v[8:11]
	v_mfma_f32_16x16x32_bf16 v[60:63], v[162:165], v[218:221], v[60:63]
	v_mfma_f32_16x16x32_bf16 v[56:59], v[176:179], v[218:221], v[56:59]
	v_mfma_f32_16x16x32_bf16 v[48:51], v[162:165], v[226:229], v[48:51]
	v_mfma_f32_16x16x32_bf16 v[40:43], v[176:179], v[226:229], v[40:43]
	v_mfma_f32_16x16x32_bf16 v[32:35], v[162:165], v[234:237], v[32:35]
	v_mfma_f32_16x16x32_bf16 v[24:27], v[176:179], v[234:237], v[24:27]
	v_mfma_f32_16x16x32_bf16 v[16:19], v[162:165], v[242:245], v[16:19]
	v_mfma_f32_16x16x32_bf16 v[8:11], v[176:179], v[242:245], v[8:11]
	v_mfma_f32_16x16x32_bf16 v[52:55], v[180:183], v[214:217], v[52:55]
	v_mfma_f32_16x16x32_bf16 v[44:47], v[188:191], v[214:217], v[44:47]
	v_mfma_f32_16x16x32_bf16 v[36:39], v[180:183], v[222:225], v[36:39]
	v_mfma_f32_16x16x32_bf16 v[28:31], v[188:191], v[222:225], v[28:31]
	v_mfma_f32_16x16x32_bf16 v[20:23], v[180:183], v[230:233], v[20:23]
	v_mfma_f32_16x16x32_bf16 v[12:15], v[188:191], v[230:233], v[12:15]
	v_mfma_f32_16x16x32_bf16 v[4:7], v[180:183], v[238:241], v[4:7]
	v_mfma_f32_16x16x32_bf16 v[0:3], v[188:191], v[238:241], v[0:3]
	v_mfma_f32_16x16x32_bf16 v[52:55], v[184:187], v[218:221], v[52:55]
	v_mfma_f32_16x16x32_bf16 v[44:47], v[210:213], v[218:221], v[44:47]
	v_mfma_f32_16x16x32_bf16 v[36:39], v[184:187], v[226:229], v[36:39]
	v_mfma_f32_16x16x32_bf16 v[28:31], v[210:213], v[226:229], v[28:31]
	v_mfma_f32_16x16x32_bf16 v[20:23], v[184:187], v[234:237], v[20:23]
	v_mfma_f32_16x16x32_bf16 v[12:15], v[210:213], v[234:237], v[12:15]
	v_mfma_f32_16x16x32_bf16 v[4:7], v[184:187], v[242:245], v[4:7]
	v_mfma_f32_16x16x32_bf16 v[0:3], v[210:213], v[242:245], v[0:3]
	s_barrier
	s_setprio 0
	s_add_i32 s52, s52, 2
	s_add_u32 s0, s0, 0x100
	s_addc_u32 s1, s1, 0
	s_add_u32 s50, s50, 0x100
	s_addc_u32 s51, s51, 0
	s_cmp_gt_u32 s52, 13
	s_cbranch_scc0 .LBB0_792
	s_and_b64 vcc, exec, s[12:13]
	s_cbranch_vccz .LBB0_795
	s_barrier

; #define PG8_STAGE(bufoff, gbase, voff) do { _Pragma("unroll") for (int _i = 0; _i < 2; ++_i) \
;         __builtin_amdgcn_global_load_lds((const unsigned*)((const char*)(gbase) + (voff)[_i]), (PG8_LAS unsigned*)(lds + (bufoff) + ldsw + _i * 8192), 16, 0, 0); } while (0)
; #define PG8_LDA(dst, b, h) do { _Pragma("unroll") for (int m = 0; m < 4; ++m) _Pragma("unroll") for (int k = 0; k < 2; ++k) dst[m][k] = *(const PG8_LAS bf16x8*)(lds + PG8_SA(b, h) + aoff + m * 2048 + k * 1024); } while (0)
; #define PG8_LDB(dst, b, h) do { _Pragma("unroll") for (int n = 0; n < 2; ++n) _Pragma("unroll") for (int k = 0; k < 2; ++k) dst[n][k] = *(const PG8_LAS bf16x8*)(lds + PG8_SB(b, h) + boff + n * 2048 + k * 1024); } while (0)
; #define PG8_WAIT_V(n) asm volatile("s_waitcnt vmcnt(" #n ")" ::: "memory")
; #define PG8_WAIT_L(n) asm volatile("s_waitcnt lgkmcnt(" #n ")" ::: "memory")
; template <class Epi, class Sched, bool ALIGN_EPI = false, bool SP2 = false>
; __device__ __forceinline__ void gemm_phase(PG8_LAS unsigned char* lds, const Gemm g, const Sched& S, const Epi& E) {
;     ...
;                 for (int n = 0; n < 2; ++n) acc[a][b][m][n] = (f32x4){0.f, 0.f, 0.f, 0.f};
;     ...
;     for (;;) {
;         const bool has_next = S.next(ui + 1, nxt);
;         const char* nA = has_next ? (const char*)g.A + (size_t)nxt.pm * tstep : cA; const char* nB = has_next ? (const char*)g.Bt + (size_t)nxt.pn * tstep : cB;
;         for (int t = 0; t < nt; t += 2) {
;             const bool last = (t == nt - 2);
;             const char* a1 = cA + (size_t)(t + 1) * kstep;
;             const char* a2 = last ? nA : cA + (size_t)(t + 2) * kstep; const char* b2 = last ? nB : cB + (size_t)(t + 2) * kstep;
;             const char* a3 = a2 + kstep; const char* b3 = b2 + kstep;
;             if (last && has_next) S.a_ready(nxt);
;             if constexpr (SP2) {
;             PG8_LDB(B0, 0, 0); PG8_LDB(B1, 0, 1); PG8_SCHED; PG8_LDA(At, 0, 0); PG8_STAGE(PG8_SA(1, 1), a1 + hstep, voffA);
;             PG8_WAIT_V(8); PG8_WAIT_L(0); PG8_BAR; PG8_MMA(0, 0, At, B0); PG8_MMA(0, 1, At, B1); PG8_BAR; PG8_SCHED;
;             PG8_LDA(At, 0, 1); PG8_STAGE(PG8_SB(0, 0), b2, voffB); PG8_STAGE(PG8_SB(0, 1), b2 + hstep, voffB); PG8_STAGE(PG8_SA(0, 0), a2, voffA);
;             PG8_WAIT_V(8); PG8_WAIT_L(0); PG8_BAR; PG8_MMA(1, 0, At, B0); PG8_MMA(1, 1, At, B1); PG8_BAR; PG8_SCHED;
.Lsgo_peel:
	ds_read_b128 v[140:143], v254
	ds_read_b128 v[166:169], v254 offset:1024
	ds_read_b128 v[170:173], v254 offset:2048
	ds_read_b128 v[174:177], v254 offset:3072
	ds_read_b128 v[178:181], v254 offset:16384
	ds_read_b128 v[182:185], v254 offset:17408
	ds_read_b128 v[186:189], v254 offset:18432
	ds_read_b128 v[210:213], v254 offset:19456
	s_add_u32 s2, s0, 0xfffc0080
	s_addc_u32 s3, s1, -1
	s_cmp_eq_u32 s55, 12
	s_cselect_b32 s5, s23, s3
	s_cselect_b32 s4, s51, s2
	s_cselect_b32 s3, s21, s54
	s_cselect_b32 s2, s52, s53
	s_add_i32 m0, s31, 0xc000
	ds_read_b128 v[214:217], v163
	ds_read_b128 v[218:221], v163 offset:1024
	ds_read_b128 v[222:225], v163 offset:2048
	ds_read_b128 v[226:229], v163 offset:3072
	ds_read_b128 v[230:233], v163 offset:4096
	ds_read_b128 v[234:237], v163 offset:5120
	ds_read_b128 v[238:241], v163 offset:6144
	ds_read_b128 v[242:245], v163 offset:7168
	global_load_lds_dwordx4 v136, s[0:1]
	s_add_i32 m0, s31, 0xe000
	s_nop 0
	global_load_lds_dwordx4 v138, s[0:1]
	s_waitcnt vmcnt(8)
	s_waitcnt lgkmcnt(0)
	s_setprio 1
	s_barrier
	v_mfma_f32_16x16x32_bf16 v[124:127], v[140:143], v[214:217], 0
	v_mfma_f32_16x16x32_bf16 v[120:123], v[170:173], v[214:217], 0
	v_mfma_f32_16x16x32_bf16 v[108:111], v[140:143], v[222:225], 0
	v_mfma_f32_16x16x32_bf16 v[104:107], v[170:173], v[222:225], 0
	v_mfma_f32_16x16x32_bf16 v[92:95], v[140:143], v[230:233], 0
	v_mfma_f32_16x16x32_bf16 v[88:91], v[170:173], v[230:233], 0
	v_mfma_f32_16x16x32_bf16 v[76:79], v[140:143], v[238:241], 0
	v_mfma_f32_16x16x32_bf16 v[72:75], v[170:173], v[238:241], 0
	v_mfma_f32_16x16x32_bf16 v[124:127], v[166:169], v[218:221], v[124:127]
	v_mfma_f32_16x16x32_bf16 v[120:123], v[174:177], v[218:221], v[120:123]
	v_mfma_f32_16x16x32_bf16 v[108:111], v[166:169], v[226:229], v[108:111]
	v_mfma_f32_16x16x32_bf16 v[104:107], v[174:177], v[226:229], v[104:107]
	v_mfma_f32_16x16x32_bf16 v[92:95], v[166:169], v[234:237], v[92:95]
	v_mfma_f32_16x16x32_bf16 v[88:91], v[174:177], v[234:237], v[88:91]
	v_mfma_f32_16x16x32_bf16 v[76:79], v[166:169], v[242:245], v[76:79]
	v_mfma_f32_16x16x32_bf16 v[72:75], v[174:177], v[242:245], v[72:75]
	v_mfma_f32_16x16x32_bf16 v[116:119], v[178:181], v[214:217], 0
	v_mfma_f32_16x16x32_bf16 v[112:115], v[186:189], v[214:217], 0
	v_mfma_f32_16x16x32_bf16 v[100:103], v[178:181], v[222:225], 0
	v_mfma_f32_16x16x32_bf16 v[96:99], v[186:189], v[222:225], 0
	v_mfma_f32_16x16x32_bf16 v[84:87], v[178:181], v[230:233], 0
	v_mfma_f32_16x16x32_bf16 v[80:83], v[186:189], v[230:233], 0
	v_mfma_f32_16x16x32_bf16 v[68:71], v[178:181], v[238:241], 0
	v_mfma_f32_16x16x32_bf16 v[64:67], v[186:189], v[238:241], 0
	v_mfma_f32_16x16x32_bf16 v[116:119], v[182:185], v[218:221], v[116:119]
	v_mfma_f32_16x16x32_bf16 v[112:115], v[210:213], v[218:221], v[112:115]
	v_mfma_f32_16x16x32_bf16 v[100:103], v[182:185], v[226:229], v[100:103]
	v_mfma_f32_16x16x32_bf16 v[96:99], v[210:213], v[226:229], v[96:99]
	v_mfma_f32_16x16x32_bf16 v[84:87], v[182:185], v[234:237], v[84:87]
	v_mfma_f32_16x16x32_bf16 v[80:83], v[210:213], v[234:237], v[80:83]
	v_mfma_f32_16x16x32_bf16 v[68:71], v[182:185], v[242:245], v[68:71]
	v_mfma_f32_16x16x32_bf16 v[64:67], v[210:213], v[242:245], v[64:67]
	s_barrier
	s_setprio 0
	s_mov_b32 m0, s33
	s_add_u32 s56, s2, 0x40000
	s_addc_u32 s57, s3, 0
	ds_read_b128 v[214:217], v163 offset:16384
	ds_read_b128 v[218:221], v163 offset:17408
	ds_read_b128 v[222:225], v163 offset:18432
	ds_read_b128 v[226:229], v163 offset:19456
	ds_read_b128 v[230:233], v163 offset:20480
	ds_read_b128 v[234:237], v163 offset:21504
	ds_read_b128 v[238:241], v163 offset:22528
	ds_read_b128 v[242:245], v163 offset:23552
	global_load_lds_dwordx4 v132, s[2:3]
	s_mov_b32 m0, s34
	s_nop 0
	global_load_lds_dwordx4 v128, s[2:3]
	s_mov_b32 m0, s35
	s_nop 0
	global_load_lds_dwordx4 v132, s[56:57]
	s_mov_b32 m0, s36
	s_nop 0
	global_load_lds_dwordx4 v128, s[56:57]
	s_mov_b32 m0, s31
	s_nop 0
	global_load_lds_dwordx4 v134, s[4:5]
	s_mov_b32 m0, s37
	s_nop 0
	global_load_lds_dwordx4 v130, s[4:5]
	s_waitcnt vmcnt(8)
	s_waitcnt lgkmcnt(0)
	s_setprio 1
	s_barrier
	v_mfma_f32_16x16x32_bf16 v[60:63], v[140:143], v[214:217], 0
	v_mfma_f32_16x16x32_bf16 v[56:59], v[170:173], v[214:217], 0
	v_mfma_f32_16x16x32_bf16 v[44:47], v[140:143], v[222:225], 0
	v_mfma_f32_16x16x32_bf16 v[40:43], v[170:173], v[222:225], 0
	v_mfma_f32_16x16x32_bf16 v[28:31], v[140:143], v[230:233], 0
	v_mfma_f32_16x16x32_bf16 v[24:27], v[170:173], v[230:233], 0
	v_mfma_f32_16x16x32_bf16 v[12:15], v[140:143], v[238:241], 0
	v_mfma_f32_16x16x32_bf16 v[8:11], v[170:173], v[238:241], 0
	v_mfma_f32_16x16x32_bf16 v[60:63], v[166:169], v[218:221], v[60:63]
	v_mfma_f32_16x16x32_bf16 v[56:59], v[174:177], v[218:221], v[56:59]
	v_mfma_f32_16x16x32_bf16 v[44:47], v[166:169], v[226:229], v[44:47]
	v_mfma_f32_16x16x32_bf16 v[40:43], v[174:177], v[226:229], v[40:43]
	v_mfma_f32_16x16x32_bf16 v[28:31], v[166:169], v[234:237], v[28:31]
	v_mfma_f32_16x16x32_bf16 v[24:27], v[174:177], v[234:237], v[24:27]
	v_mfma_f32_16x16x32_bf16 v[12:15], v[166:169], v[242:245], v[12:15]
	v_mfma_f32_16x16x32_bf16 v[8:11], v[174:177], v[242:245], v[8:11]
	v_mfma_f32_16x16x32_bf16 v[52:55], v[178:181], v[214:217], 0
	v_mfma_f32_16x16x32_bf16 v[48:51], v[186:189], v[214:217], 0
	v_mfma_f32_16x16x32_bf16 v[36:39], v[178:181], v[222:225], 0
	v_mfma_f32_16x16x32_bf16 v[32:35], v[186:189], v[222:225], 0
	v_mfma_f32_16x16x32_bf16 v[20:23], v[178:181], v[230:233], 0
	v_mfma_f32_16x16x32_bf16 v[16:19], v[186:189], v[230:233], 0
	v_mfma_f32_16x16x32_bf16 v[4:7], v[178:181], v[238:241], 0
	v_mfma_f32_16x16x32_bf16 v[0:3], v[186:189], v[238:241], 0
	v_mfma_f32_16x16x32_bf16 v[52:55], v[182:185], v[218:221], v[52:55]
	v_mfma_f32_16x16x32_bf16 v[48:51], v[210:213], v[218:221], v[48:51]
	v_mfma_f32_16x16x32_bf16 v[36:39], v[182:185], v[226:229], v[36:39]
	v_mfma_f32_16x16x32_bf16 v[32:35], v[210:213], v[226:229], v[32:35]
	v_mfma_f32_16x16x32_bf16 v[20:23], v[182:185], v[234:237], v[20:23]
	v_mfma_f32_16x16x32_bf16 v[16:19], v[210:213], v[234:237], v[16:19]
	v_mfma_f32_16x16x32_bf16 v[4:7], v[182:185], v[242:245], v[4:7]
	v_mfma_f32_16x16x32_bf16 v[0:3], v[210:213], v[242:245], v[0:3]
	s_barrier
; #define PG8_STAGE(bufoff, gbase, voff) do { _Pragma("unroll") for (int _i = 0; _i < 2; ++_i) \
;         __builtin_amdgcn_global_load_lds((const unsigned*)((const char*)(gbase) + (voff)[_i]), (PG8_LAS unsigned*)(lds + (bufoff) + ldsw + _i * 8192), 16, 0, 0); } while (0)
; #define PG8_LDA(dst, b, h) do { _Pragma("unroll") for (int m = 0; m < 4; ++m) _Pragma("unroll") for (int k = 0; k < 2; ++k) dst[m][k] = *(const PG8_LAS bf16x8*)(lds + PG8_SA(b, h) + aoff + m * 2048 + k * 1024); } while (0)
; #define PG8_LDB(dst, b, h) do { _Pragma("unroll") for (int n = 0; n < 2; ++n) _Pragma("unroll") for (int k = 0; k < 2; ++k) dst[n][k] = *(const PG8_LAS bf16x8*)(lds + PG8_SB(b, h) + boff + n * 2048 + k * 1024); } while (0)
; #define PG8_MMA(ai, bj, At, Bt) do { __builtin_amdgcn_s_setprio(1); _Pragma("unroll") for (int m = 0; m < 4; ++m) _Pragma("unroll") for (int n = 0; n < 2; ++n) _Pragma("unroll") for (int k = 0; k < 2; ++k) \
;         acc[ai][bj][m][n] = __builtin_amdgcn_mfma_f32_16x16x32_bf16(Bt[n][k], At[m][k], acc[ai][bj][m][n], 0, 0, 0); __builtin_amdgcn_s_setprio(0); } while (0)
; #define PG8_WAIT_V(n) asm volatile("s_waitcnt vmcnt(" #n ")" ::: "memory")
; template <class Epi, class Sched, bool ALIGN_EPI = false, bool SP2 = false>
; __device__ __forceinline__ void gemm_phase(PG8_LAS unsigned char* lds, const Gemm g, const Sched& S, const Epi& E) {
;     ...
;             PG8_LDB(B0, 0, 0); PG8_LDB(B1, 0, 1); PG8_SCHED; PG8_LDA(At, 0, 0); PG8_STAGE(PG8_SA(1, 1), a1 + hstep, voffA);
;             PG8_WAIT_V(8); PG8_WAIT_L(0); PG8_BAR; PG8_MMA(0, 0, At, B0); PG8_MMA(0, 1, At, B1); PG8_BAR; PG8_SCHED;
;             PG8_LDA(At, 0, 1); PG8_STAGE(PG8_SB(0, 0), b2, voffB); PG8_STAGE(PG8_SB(0, 1), b2 + hstep, voffB); PG8_STAGE(PG8_SA(0, 0), a2, voffA);
;             PG8_WAIT_V(8); PG8_WAIT_L(0); PG8_BAR; PG8_MMA(1, 0, At, B0); PG8_MMA(1, 1, At, B1); PG8_BAR; PG8_SCHED;
;             PG8_LDB(B0, 1, 0); PG8_LDB(B1, 1, 1); PG8_SCHED; PG8_LDA(At, 1, 0); PG8_STAGE(PG8_SA(0, 1), a2 + hstep, voffA);
;             PG8_WAIT_V(8); PG8_WAIT_L(0); PG8_BAR; PG8_MMA(0, 0, At, B0); PG8_MMA(0, 1, At, B1); PG8_BAR; PG8_SCHED;
;             PG8_LDA(At, 1, 1); PG8_STAGE(PG8_SB(1, 0), b3, voffB); PG8_STAGE(PG8_SB(1, 1), b3 + hstep, voffB); PG8_STAGE(PG8_SA(1, 0), a3, voffA);
;             PG8_WAIT_V(8); PG8_WAIT_L(0); PG8_BAR; PG8_MMA(1, 0, At, B0); PG8_MMA(1, 1, At, B1); PG8_BAR; PG8_SCHED;
	s_setprio 0
	ds_read_b128 v[140:143], v254 offset:32768
	ds_read_b128 v[166:169], v254 offset:33792
	ds_read_b128 v[170:173], v254 offset:34816
	ds_read_b128 v[174:177], v254 offset:35840
	ds_read_b128 v[178:181], v254 offset:49152
	ds_read_b128 v[182:185], v254 offset:50176
	ds_read_b128 v[186:189], v254 offset:51200
	ds_read_b128 v[210:213], v254 offset:52224
	s_add_u32 s4, s4, 0x40000
	s_addc_u32 s5, s5, 0
	s_mov_b32 m0, s38
	ds_read_b128 v[214:217], v163 offset:32768
	ds_read_b128 v[218:221], v163 offset:33792
	ds_read_b128 v[222:225], v163 offset:34816
	ds_read_b128 v[226:229], v163 offset:35840
	ds_read_b128 v[230:233], v163 offset:36864
	ds_read_b128 v[234:237], v163 offset:37888
	ds_read_b128 v[238:241], v163 offset:38912
	ds_read_b128 v[242:245], v163 offset:39936
	global_load_lds_dwordx4 v134, s[4:5]
	s_mov_b32 m0, s39
	s_nop 0
	global_load_lds_dwordx4 v130, s[4:5]
	s_waitcnt vmcnt(8)
	s_waitcnt lgkmcnt(0)
	s_setprio 1
	s_barrier
	v_mfma_f32_16x16x32_bf16 v[124:127], v[140:143], v[214:217], v[124:127]
	v_mfma_f32_16x16x32_bf16 v[120:123], v[170:173], v[214:217], v[120:123]
	v_mfma_f32_16x16x32_bf16 v[108:111], v[140:143], v[222:225], v[108:111]
	v_mfma_f32_16x16x32_bf16 v[104:107], v[170:173], v[222:225], v[104:107]
	v_mfma_f32_16x16x32_bf16 v[92:95], v[140:143], v[230:233], v[92:95]
	v_mfma_f32_16x16x32_bf16 v[88:91], v[170:173], v[230:233], v[88:91]
	v_mfma_f32_16x16x32_bf16 v[76:79], v[140:143], v[238:241], v[76:79]
	v_mfma_f32_16x16x32_bf16 v[72:75], v[170:173], v[238:241], v[72:75]
	v_mfma_f32_16x16x32_bf16 v[124:127], v[166:169], v[218:221], v[124:127]
	v_mfma_f32_16x16x32_bf16 v[120:123], v[174:177], v[218:221], v[120:123]
	v_mfma_f32_16x16x32_bf16 v[108:111], v[166:169], v[226:229], v[108:111]
	v_mfma_f32_16x16x32_bf16 v[104:107], v[174:177], v[226:229], v[104:107]
	v_mfma_f32_16x16x32_bf16 v[92:95], v[166:169], v[234:237], v[92:95]
	v_mfma_f32_16x16x32_bf16 v[88:91], v[174:177], v[234:237], v[88:91]
	v_mfma_f32_16x16x32_bf16 v[76:79], v[166:169], v[242:245], v[76:79]
	v_mfma_f32_16x16x32_bf16 v[72:75], v[174:177], v[242:245], v[72:75]
	v_mfma_f32_16x16x32_bf16 v[116:119], v[178:181], v[214:217], v[116:119]
	v_mfma_f32_16x16x32_bf16 v[112:115], v[186:189], v[214:217], v[112:115]
	v_mfma_f32_16x16x32_bf16 v[100:103], v[178:181], v[222:225], v[100:103]
	v_mfma_f32_16x16x32_bf16 v[96:99], v[186:189], v[222:225], v[96:99]
	v_mfma_f32_16x16x32_bf16 v[84:87], v[178:181], v[230:233], v[84:87]
	v_mfma_f32_16x16x32_bf16 v[80:83], v[186:189], v[230:233], v[80:83]
	v_mfma_f32_16x16x32_bf16 v[68:71], v[178:181], v[238:241], v[68:71]
	v_mfma_f32_16x16x32_bf16 v[64:67], v[186:189], v[238:241], v[64:67]
	v_mfma_f32_16x16x32_bf16 v[116:119], v[182:185], v[218:221], v[116:119]
	v_mfma_f32_16x16x32_bf16 v[112:115], v[210:213], v[218:221], v[112:115]
	v_mfma_f32_16x16x32_bf16 v[100:103], v[182:185], v[226:229], v[100:103]
	v_mfma_f32_16x16x32_bf16 v[96:99], v[210:213], v[226:229], v[96:99]
	v_mfma_f32_16x16x32_bf16 v[84:87], v[182:185], v[234:237], v[84:87]
	v_mfma_f32_16x16x32_bf16 v[80:83], v[210:213], v[234:237], v[80:83]
	v_mfma_f32_16x16x32_bf16 v[68:71], v[182:185], v[242:245], v[68:71]
	v_mfma_f32_16x16x32_bf16 v[64:67], v[210:213], v[242:245], v[64:67]
	s_barrier
	s_setprio 0
	s_mov_b32 m0, s43
	s_add_u32 s2, s2, 0x40080
	s_addc_u32 s3, s3, 0
	ds_read_b128 v[214:217], v163 offset:49152
	ds_read_b128 v[218:221], v163 offset:50176
	ds_read_b128 v[222:225], v163 offset:51200
	ds_read_b128 v[226:229], v163 offset:52224
	ds_read_b128 v[230:233], v163 offset:53248
	ds_read_b128 v[234:237], v163 offset:54272
	ds_read_b128 v[238:241], v163 offset:55296
	ds_read_b128 v[242:245], v163 offset:56320
	s_add_u32 s98, s2, 0xfffc0000
	s_addc_u32 s99, s3, -1
	global_load_lds_dwordx4 v132, s[98:99]
	s_mov_b32 m0, s44
	s_nop 0
	global_load_lds_dwordx4 v128, s[98:99]
	s_mov_b32 m0, s48
	s_nop 0
	global_load_lds_dwordx4 v132, s[2:3]
	s_mov_b32 m0, s49
	s_nop 0
	global_load_lds_dwordx4 v128, s[2:3]
	s_mov_b32 m0, s45
	s_nop 0
	s_add_u32 s100, s4, 0xfffc0080
	s_addc_u32 s101, s5, -1
	global_load_lds_dwordx4 v134, s[100:101]
	s_mov_b32 m0, s47
	s_nop 0
	global_load_lds_dwordx4 v130, s[100:101]
	s_waitcnt vmcnt(8)
	s_waitcnt lgkmcnt(0)
	s_setprio 1
	s_barrier
	v_mfma_f32_16x16x32_bf16 v[60:63], v[140:143], v[214:217], v[60:63]
	v_mfma_f32_16x16x32_bf16 v[56:59], v[170:173], v[214:217], v[56:59]
	v_mfma_f32_16x16x32_bf16 v[44:47], v[140:143], v[222:225], v[44:47]
	v_mfma_f32_16x16x32_bf16 v[40:43], v[170:173], v[222:225], v[40:43]
	v_mfma_f32_16x16x32_bf16 v[28:31], v[140:143], v[230:233], v[28:31]
	v_mfma_f32_16x16x32_bf16 v[24:27], v[170:173], v[230:233], v[24:27]
	v_mfma_f32_16x16x32_bf16 v[12:15], v[140:143], v[238:241], v[12:15]
	v_mfma_f32_16x16x32_bf16 v[8:11], v[170:173], v[238:241], v[8:11]
	v_mfma_f32_16x16x32_bf16 v[60:63], v[166:169], v[218:221], v[60:63]
	v_mfma_f32_16x16x32_bf16 v[56:59], v[174:177], v[218:221], v[56:59]
	v_mfma_f32_16x16x32_bf16 v[44:47], v[166:169], v[226:229], v[44:47]
	v_mfma_f32_16x16x32_bf16 v[40:43], v[174:177], v[226:229], v[40:43]
	v_mfma_f32_16x16x32_bf16 v[28:31], v[166:169], v[234:237], v[28:31]
	v_mfma_f32_16x16x32_bf16 v[24:27], v[174:177], v[234:237], v[24:27]
	v_mfma_f32_16x16x32_bf16 v[12:15], v[166:169], v[242:245], v[12:15]
	v_mfma_f32_16x16x32_bf16 v[8:11], v[174:177], v[242:245], v[8:11]
	v_mfma_f32_16x16x32_bf16 v[52:55], v[178:181], v[214:217], v[52:55]
	v_mfma_f32_16x16x32_bf16 v[48:51], v[186:189], v[214:217], v[48:51]
	v_mfma_f32_16x16x32_bf16 v[36:39], v[178:181], v[222:225], v[36:39]
	v_mfma_f32_16x16x32_bf16 v[32:35], v[186:189], v[222:225], v[32:35]
	v_mfma_f32_16x16x32_bf16 v[20:23], v[178:181], v[230:233], v[20:23]
	v_mfma_f32_16x16x32_bf16 v[16:19], v[186:189], v[230:233], v[16:19]
	v_mfma_f32_16x16x32_bf16 v[4:7], v[178:181], v[238:241], v[4:7]
	v_mfma_f32_16x16x32_bf16 v[0:3], v[186:189], v[238:241], v[0:3]
	v_mfma_f32_16x16x32_bf16 v[52:55], v[182:185], v[218:221], v[52:55]
	v_mfma_f32_16x16x32_bf16 v[48:51], v[210:213], v[218:221], v[48:51]
	v_mfma_f32_16x16x32_bf16 v[36:39], v[182:185], v[226:229], v[36:39]
	v_mfma_f32_16x16x32_bf16 v[32:35], v[210:213], v[226:229], v[32:35]
	v_mfma_f32_16x16x32_bf16 v[20:23], v[182:185], v[234:237], v[20:23]
	v_mfma_f32_16x16x32_bf16 v[16:19], v[210:213], v[234:237], v[16:19]
	v_mfma_f32_16x16x32_bf16 v[4:7], v[182:185], v[242:245], v[4:7]
	v_mfma_f32_16x16x32_bf16 v[0:3], v[210:213], v[242:245], v[0:3]
	s_barrier
	s_setprio 0
	s_add_i32 s55, s55, 2
	s_add_u32 s0, s0, 0x100
	s_addc_u32 s1, s1, 0
	s_add_u32 s53, s53, 0x100
	s_addc_u32 s54, s54, 0
	s_cmp_gt_u32 s55, 13
; #define PG8_STAGE(bufoff, gbase, voff) do { _Pragma("unroll") for (int _i = 0; _i < 2; ++_i) \
;         __builtin_amdgcn_global_load_lds((const unsigned*)((const char*)(gbase) + (voff)[_i]), (PG8_LAS unsigned*)(lds + (bufoff) + ldsw + _i * 8192), 16, 0, 0); } while (0)
; #define PG8_LDA(dst, b, h) do { _Pragma("unroll") for (int m = 0; m < 4; ++m) _Pragma("unroll") for (int k = 0; k < 2; ++k) dst[m][k] = *(const PG8_LAS bf16x8*)(lds + PG8_SA(b, h) + aoff + m * 2048 + k * 1024); } while (0)
; #define PG8_LDB(dst, b, h) do { _Pragma("unroll") for (int n = 0; n < 2; ++n) _Pragma("unroll") for (int k = 0; k < 2; ++k) dst[n][k] = *(const PG8_LAS bf16x8*)(lds + PG8_SB(b, h) + boff + n * 2048 + k * 1024); } while (0)
; #define PG8_MMA(ai, bj, At, Bt) do { __builtin_amdgcn_s_setprio(1); _Pragma("unroll") for (int m = 0; m < 4; ++m) _Pragma("unroll") for (int n = 0; n < 2; ++n) _Pragma("unroll") for (int k = 0; k < 2; ++k) \
;         acc[ai][bj][m][n] = __builtin_amdgcn_mfma_f32_16x16x32_bf16(Bt[n][k], At[m][k], acc[ai][bj][m][n], 0, 0, 0); __builtin_amdgcn_s_setprio(0); } while (0)
; #define PG8_WAIT_V(n) asm volatile("s_waitcnt vmcnt(" #n ")" ::: "memory")
; #define PG8_WAIT_L(n) asm volatile("s_waitcnt lgkmcnt(" #n ")" ::: "memory")
; template <class Epi, class Sched, bool ALIGN_EPI = false, bool SP2 = false>
; __device__ __forceinline__ void gemm_phase(PG8_LAS unsigned char* lds, const Gemm g, const Sched& S, const Epi& E) {
;     ...
;             const bool last = (t == nt - 2);
;             const char* a1 = cA + (size_t)(t + 1) * kstep;
;             const char* a2 = last ? nA : cA + (size_t)(t + 2) * kstep; const char* b2 = last ? nB : cB + (size_t)(t + 2) * kstep;
;             const char* a3 = a2 + kstep; const char* b3 = b2 + kstep;
;             if (last && has_next) S.a_ready(nxt);
;             if constexpr (SP2) {
;             PG8_LDB(B0, 0, 0); PG8_LDB(B1, 0, 1); PG8_SCHED; PG8_LDA(At, 0, 0); PG8_STAGE(PG8_SA(1, 1), a1 + hstep, voffA);
;             PG8_WAIT_V(8); PG8_WAIT_L(0); PG8_BAR; PG8_MMA(0, 0, At, B0); PG8_MMA(0, 1, At, B1); PG8_BAR; PG8_SCHED;
;             PG8_LDA(At, 0, 1); PG8_STAGE(PG8_SB(0, 0), b2, voffB); PG8_STAGE(PG8_SB(0, 1), b2 + hstep, voffB); PG8_STAGE(PG8_SA(0, 0), a2, voffA);
;             PG8_WAIT_V(8); PG8_WAIT_L(0); PG8_BAR; PG8_MMA(1, 0, At, B0); PG8_MMA(1, 1, At, B1); PG8_BAR; PG8_SCHED;
.LBB0_1042:
	ds_read_b128 v[140:143], v254
	ds_read_b128 v[166:169], v254 offset:1024
	ds_read_b128 v[170:173], v254 offset:2048
	ds_read_b128 v[174:177], v254 offset:3072
	ds_read_b128 v[178:181], v254 offset:16384
	ds_read_b128 v[182:185], v254 offset:17408
	ds_read_b128 v[186:189], v254 offset:18432
	ds_read_b128 v[210:213], v254 offset:19456
	s_add_u32 s2, s0, 0xfffc0080
	s_addc_u32 s3, s1, -1
	s_cmp_eq_u32 s55, 12
	s_cselect_b32 s5, s23, s3
	s_cselect_b32 s4, s51, s2
	s_cselect_b32 s3, s21, s54
	s_cselect_b32 s2, s52, s53
	s_add_i32 m0, s31, 0xc000
	ds_read_b128 v[214:217], v163
	ds_read_b128 v[218:221], v163 offset:1024
	ds_read_b128 v[222:225], v163 offset:2048
	ds_read_b128 v[226:229], v163 offset:3072
	ds_read_b128 v[230:233], v163 offset:4096
	ds_read_b128 v[234:237], v163 offset:5120
	ds_read_b128 v[238:241], v163 offset:6144
	ds_read_b128 v[242:245], v163 offset:7168
	global_load_lds_dwordx4 v136, s[0:1]
	s_add_i32 m0, s31, 0xe000
	s_nop 0
	global_load_lds_dwordx4 v138, s[0:1]
	s_waitcnt vmcnt(8)
	s_waitcnt lgkmcnt(0)
	s_setprio 1
	s_barrier
	v_mfma_f32_16x16x32_bf16 v[124:127], v[140:143], v[214:217], v[124:127]
	v_mfma_f32_16x16x32_bf16 v[120:123], v[170:173], v[214:217], v[120:123]
	v_mfma_f32_16x16x32_bf16 v[108:111], v[140:143], v[222:225], v[108:111]
	v_mfma_f32_16x16x32_bf16 v[104:107], v[170:173], v[222:225], v[104:107]
	v_mfma_f32_16x16x32_bf16 v[92:95], v[140:143], v[230:233], v[92:95]
	v_mfma_f32_16x16x32_bf16 v[88:91], v[170:173], v[230:233], v[88:91]
	v_mfma_f32_16x16x32_bf16 v[76:79], v[140:143], v[238:241], v[76:79]
	v_mfma_f32_16x16x32_bf16 v[72:75], v[170:173], v[238:241], v[72:75]
	v_mfma_f32_16x16x32_bf16 v[124:127], v[166:169], v[218:221], v[124:127]
	v_mfma_f32_16x16x32_bf16 v[120:123], v[174:177], v[218:221], v[120:123]
	v_mfma_f32_16x16x32_bf16 v[108:111], v[166:169], v[226:229], v[108:111]
	v_mfma_f32_16x16x32_bf16 v[104:107], v[174:177], v[226:229], v[104:107]
	v_mfma_f32_16x16x32_bf16 v[92:95], v[166:169], v[234:237], v[92:95]
	v_mfma_f32_16x16x32_bf16 v[88:91], v[174:177], v[234:237], v[88:91]
	v_mfma_f32_16x16x32_bf16 v[76:79], v[166:169], v[242:245], v[76:79]
	v_mfma_f32_16x16x32_bf16 v[72:75], v[174:177], v[242:245], v[72:75]
	v_mfma_f32_16x16x32_bf16 v[116:119], v[178:181], v[214:217], v[116:119]
	v_mfma_f32_16x16x32_bf16 v[112:115], v[186:189], v[214:217], v[112:115]
	v_mfma_f32_16x16x32_bf16 v[100:103], v[178:181], v[222:225], v[100:103]
	v_mfma_f32_16x16x32_bf16 v[96:99], v[186:189], v[222:225], v[96:99]
	v_mfma_f32_16x16x32_bf16 v[84:87], v[178:181], v[230:233], v[84:87]
	v_mfma_f32_16x16x32_bf16 v[80:83], v[186:189], v[230:233], v[80:83]
	v_mfma_f32_16x16x32_bf16 v[68:71], v[178:181], v[238:241], v[68:71]
	v_mfma_f32_16x16x32_bf16 v[64:67], v[186:189], v[238:241], v[64:67]
	v_mfma_f32_16x16x32_bf16 v[116:119], v[182:185], v[218:221], v[116:119]
	v_mfma_f32_16x16x32_bf16 v[112:115], v[210:213], v[218:221], v[112:115]
	v_mfma_f32_16x16x32_bf16 v[100:103], v[182:185], v[226:229], v[100:103]
	v_mfma_f32_16x16x32_bf16 v[96:99], v[210:213], v[226:229], v[96:99]
	v_mfma_f32_16x16x32_bf16 v[84:87], v[182:185], v[234:237], v[84:87]
	v_mfma_f32_16x16x32_bf16 v[80:83], v[210:213], v[234:237], v[80:83]
	v_mfma_f32_16x16x32_bf16 v[68:71], v[182:185], v[242:245], v[68:71]
	v_mfma_f32_16x16x32_bf16 v[64:67], v[210:213], v[242:245], v[64:67]
	s_barrier
	s_setprio 0
	s_mov_b32 m0, s33
	s_add_u32 s56, s2, 0x40000
	s_addc_u32 s57, s3, 0
	ds_read_b128 v[214:217], v163 offset:16384
	ds_read_b128 v[218:221], v163 offset:17408
	ds_read_b128 v[222:225], v163 offset:18432
	ds_read_b128 v[226:229], v163 offset:19456
	ds_read_b128 v[230:233], v163 offset:20480
	ds_read_b128 v[234:237], v163 offset:21504
	ds_read_b128 v[238:241], v163 offset:22528
	ds_read_b128 v[242:245], v163 offset:23552
	global_load_lds_dwordx4 v132, s[2:3]
	s_mov_b32 m0, s34
	s_nop 0
	global_load_lds_dwordx4 v128, s[2:3]
	s_mov_b32 m0, s35
	s_nop 0
	global_load_lds_dwordx4 v132, s[56:57]
	s_mov_b32 m0, s36
	s_nop 0
	global_load_lds_dwordx4 v128, s[56:57]
	s_mov_b32 m0, s31
	s_nop 0
	global_load_lds_dwordx4 v134, s[4:5]
	s_mov_b32 m0, s37
	s_nop 0
	global_load_lds_dwordx4 v130, s[4:5]
	s_waitcnt vmcnt(8)
	s_waitcnt lgkmcnt(0)
	s_setprio 1
	s_barrier
	v_mfma_f32_16x16x32_bf16 v[60:63], v[140:143], v[214:217], v[60:63]
	v_mfma_f32_16x16x32_bf16 v[56:59], v[170:173], v[214:217], v[56:59]
	v_mfma_f32_16x16x32_bf16 v[44:47], v[140:143], v[222:225], v[44:47]
	v_mfma_f32_16x16x32_bf16 v[40:43], v[170:173], v[222:225], v[40:43]
	v_mfma_f32_16x16x32_bf16 v[28:31], v[140:143], v[230:233], v[28:31]
	v_mfma_f32_16x16x32_bf16 v[24:27], v[170:173], v[230:233], v[24:27]
	v_mfma_f32_16x16x32_bf16 v[12:15], v[140:143], v[238:241], v[12:15]
	v_mfma_f32_16x16x32_bf16 v[8:11], v[170:173], v[238:241], v[8:11]
	v_mfma_f32_16x16x32_bf16 v[60:63], v[166:169], v[218:221], v[60:63]
	v_mfma_f32_16x16x32_bf16 v[56:59], v[174:177], v[218:221], v[56:59]
	v_mfma_f32_16x16x32_bf16 v[44:47], v[166:169], v[226:229], v[44:47]
	v_mfma_f32_16x16x32_bf16 v[40:43], v[174:177], v[226:229], v[40:43]
	v_mfma_f32_16x16x32_bf16 v[28:31], v[166:169], v[234:237], v[28:31]
	v_mfma_f32_16x16x32_bf16 v[24:27], v[174:177], v[234:237], v[24:27]
	v_mfma_f32_16x16x32_bf16 v[12:15], v[166:169], v[242:245], v[12:15]
	v_mfma_f32_16x16x32_bf16 v[8:11], v[174:177], v[242:245], v[8:11]
	v_mfma_f32_16x16x32_bf16 v[52:55], v[178:181], v[214:217], v[52:55]
	v_mfma_f32_16x16x32_bf16 v[48:51], v[186:189], v[214:217], v[48:51]
	v_mfma_f32_16x16x32_bf16 v[36:39], v[178:181], v[222:225], v[36:39]
	v_mfma_f32_16x16x32_bf16 v[32:35], v[186:189], v[222:225], v[32:35]
	v_mfma_f32_16x16x32_bf16 v[20:23], v[178:181], v[230:233], v[20:23]
	v_mfma_f32_16x16x32_bf16 v[16:19], v[186:189], v[230:233], v[16:19]
	v_mfma_f32_16x16x32_bf16 v[4:7], v[178:181], v[238:241], v[4:7]
	v_mfma_f32_16x16x32_bf16 v[0:3], v[186:189], v[238:241], v[0:3]
	v_mfma_f32_16x16x32_bf16 v[52:55], v[182:185], v[218:221], v[52:55]
	v_mfma_f32_16x16x32_bf16 v[48:51], v[210:213], v[218:221], v[48:51]
	v_mfma_f32_16x16x32_bf16 v[36:39], v[182:185], v[226:229], v[36:39]
	v_mfma_f32_16x16x32_bf16 v[32:35], v[210:213], v[226:229], v[32:35]
	v_mfma_f32_16x16x32_bf16 v[20:23], v[182:185], v[234:237], v[20:23]
	v_mfma_f32_16x16x32_bf16 v[16:19], v[210:213], v[234:237], v[16:19]
	v_mfma_f32_16x16x32_bf16 v[4:7], v[182:185], v[242:245], v[4:7]
	v_mfma_f32_16x16x32_bf16 v[0:3], v[210:213], v[242:245], v[0:3]
	s_barrier
; #define PG8_STAGE(bufoff, gbase, voff) do { _Pragma("unroll") for (int _i = 0; _i < 2; ++_i) \
;         __builtin_amdgcn_global_load_lds((const unsigned*)((const char*)(gbase) + (voff)[_i]), (PG8_LAS unsigned*)(lds + (bufoff) + ldsw + _i * 8192), 16, 0, 0); } while (0)
; #define PG8_LDA(dst, b, h) do { _Pragma("unroll") for (int m = 0; m < 4; ++m) _Pragma("unroll") for (int k = 0; k < 2; ++k) dst[m][k] = *(const PG8_LAS bf16x8*)(lds + PG8_SA(b, h) + aoff + m * 2048 + k * 1024); } while (0)
; #define PG8_LDB(dst, b, h) do { _Pragma("unroll") for (int n = 0; n < 2; ++n) _Pragma("unroll") for (int k = 0; k < 2; ++k) dst[n][k] = *(const PG8_LAS bf16x8*)(lds + PG8_SB(b, h) + boff + n * 2048 + k * 1024); } while (0)
; #define PG8_MMA(ai, bj, At, Bt) do { __builtin_amdgcn_s_setprio(1); _Pragma("unroll") for (int m = 0; m < 4; ++m) _Pragma("unroll") for (int n = 0; n < 2; ++n) _Pragma("unroll") for (int k = 0; k < 2; ++k) \
;         acc[ai][bj][m][n] = __builtin_amdgcn_mfma_f32_16x16x32_bf16(Bt[n][k], At[m][k], acc[ai][bj][m][n], 0, 0, 0); __builtin_amdgcn_s_setprio(0); } while (0)
; #define PG8_WAIT_V(n) asm volatile("s_waitcnt vmcnt(" #n ")" ::: "memory")
; #define PG8_WAIT_L(n) asm volatile("s_waitcnt lgkmcnt(" #n ")" ::: "memory")
; #define PG8_BAR __builtin_amdgcn_s_barrier()
; #define PG8_SCHED __builtin_amdgcn_sched_barrier(0)
; template <class Epi, class Sched, bool ALIGN_EPI = false, bool SP2 = false>
; __device__ __forceinline__ void gemm_phase(PG8_LAS unsigned char* lds, const Gemm g, const Sched& S, const Epi& E) {
;     ...
;             PG8_WAIT_V(8); PG8_WAIT_L(0); PG8_BAR; PG8_MMA(1, 0, At, B0); PG8_MMA(1, 1, At, B1); PG8_BAR; PG8_SCHED;
;             PG8_LDB(B0, 1, 0); PG8_LDB(B1, 1, 1); PG8_SCHED; PG8_LDA(At, 1, 0); PG8_STAGE(PG8_SA(0, 1), a2 + hstep, voffA);
;             PG8_WAIT_V(8); PG8_WAIT_L(0); PG8_BAR; PG8_MMA(0, 0, At, B0); PG8_MMA(0, 1, At, B1); PG8_BAR; PG8_SCHED;
;             PG8_LDA(At, 1, 1); PG8_STAGE(PG8_SB(1, 0), b3, voffB); PG8_STAGE(PG8_SB(1, 1), b3 + hstep, voffB); PG8_STAGE(PG8_SA(1, 0), a3, voffA);
;             PG8_WAIT_V(8); PG8_WAIT_L(0); PG8_BAR; PG8_MMA(1, 0, At, B0); PG8_MMA(1, 1, At, B1); PG8_BAR; PG8_SCHED;
;     ...
;         if constexpr (ALIGN_EPI) { if (wr == 0) PG8_BAR; }
	s_setprio 0
	ds_read_b128 v[140:143], v254 offset:32768
	ds_read_b128 v[166:169], v254 offset:33792
	ds_read_b128 v[170:173], v254 offset:34816
	ds_read_b128 v[174:177], v254 offset:35840
	ds_read_b128 v[178:181], v254 offset:49152
	ds_read_b128 v[182:185], v254 offset:50176
	ds_read_b128 v[186:189], v254 offset:51200
	ds_read_b128 v[210:213], v254 offset:52224
	s_add_u32 s4, s4, 0x40000
	s_addc_u32 s5, s5, 0
	s_mov_b32 m0, s38
	ds_read_b128 v[214:217], v163 offset:32768
	ds_read_b128 v[218:221], v163 offset:33792
	ds_read_b128 v[222:225], v163 offset:34816
	ds_read_b128 v[226:229], v163 offset:35840
	ds_read_b128 v[230:233], v163 offset:36864
	ds_read_b128 v[234:237], v163 offset:37888
	ds_read_b128 v[238:241], v163 offset:38912
	ds_read_b128 v[242:245], v163 offset:39936
	global_load_lds_dwordx4 v134, s[4:5]
	s_mov_b32 m0, s39
	s_nop 0
	global_load_lds_dwordx4 v130, s[4:5]
	s_waitcnt vmcnt(8)
	s_waitcnt lgkmcnt(0)
	s_setprio 1
	s_barrier
	v_mfma_f32_16x16x32_bf16 v[124:127], v[140:143], v[214:217], v[124:127]
	v_mfma_f32_16x16x32_bf16 v[120:123], v[170:173], v[214:217], v[120:123]
	v_mfma_f32_16x16x32_bf16 v[108:111], v[140:143], v[222:225], v[108:111]
	v_mfma_f32_16x16x32_bf16 v[104:107], v[170:173], v[222:225], v[104:107]
	v_mfma_f32_16x16x32_bf16 v[92:95], v[140:143], v[230:233], v[92:95]
	v_mfma_f32_16x16x32_bf16 v[88:91], v[170:173], v[230:233], v[88:91]
	v_mfma_f32_16x16x32_bf16 v[76:79], v[140:143], v[238:241], v[76:79]
	v_mfma_f32_16x16x32_bf16 v[72:75], v[170:173], v[238:241], v[72:75]
	v_mfma_f32_16x16x32_bf16 v[124:127], v[166:169], v[218:221], v[124:127]
	v_mfma_f32_16x16x32_bf16 v[120:123], v[174:177], v[218:221], v[120:123]
	v_mfma_f32_16x16x32_bf16 v[108:111], v[166:169], v[226:229], v[108:111]
	v_mfma_f32_16x16x32_bf16 v[104:107], v[174:177], v[226:229], v[104:107]
	v_mfma_f32_16x16x32_bf16 v[92:95], v[166:169], v[234:237], v[92:95]
	v_mfma_f32_16x16x32_bf16 v[88:91], v[174:177], v[234:237], v[88:91]
	v_mfma_f32_16x16x32_bf16 v[76:79], v[166:169], v[242:245], v[76:79]
	v_mfma_f32_16x16x32_bf16 v[72:75], v[174:177], v[242:245], v[72:75]
	v_mfma_f32_16x16x32_bf16 v[116:119], v[178:181], v[214:217], v[116:119]
	v_mfma_f32_16x16x32_bf16 v[112:115], v[186:189], v[214:217], v[112:115]
	v_mfma_f32_16x16x32_bf16 v[100:103], v[178:181], v[222:225], v[100:103]
	v_mfma_f32_16x16x32_bf16 v[96:99], v[186:189], v[222:225], v[96:99]
	v_mfma_f32_16x16x32_bf16 v[84:87], v[178:181], v[230:233], v[84:87]
	v_mfma_f32_16x16x32_bf16 v[80:83], v[186:189], v[230:233], v[80:83]
	v_mfma_f32_16x16x32_bf16 v[68:71], v[178:181], v[238:241], v[68:71]
	v_mfma_f32_16x16x32_bf16 v[64:67], v[186:189], v[238:241], v[64:67]
	v_mfma_f32_16x16x32_bf16 v[116:119], v[182:185], v[218:221], v[116:119]
	v_mfma_f32_16x16x32_bf16 v[112:115], v[210:213], v[218:221], v[112:115]
	v_mfma_f32_16x16x32_bf16 v[100:103], v[182:185], v[226:229], v[100:103]
	v_mfma_f32_16x16x32_bf16 v[96:99], v[210:213], v[226:229], v[96:99]
	v_mfma_f32_16x16x32_bf16 v[84:87], v[182:185], v[234:237], v[84:87]
	v_mfma_f32_16x16x32_bf16 v[80:83], v[210:213], v[234:237], v[80:83]
	v_mfma_f32_16x16x32_bf16 v[68:71], v[182:185], v[242:245], v[68:71]
	v_mfma_f32_16x16x32_bf16 v[64:67], v[210:213], v[242:245], v[64:67]
	s_barrier
	s_setprio 0
	s_mov_b32 m0, s43
	s_add_u32 s2, s2, 0x40080
	s_addc_u32 s3, s3, 0
	ds_read_b128 v[214:217], v163 offset:49152
	ds_read_b128 v[218:221], v163 offset:50176
	ds_read_b128 v[222:225], v163 offset:51200
	ds_read_b128 v[226:229], v163 offset:52224
	ds_read_b128 v[230:233], v163 offset:53248
	ds_read_b128 v[234:237], v163 offset:54272
	ds_read_b128 v[238:241], v163 offset:55296
	ds_read_b128 v[242:245], v163 offset:56320
	s_add_u32 s98, s2, 0xfffc0000
	s_addc_u32 s99, s3, -1
	global_load_lds_dwordx4 v132, s[98:99]
	s_mov_b32 m0, s44
	s_nop 0
	global_load_lds_dwordx4 v128, s[98:99]
	s_mov_b32 m0, s48
	s_nop 0
	global_load_lds_dwordx4 v132, s[2:3]
	s_mov_b32 m0, s49
	s_nop 0
	global_load_lds_dwordx4 v128, s[2:3]
	s_mov_b32 m0, s45
	s_nop 0
	s_add_u32 s100, s4, 0xfffc0080
	s_addc_u32 s101, s5, -1
	global_load_lds_dwordx4 v134, s[100:101]
	s_mov_b32 m0, s47
	s_nop 0
	global_load_lds_dwordx4 v130, s[100:101]
	s_waitcnt vmcnt(8)
	s_waitcnt lgkmcnt(0)
	s_setprio 1
	s_barrier
	v_mfma_f32_16x16x32_bf16 v[60:63], v[140:143], v[214:217], v[60:63]
	v_mfma_f32_16x16x32_bf16 v[56:59], v[170:173], v[214:217], v[56:59]
	v_mfma_f32_16x16x32_bf16 v[44:47], v[140:143], v[222:225], v[44:47]
	v_mfma_f32_16x16x32_bf16 v[40:43], v[170:173], v[222:225], v[40:43]
	v_mfma_f32_16x16x32_bf16 v[28:31], v[140:143], v[230:233], v[28:31]
	v_mfma_f32_16x16x32_bf16 v[24:27], v[170:173], v[230:233], v[24:27]
	v_mfma_f32_16x16x32_bf16 v[12:15], v[140:143], v[238:241], v[12:15]
	v_mfma_f32_16x16x32_bf16 v[8:11], v[170:173], v[238:241], v[8:11]
	v_mfma_f32_16x16x32_bf16 v[60:63], v[166:169], v[218:221], v[60:63]
	v_mfma_f32_16x16x32_bf16 v[56:59], v[174:177], v[218:221], v[56:59]
	v_mfma_f32_16x16x32_bf16 v[44:47], v[166:169], v[226:229], v[44:47]
	v_mfma_f32_16x16x32_bf16 v[40:43], v[174:177], v[226:229], v[40:43]
	v_mfma_f32_16x16x32_bf16 v[28:31], v[166:169], v[234:237], v[28:31]
	v_mfma_f32_16x16x32_bf16 v[24:27], v[174:177], v[234:237], v[24:27]
	v_mfma_f32_16x16x32_bf16 v[12:15], v[166:169], v[242:245], v[12:15]
	v_mfma_f32_16x16x32_bf16 v[8:11], v[174:177], v[242:245], v[8:11]
	v_mfma_f32_16x16x32_bf16 v[52:55], v[178:181], v[214:217], v[52:55]
	v_mfma_f32_16x16x32_bf16 v[48:51], v[186:189], v[214:217], v[48:51]
	v_mfma_f32_16x16x32_bf16 v[36:39], v[178:181], v[222:225], v[36:39]
	v_mfma_f32_16x16x32_bf16 v[32:35], v[186:189], v[222:225], v[32:35]
	v_mfma_f32_16x16x32_bf16 v[20:23], v[178:181], v[230:233], v[20:23]
	v_mfma_f32_16x16x32_bf16 v[16:19], v[186:189], v[230:233], v[16:19]
	v_mfma_f32_16x16x32_bf16 v[4:7], v[178:181], v[238:241], v[4:7]
	v_mfma_f32_16x16x32_bf16 v[0:3], v[186:189], v[238:241], v[0:3]
	v_mfma_f32_16x16x32_bf16 v[52:55], v[182:185], v[218:221], v[52:55]
	v_mfma_f32_16x16x32_bf16 v[48:51], v[210:213], v[218:221], v[48:51]
	v_mfma_f32_16x16x32_bf16 v[36:39], v[182:185], v[226:229], v[36:39]
	v_mfma_f32_16x16x32_bf16 v[32:35], v[210:213], v[226:229], v[32:35]
	v_mfma_f32_16x16x32_bf16 v[20:23], v[182:185], v[234:237], v[20:23]
	v_mfma_f32_16x16x32_bf16 v[16:19], v[210:213], v[234:237], v[16:19]
	v_mfma_f32_16x16x32_bf16 v[4:7], v[182:185], v[242:245], v[4:7]
	v_mfma_f32_16x16x32_bf16 v[0:3], v[210:213], v[242:245], v[0:3]
	s_barrier
	s_setprio 0
	s_add_i32 s55, s55, 2
	s_add_u32 s0, s0, 0x100
	s_addc_u32 s1, s1, 0
	s_add_u32 s53, s53, 0x100
	s_addc_u32 s54, s54, 0
	s_cmp_gt_u32 s55, 13
	s_cbranch_scc0 .LBB0_1042
	s_and_b64 vcc, exec, s[18:19]
	s_cbranch_vccz .LBB0_1045
	s_barrier
